# output stores sc1 nt instead of nt
# baseline (speedup 1.0000x reference)
.LBB0_239:
	s_lshl_b64 s[6:7], s[64:65], 1
	s_add_u32 s6, s14, s6
	s_addc_u32 s7, s15, s7
	s_lshl_b32 s4, s4, 8
	s_add_i32 s4, s4, s76
	v_and_or_b32 v114, v138, 7, s4
	v_mad_i64_i32 v[114:115], s[4:5], s60, v114, 0
	v_lshl_add_u64 v[114:115], v[114:115], 1, s[6:7]
	v_cmp_gt_i32_e64 s[4:5], 8, v138
	v_lshl_add_u64 v[114:115], s[8:9], 1, v[114:115]
	v_lshlrev_b32_e32 v116, 4, v163
	v_cndmask_b32_e64 v138, 64, 0, s[4:5]
	v_lshl_add_u64 v[114:115], v[114:115], 0, v[138:139]
	v_ashrrev_i32_e32 v117, 31, v116
	v_lshl_add_u64 v[152:153], v[114:115], 0, v[116:117]
	v_mov_b32_e32 v114, v139
	v_mov_b32_e32 v115, v139
	v_mov_b32_e32 v116, v139
	v_mov_b32_e32 v117, v139
	v_cvt_pk_bf16_f32 v118, v122, v123
	v_cvt_pk_bf16_f32 v119, v126, v127
	v_cvt_pk_bf16_f32 v120, v124, v125
	v_cvt_pk_bf16_f32 v121, v128, v129
	v_mov_b32_e32 v122, v139
	v_mov_b32_e32 v123, v139
	v_mov_b32_dpp v114, v118 row_ror:8 row_mask:0xf bank_mask:0xf
	v_mov_b32_dpp v115, v119 row_ror:8 row_mask:0xf bank_mask:0xf
	v_mov_b32_e32 v124, v139
	v_mov_b32_dpp v116, v120 row_ror:8 row_mask:0xf bank_mask:0xf
	v_mov_b32_e32 v125, v139
	v_mov_b32_dpp v117, v121 row_ror:8 row_mask:0xf bank_mask:0xf
	s_lshl_b32 s8, s60, 4
	v_mov_b32_dpp v122, v148 row_ror:8 row_mask:0xf bank_mask:0xf
	v_mov_b32_dpp v123, v149 row_ror:8 row_mask:0xf bank_mask:0xf
	v_mov_b32_dpp v124, v150 row_ror:8 row_mask:0xf bank_mask:0xf
	v_mov_b32_dpp v125, v151 row_ror:8 row_mask:0xf bank_mask:0xf
	v_cndmask_b32_e64 v114, v114, v148, s[4:5]
	v_cndmask_b32_e64 v115, v115, v149, s[4:5]
	v_cndmask_b32_e64 v116, v116, v150, s[4:5]
	v_cndmask_b32_e64 v117, v117, v151, s[4:5]
	v_cndmask_b32_e64 v118, v118, v122, s[4:5]
	v_cndmask_b32_e64 v119, v119, v123, s[4:5]
	v_cndmask_b32_e64 v120, v120, v124, s[4:5]
	v_cndmask_b32_e64 v121, v121, v125, s[4:5]
	global_store_dwordx4 v[152:153], v[114:117], off sc1 nt
	s_bitset1_b32 s98, 16
	s_cmp_lt_i32 s49, 2
	s_mov_b64 s[62:63], -1
	v_lshl_add_u64 v[114:115], v[152:153], 0, s[8:9]
	global_store_dwordx4 v[114:115], v[118:121], off sc1 nt
	s_bitset1_b32 s98, 17
	s_cbranch_scc1 .LBB0_245
	s_cmp_gt_i32 s49, 2
	s_cbranch_scc0 .LBB0_242
	v_mul_f32_e32 v117, 0xbfb8aa3b, v106
	v_mul_f32_e32 v118, 0xbfb8aa3b, v111
	v_exp_f32_e32 v117, v117
	v_exp_f32_e32 v119, v118
	v_mul_f32_e32 v118, 0xbfb8aa3b, v107
	v_exp_f32_e32 v120, v118
	v_add_f32_e32 v117, 1.0, v117
	v_mul_f32_e32 v121, 0xbfb8aa3b, v108
	v_mul_f32_e32 v122, 0xbfb8aa3b, v113
	v_mul_f32_e32 v116, 0xbfb8aa3b, v110
	v_rcp_f32_e32 v118, v117
	v_add_f32_e32 v117, 1.0, v119
	v_add_f32_e32 v119, 1.0, v120
	v_mul_f32_e32 v120, 0xbfb8aa3b, v112
	v_exp_f32_e32 v121, v121
	v_exp_f32_e32 v123, v122
	v_mul_f32_e32 v122, 0xbfb8aa3b, v109
	v_exp_f32_e32 v116, v116
	v_exp_f32_e32 v120, v120
	v_exp_f32_e32 v124, v122
	v_add_f32_e32 v121, 1.0, v121
	v_add_f32_e32 v116, 1.0, v116
	v_add_f32_e32 v120, 1.0, v120
	v_rcp_f32_e32 v122, v121
	v_add_f32_e32 v121, 1.0, v123
	v_add_f32_e32 v123, 1.0, v124
	v_rcp_f32_e32 v116, v116
	v_rcp_f32_e32 v117, v117
	v_rcp_f32_e32 v119, v119
	v_rcp_f32_e32 v120, v120
	v_rcp_f32_e32 v121, v121
	v_rcp_f32_e32 v123, v123
	s_mov_b64 s[62:63], 0

.LBB0_259:
	v_mov_b32_e32 v100, v139
	v_mov_b32_e32 v101, v139
	v_mov_b32_e32 v102, v139
	v_mov_b32_e32 v103, v139
	v_cvt_pk_bf16_f32 v104, v106, v107
	v_cvt_pk_bf16_f32 v105, v110, v111
	v_cvt_pk_bf16_f32 v106, v108, v109
	v_cvt_pk_bf16_f32 v107, v112, v113
	v_mov_b32_e32 v108, v139
	v_mov_b32_e32 v109, v139
	v_mov_b32_dpp v100, v104 row_ror:8 row_mask:0xf bank_mask:0xf
	v_mov_b32_dpp v101, v105 row_ror:8 row_mask:0xf bank_mask:0xf
	v_mov_b32_e32 v110, v139
	v_mov_b32_dpp v102, v106 row_ror:8 row_mask:0xf bank_mask:0xf
	v_mov_b32_e32 v111, v139
	v_mov_b32_dpp v103, v107 row_ror:8 row_mask:0xf bank_mask:0xf
	v_lshl_add_u64 v[98:99], v[114:115], 0, s[8:9]
	v_mov_b32_dpp v108, v116 row_ror:8 row_mask:0xf bank_mask:0xf
	v_mov_b32_dpp v109, v117 row_ror:8 row_mask:0xf bank_mask:0xf
	v_mov_b32_dpp v110, v118 row_ror:8 row_mask:0xf bank_mask:0xf
	v_mov_b32_dpp v111, v119 row_ror:8 row_mask:0xf bank_mask:0xf
	v_cndmask_b32_e64 v100, v100, v116, s[4:5]
	v_cndmask_b32_e64 v101, v101, v117, s[4:5]
	v_cndmask_b32_e64 v102, v102, v118, s[4:5]
	v_cndmask_b32_e64 v103, v103, v119, s[4:5]
	v_cndmask_b32_e64 v104, v104, v108, s[4:5]
	v_cndmask_b32_e64 v105, v105, v109, s[4:5]
	v_cndmask_b32_e64 v106, v106, v110, s[4:5]
	v_cndmask_b32_e64 v107, v107, v111, s[4:5]
	global_store_dwordx4 v[98:99], v[100:103], off sc1 nt
	s_bitset1_b32 s98, 18
	s_cmp_lt_i32 s49, 2
	s_mov_b64 s[62:63], -1
	v_lshl_add_u64 v[100:101], v[98:99], 0, s[8:9]
	global_store_dwordx4 v[100:101], v[104:107], off sc1 nt
	s_bitset1_b32 s98, 19
	s_cbranch_scc1 .LBB0_265
	s_cmp_gt_i32 s49, 2
	s_cbranch_scc0 .LBB0_262
	v_mul_f32_e32 v101, 0xbfb8aa3b, v90
	v_mul_f32_e32 v102, 0xbfb8aa3b, v95
	v_exp_f32_e32 v101, v101
	v_exp_f32_e32 v103, v102
	v_mul_f32_e32 v102, 0xbfb8aa3b, v91
	v_exp_f32_e32 v104, v102
	v_add_f32_e32 v101, 1.0, v101
	v_mul_f32_e32 v105, 0xbfb8aa3b, v92
	v_mul_f32_e32 v106, 0xbfb8aa3b, v97
	v_mul_f32_e32 v100, 0xbfb8aa3b, v94
	v_rcp_f32_e32 v102, v101
	v_add_f32_e32 v101, 1.0, v103
	v_add_f32_e32 v103, 1.0, v104
	v_mul_f32_e32 v104, 0xbfb8aa3b, v96
	v_exp_f32_e32 v105, v105
	v_exp_f32_e32 v107, v106
	v_mul_f32_e32 v106, 0xbfb8aa3b, v93
	v_exp_f32_e32 v100, v100
	v_exp_f32_e32 v104, v104
	v_exp_f32_e32 v108, v106
	v_add_f32_e32 v105, 1.0, v105
	v_add_f32_e32 v100, 1.0, v100
	v_add_f32_e32 v104, 1.0, v104
	v_rcp_f32_e32 v106, v105
	v_add_f32_e32 v105, 1.0, v107
	v_add_f32_e32 v107, 1.0, v108
	v_rcp_f32_e32 v100, v100
	v_rcp_f32_e32 v101, v101
	v_rcp_f32_e32 v103, v103
	v_rcp_f32_e32 v104, v104
	v_rcp_f32_e32 v105, v105
	v_rcp_f32_e32 v107, v107
	s_mov_b64 s[62:63], 0

.LBB0_279:
	v_mov_b32_e32 v84, v139
	v_mov_b32_e32 v85, v139
	v_mov_b32_e32 v86, v139
	v_mov_b32_e32 v87, v139
	v_cvt_pk_bf16_f32 v88, v90, v91
	v_cvt_pk_bf16_f32 v89, v94, v95
	v_cvt_pk_bf16_f32 v90, v92, v93
	v_cvt_pk_bf16_f32 v91, v96, v97
	s_lshl_b32 s62, s60, 5
	s_mov_b32 s63, s9
	v_mov_b32_e32 v92, v139
	v_mov_b32_dpp v84, v88 row_ror:8 row_mask:0xf bank_mask:0xf
	v_mov_b32_e32 v93, v139
	v_mov_b32_dpp v85, v89 row_ror:8 row_mask:0xf bank_mask:0xf
	v_mov_b32_e32 v94, v139
	v_mov_b32_dpp v86, v90 row_ror:8 row_mask:0xf bank_mask:0xf
	v_mov_b32_e32 v95, v139
	v_mov_b32_dpp v87, v91 row_ror:8 row_mask:0xf bank_mask:0xf
	v_lshl_add_u64 v[82:83], v[98:99], 0, s[62:63]
	v_mov_b32_dpp v92, v100 row_ror:8 row_mask:0xf bank_mask:0xf
	v_mov_b32_dpp v93, v101 row_ror:8 row_mask:0xf bank_mask:0xf
	v_mov_b32_dpp v94, v102 row_ror:8 row_mask:0xf bank_mask:0xf
	v_mov_b32_dpp v95, v103 row_ror:8 row_mask:0xf bank_mask:0xf
	v_cndmask_b32_e64 v84, v84, v100, s[4:5]
	v_cndmask_b32_e64 v85, v85, v101, s[4:5]
	v_cndmask_b32_e64 v86, v86, v102, s[4:5]
	v_cndmask_b32_e64 v87, v87, v103, s[4:5]
	v_cndmask_b32_e64 v88, v88, v92, s[4:5]
	v_cndmask_b32_e64 v89, v89, v93, s[4:5]
	v_cndmask_b32_e64 v90, v90, v94, s[4:5]
	v_cndmask_b32_e64 v91, v91, v95, s[4:5]
	global_store_dwordx4 v[82:83], v[84:87], off sc1 nt
	s_bitset1_b32 s98, 20
	s_cmp_lt_i32 s49, 2
	s_mov_b64 s[64:65], -1
	v_lshl_add_u64 v[84:85], v[82:83], 0, s[8:9]
	global_store_dwordx4 v[84:85], v[88:91], off sc1 nt
	s_bitset1_b32 s98, 21
	s_cbranch_scc1 .LBB0_285
	s_cmp_gt_i32 s49, 2
	s_cbranch_scc0 .LBB0_282
	v_mul_f32_e32 v85, 0xbfb8aa3b, v74
	v_mul_f32_e32 v86, 0xbfb8aa3b, v79
	v_exp_f32_e32 v85, v85
	v_exp_f32_e32 v87, v86
	v_mul_f32_e32 v86, 0xbfb8aa3b, v75
	v_exp_f32_e32 v88, v86
	v_add_f32_e32 v85, 1.0, v85
	v_mul_f32_e32 v89, 0xbfb8aa3b, v76
	v_mul_f32_e32 v90, 0xbfb8aa3b, v81
	v_mul_f32_e32 v84, 0xbfb8aa3b, v78
	v_rcp_f32_e32 v86, v85
	v_add_f32_e32 v85, 1.0, v87
	v_add_f32_e32 v87, 1.0, v88
	v_mul_f32_e32 v88, 0xbfb8aa3b, v80
	v_exp_f32_e32 v89, v89
	v_exp_f32_e32 v91, v90
	v_mul_f32_e32 v90, 0xbfb8aa3b, v77
	v_exp_f32_e32 v84, v84
	v_exp_f32_e32 v88, v88
	v_exp_f32_e32 v92, v90
	v_add_f32_e32 v89, 1.0, v89
	v_add_f32_e32 v84, 1.0, v84
	v_add_f32_e32 v88, 1.0, v88
	v_rcp_f32_e32 v90, v89
	v_add_f32_e32 v89, 1.0, v91
	v_add_f32_e32 v91, 1.0, v92
	v_rcp_f32_e32 v84, v84
	v_rcp_f32_e32 v85, v85
	v_rcp_f32_e32 v87, v87
	v_rcp_f32_e32 v88, v88
	v_rcp_f32_e32 v89, v89
	v_rcp_f32_e32 v91, v91
	s_mov_b64 s[64:65], 0

.LBB0_299:
	v_mov_b32_e32 v68, v139
	v_mov_b32_e32 v69, v139
	v_mov_b32_e32 v70, v139
	v_mov_b32_e32 v71, v139
	v_cvt_pk_bf16_f32 v72, v74, v75
	v_cvt_pk_bf16_f32 v73, v78, v79
	v_cvt_pk_bf16_f32 v74, v76, v77
	v_cvt_pk_bf16_f32 v75, v80, v81
	v_mov_b32_e32 v76, v139
	v_mov_b32_e32 v77, v139
	v_mov_b32_dpp v68, v72 row_ror:8 row_mask:0xf bank_mask:0xf
	v_mov_b32_dpp v69, v73 row_ror:8 row_mask:0xf bank_mask:0xf
	v_mov_b32_e32 v78, v139
	v_mov_b32_dpp v70, v74 row_ror:8 row_mask:0xf bank_mask:0xf
	v_mov_b32_e32 v79, v139
	v_mov_b32_dpp v71, v75 row_ror:8 row_mask:0xf bank_mask:0xf
	v_lshl_add_u64 v[66:67], v[82:83], 0, s[62:63]
	v_mov_b32_dpp v76, v84 row_ror:8 row_mask:0xf bank_mask:0xf
	v_mov_b32_dpp v77, v85 row_ror:8 row_mask:0xf bank_mask:0xf
	v_mov_b32_dpp v78, v86 row_ror:8 row_mask:0xf bank_mask:0xf
	v_mov_b32_dpp v79, v87 row_ror:8 row_mask:0xf bank_mask:0xf
	v_cndmask_b32_e64 v68, v68, v84, s[4:5]
	v_cndmask_b32_e64 v69, v69, v85, s[4:5]
	v_cndmask_b32_e64 v70, v70, v86, s[4:5]
	v_cndmask_b32_e64 v71, v71, v87, s[4:5]
	v_cndmask_b32_e64 v72, v72, v76, s[4:5]
	v_cndmask_b32_e64 v73, v73, v77, s[4:5]
	v_cndmask_b32_e64 v74, v74, v78, s[4:5]
	v_cndmask_b32_e64 v75, v75, v79, s[4:5]
	global_store_dwordx4 v[66:67], v[68:71], off sc1 nt
	s_bitset1_b32 s98, 22
	s_cmp_lt_i32 s49, 2
	s_mov_b64 s[64:65], -1
	v_lshl_add_u64 v[68:69], v[66:67], 0, s[8:9]
	global_store_dwordx4 v[68:69], v[72:75], off sc1 nt
	s_bitset1_b32 s98, 23
	s_cbranch_scc1 .LBB0_305
	s_cmp_gt_i32 s49, 2
	s_cbranch_scc0 .LBB0_302
	v_mul_f32_e32 v69, 0xbfb8aa3b, v58
	v_mul_f32_e32 v70, 0xbfb8aa3b, v63
	v_exp_f32_e32 v69, v69
	v_exp_f32_e32 v71, v70
	v_mul_f32_e32 v70, 0xbfb8aa3b, v59
	v_exp_f32_e32 v72, v70
	v_add_f32_e32 v69, 1.0, v69
	v_mul_f32_e32 v73, 0xbfb8aa3b, v60
	v_mul_f32_e32 v74, 0xbfb8aa3b, v65
	v_mul_f32_e32 v68, 0xbfb8aa3b, v62
	v_rcp_f32_e32 v70, v69
	v_add_f32_e32 v69, 1.0, v71
	v_add_f32_e32 v71, 1.0, v72
	v_mul_f32_e32 v72, 0xbfb8aa3b, v64
	v_exp_f32_e32 v73, v73
	v_exp_f32_e32 v75, v74
	v_mul_f32_e32 v74, 0xbfb8aa3b, v61
	v_exp_f32_e32 v68, v68
	v_exp_f32_e32 v72, v72
	v_exp_f32_e32 v76, v74
	v_add_f32_e32 v73, 1.0, v73
	v_add_f32_e32 v68, 1.0, v68
	v_add_f32_e32 v72, 1.0, v72
	v_rcp_f32_e32 v74, v73
	v_add_f32_e32 v73, 1.0, v75
	v_add_f32_e32 v75, 1.0, v76
	v_rcp_f32_e32 v68, v68
	v_rcp_f32_e32 v69, v69
	v_rcp_f32_e32 v71, v71
	v_rcp_f32_e32 v72, v72
	v_rcp_f32_e32 v73, v73
	v_rcp_f32_e32 v75, v75
	s_mov_b64 s[64:65], 0

.LBB0_319:
	v_mov_b32_e32 v52, v139
	v_mov_b32_e32 v53, v139
	v_mov_b32_e32 v54, v139
	v_mov_b32_e32 v55, v139
	v_cvt_pk_bf16_f32 v56, v58, v59
	v_cvt_pk_bf16_f32 v57, v62, v63
	v_cvt_pk_bf16_f32 v58, v60, v61
	v_cvt_pk_bf16_f32 v59, v64, v65
	s_mul_i32 s6, s60, 0xa0
	s_mov_b32 s7, s9
	v_mov_b32_e32 v60, v139
	v_mov_b32_dpp v52, v56 row_ror:8 row_mask:0xf bank_mask:0xf
	v_mov_b32_e32 v61, v139
	v_mov_b32_dpp v53, v57 row_ror:8 row_mask:0xf bank_mask:0xf
	v_mov_b32_e32 v62, v139
	v_mov_b32_dpp v54, v58 row_ror:8 row_mask:0xf bank_mask:0xf
	v_mov_b32_e32 v63, v139
	v_mov_b32_dpp v55, v59 row_ror:8 row_mask:0xf bank_mask:0xf
	v_lshl_add_u64 v[50:51], v[66:67], 0, s[6:7]
	v_mov_b32_dpp v60, v68 row_ror:8 row_mask:0xf bank_mask:0xf
	v_mov_b32_dpp v61, v69 row_ror:8 row_mask:0xf bank_mask:0xf
	v_mov_b32_dpp v62, v70 row_ror:8 row_mask:0xf bank_mask:0xf
	v_mov_b32_dpp v63, v71 row_ror:8 row_mask:0xf bank_mask:0xf
	v_cndmask_b32_e64 v52, v52, v68, s[4:5]
	v_cndmask_b32_e64 v53, v53, v69, s[4:5]
	v_cndmask_b32_e64 v54, v54, v70, s[4:5]
	v_cndmask_b32_e64 v55, v55, v71, s[4:5]
	v_cndmask_b32_e64 v56, v56, v60, s[4:5]
	v_cndmask_b32_e64 v57, v57, v61, s[4:5]
	v_cndmask_b32_e64 v58, v58, v62, s[4:5]
	v_cndmask_b32_e64 v59, v59, v63, s[4:5]
	global_store_dwordx4 v[50:51], v[52:55], off sc1 nt
	s_bitset1_b32 s98, 24
	s_cmp_lt_i32 s49, 2
	s_mov_b64 s[60:61], -1
	v_lshl_add_u64 v[52:53], v[50:51], 0, s[8:9]
	global_store_dwordx4 v[52:53], v[56:59], off sc1 nt
	s_bitset1_b32 s98, 25
	s_cbranch_scc1 .LBB0_325
	s_cmp_gt_i32 s49, 2
	s_cbranch_scc0 .LBB0_322
	v_mul_f32_e32 v53, 0xbfb8aa3b, v42
	v_mul_f32_e32 v54, 0xbfb8aa3b, v47
	v_exp_f32_e32 v53, v53
	v_exp_f32_e32 v55, v54
	v_mul_f32_e32 v54, 0xbfb8aa3b, v43
	v_exp_f32_e32 v56, v54
	v_add_f32_e32 v53, 1.0, v53
	v_mul_f32_e32 v57, 0xbfb8aa3b, v44
	v_mul_f32_e32 v58, 0xbfb8aa3b, v49
	v_mul_f32_e32 v52, 0xbfb8aa3b, v46
	v_rcp_f32_e32 v54, v53
	v_add_f32_e32 v53, 1.0, v55
	v_add_f32_e32 v55, 1.0, v56
	v_mul_f32_e32 v56, 0xbfb8aa3b, v48
	v_exp_f32_e32 v57, v57
	v_exp_f32_e32 v59, v58
	v_mul_f32_e32 v58, 0xbfb8aa3b, v45
	v_exp_f32_e32 v52, v52
	v_exp_f32_e32 v56, v56
	v_exp_f32_e32 v60, v58
	v_add_f32_e32 v57, 1.0, v57
	v_add_f32_e32 v52, 1.0, v52
	v_add_f32_e32 v56, 1.0, v56
	v_rcp_f32_e32 v58, v57
	v_add_f32_e32 v57, 1.0, v59
	v_add_f32_e32 v59, 1.0, v60
	v_rcp_f32_e32 v52, v52
	v_rcp_f32_e32 v53, v53
	v_rcp_f32_e32 v55, v55
	v_rcp_f32_e32 v56, v56
	v_rcp_f32_e32 v57, v57
	v_rcp_f32_e32 v59, v59
	s_mov_b64 s[60:61], 0

.LBB0_339:
	v_mov_b32_e32 v36, v139
	v_mov_b32_e32 v37, v139
	v_mov_b32_e32 v38, v139
	v_mov_b32_e32 v39, v139
	v_cvt_pk_bf16_f32 v40, v42, v43
	v_cvt_pk_bf16_f32 v41, v46, v47
	v_cvt_pk_bf16_f32 v42, v44, v45
	v_cvt_pk_bf16_f32 v43, v48, v49
	v_mov_b32_e32 v44, v139
	v_mov_b32_e32 v45, v139
	v_mov_b32_dpp v36, v40 row_ror:8 row_mask:0xf bank_mask:0xf
	v_mov_b32_dpp v37, v41 row_ror:8 row_mask:0xf bank_mask:0xf
	v_mov_b32_e32 v46, v139
	v_mov_b32_dpp v38, v42 row_ror:8 row_mask:0xf bank_mask:0xf
	v_mov_b32_e32 v47, v139
	v_mov_b32_dpp v39, v43 row_ror:8 row_mask:0xf bank_mask:0xf
	v_lshl_add_u64 v[34:35], v[50:51], 0, s[62:63]
	v_mov_b32_dpp v44, v52 row_ror:8 row_mask:0xf bank_mask:0xf
	v_mov_b32_dpp v45, v53 row_ror:8 row_mask:0xf bank_mask:0xf
	v_mov_b32_dpp v46, v54 row_ror:8 row_mask:0xf bank_mask:0xf
	v_mov_b32_dpp v47, v55 row_ror:8 row_mask:0xf bank_mask:0xf
	v_cndmask_b32_e64 v36, v36, v52, s[4:5]
	v_cndmask_b32_e64 v37, v37, v53, s[4:5]
	v_cndmask_b32_e64 v38, v38, v54, s[4:5]
	v_cndmask_b32_e64 v39, v39, v55, s[4:5]
	v_cndmask_b32_e64 v40, v40, v44, s[4:5]
	v_cndmask_b32_e64 v41, v41, v45, s[4:5]
	v_cndmask_b32_e64 v42, v42, v46, s[4:5]
	v_cndmask_b32_e64 v43, v43, v47, s[4:5]
	global_store_dwordx4 v[34:35], v[36:39], off sc1 nt
	s_bitset1_b32 s98, 26
	s_cmp_lt_i32 s49, 2
	s_mov_b64 s[60:61], -1
	v_lshl_add_u64 v[36:37], v[34:35], 0, s[8:9]
	global_store_dwordx4 v[36:37], v[40:43], off sc1 nt
	s_bitset1_b32 s98, 27
	s_cbranch_scc1 .LBB0_345
	s_cmp_gt_i32 s49, 2
	s_cbranch_scc0 .LBB0_342
	v_mul_f32_e32 v37, 0xbfb8aa3b, v26
	v_mul_f32_e32 v38, 0xbfb8aa3b, v31
	v_exp_f32_e32 v37, v37
	v_exp_f32_e32 v39, v38
	v_mul_f32_e32 v38, 0xbfb8aa3b, v27
	v_exp_f32_e32 v40, v38
	v_add_f32_e32 v37, 1.0, v37
	v_mul_f32_e32 v41, 0xbfb8aa3b, v28
	v_mul_f32_e32 v42, 0xbfb8aa3b, v33
	v_mul_f32_e32 v36, 0xbfb8aa3b, v30
	v_rcp_f32_e32 v38, v37
	v_add_f32_e32 v37, 1.0, v39
	v_add_f32_e32 v39, 1.0, v40
	v_mul_f32_e32 v40, 0xbfb8aa3b, v32
	v_exp_f32_e32 v41, v41
	v_exp_f32_e32 v43, v42
	v_mul_f32_e32 v42, 0xbfb8aa3b, v29
	v_exp_f32_e32 v36, v36
	v_exp_f32_e32 v40, v40
	v_exp_f32_e32 v44, v42
	v_add_f32_e32 v41, 1.0, v41
	v_add_f32_e32 v36, 1.0, v36
	v_add_f32_e32 v40, 1.0, v40
	v_rcp_f32_e32 v42, v41
	v_add_f32_e32 v41, 1.0, v43
	v_add_f32_e32 v43, 1.0, v44
	v_rcp_f32_e32 v36, v36
	v_rcp_f32_e32 v37, v37
	v_rcp_f32_e32 v39, v39
	v_rcp_f32_e32 v40, v40
	v_rcp_f32_e32 v41, v41
	v_rcp_f32_e32 v43, v43
	s_mov_b64 s[60:61], 0

.LBB0_359:
	v_mov_b32_e32 v20, v139
	v_mov_b32_e32 v21, v139
	v_mov_b32_e32 v22, v139
	v_mov_b32_e32 v23, v139
	v_cvt_pk_bf16_f32 v24, v26, v27
	v_cvt_pk_bf16_f32 v25, v30, v31
	v_cvt_pk_bf16_f32 v26, v28, v29
	v_cvt_pk_bf16_f32 v27, v32, v33
	v_mov_b32_e32 v28, v139
	v_mov_b32_e32 v29, v139
	v_mov_b32_dpp v20, v24 row_ror:8 row_mask:0xf bank_mask:0xf
	v_mov_b32_dpp v21, v25 row_ror:8 row_mask:0xf bank_mask:0xf
	v_mov_b32_e32 v30, v139
	v_mov_b32_dpp v22, v26 row_ror:8 row_mask:0xf bank_mask:0xf
	v_mov_b32_e32 v31, v139
	v_mov_b32_dpp v23, v27 row_ror:8 row_mask:0xf bank_mask:0xf
	v_lshl_add_u64 v[18:19], v[34:35], 0, s[62:63]
	v_mov_b32_dpp v28, v36 row_ror:8 row_mask:0xf bank_mask:0xf
	v_mov_b32_dpp v29, v37 row_ror:8 row_mask:0xf bank_mask:0xf
	v_mov_b32_dpp v30, v38 row_ror:8 row_mask:0xf bank_mask:0xf
	v_mov_b32_dpp v31, v39 row_ror:8 row_mask:0xf bank_mask:0xf
	v_cndmask_b32_e64 v20, v20, v36, s[4:5]
	v_cndmask_b32_e64 v21, v21, v37, s[4:5]
	v_cndmask_b32_e64 v22, v22, v38, s[4:5]
	v_cndmask_b32_e64 v23, v23, v39, s[4:5]
	v_cndmask_b32_e64 v24, v24, v28, s[4:5]
	v_cndmask_b32_e64 v25, v25, v29, s[4:5]
	v_cndmask_b32_e64 v26, v26, v30, s[4:5]
	v_cndmask_b32_e64 v27, v27, v31, s[4:5]
	global_store_dwordx4 v[18:19], v[20:23], off sc1 nt
	s_bitset1_b32 s98, 28
	s_cmp_lt_i32 s49, 2
	s_mov_b64 s[60:61], -1
	v_lshl_add_u64 v[20:21], v[18:19], 0, s[8:9]
	global_store_dwordx4 v[20:21], v[24:27], off sc1 nt
	s_bitset1_b32 s98, 29
	s_cbranch_scc1 .LBB0_365
	s_cmp_gt_i32 s49, 2
	s_cbranch_scc0 .LBB0_362
	v_mul_f32_e32 v21, 0xbfb8aa3b, v10
	v_mul_f32_e32 v22, 0xbfb8aa3b, v15
	v_exp_f32_e32 v21, v21
	v_exp_f32_e32 v23, v22
	v_mul_f32_e32 v22, 0xbfb8aa3b, v11
	v_exp_f32_e32 v24, v22
	v_add_f32_e32 v21, 1.0, v21
	v_mul_f32_e32 v25, 0xbfb8aa3b, v12
	v_mul_f32_e32 v26, 0xbfb8aa3b, v17
	v_mul_f32_e32 v20, 0xbfb8aa3b, v14
	v_rcp_f32_e32 v22, v21
	v_add_f32_e32 v21, 1.0, v23
	v_add_f32_e32 v23, 1.0, v24
	v_mul_f32_e32 v24, 0xbfb8aa3b, v16
	v_exp_f32_e32 v25, v25
	v_exp_f32_e32 v27, v26
	v_mul_f32_e32 v26, 0xbfb8aa3b, v13
	v_exp_f32_e32 v20, v20
	v_exp_f32_e32 v24, v24
	v_exp_f32_e32 v28, v26
	v_add_f32_e32 v25, 1.0, v25
	v_add_f32_e32 v20, 1.0, v20
	v_add_f32_e32 v24, 1.0, v24
	v_rcp_f32_e32 v26, v25
	v_add_f32_e32 v25, 1.0, v27
	v_add_f32_e32 v27, 1.0, v28
	v_rcp_f32_e32 v20, v20
	v_rcp_f32_e32 v21, v21
	v_rcp_f32_e32 v23, v23
	v_rcp_f32_e32 v24, v24
	v_rcp_f32_e32 v25, v25
	v_rcp_f32_e32 v27, v27
	s_mov_b64 s[60:61], 0

.LBB0_379:
	v_mov_b32_e32 v2, 0
	v_mov_b32_e32 v3, 0
	v_mov_b32_e32 v4, 0
	v_mov_b32_e32 v5, 0
	v_cvt_pk_bf16_f32 v6, v10, v11
	v_cvt_pk_bf16_f32 v7, v14, v15
	v_cvt_pk_bf16_f32 v8, v12, v13
	v_cvt_pk_bf16_f32 v9, v16, v17
	v_mov_b32_e32 v12, 0
	v_mov_b32_e32 v13, 0
	v_mov_b32_dpp v2, v6 row_ror:8 row_mask:0xf bank_mask:0xf
	v_mov_b32_dpp v3, v7 row_ror:8 row_mask:0xf bank_mask:0xf
	v_mov_b32_e32 v14, 0
	v_mov_b32_dpp v4, v8 row_ror:8 row_mask:0xf bank_mask:0xf
	v_mov_b32_e32 v15, 0
	v_mov_b32_dpp v5, v9 row_ror:8 row_mask:0xf bank_mask:0xf
	v_lshl_add_u64 v[10:11], v[18:19], 0, s[62:63]
	v_mov_b32_dpp v12, v20 row_ror:8 row_mask:0xf bank_mask:0xf
	v_mov_b32_dpp v13, v21 row_ror:8 row_mask:0xf bank_mask:0xf
	v_mov_b32_dpp v14, v22 row_ror:8 row_mask:0xf bank_mask:0xf
	v_mov_b32_dpp v15, v23 row_ror:8 row_mask:0xf bank_mask:0xf
	v_cndmask_b32_e64 v2, v2, v20, s[4:5]
	v_cndmask_b32_e64 v3, v3, v21, s[4:5]
	v_cndmask_b32_e64 v4, v4, v22, s[4:5]
	v_cndmask_b32_e64 v5, v5, v23, s[4:5]
	v_cndmask_b32_e64 v6, v6, v12, s[4:5]
	v_cndmask_b32_e64 v7, v7, v13, s[4:5]
	v_cndmask_b32_e64 v8, v8, v14, s[4:5]
	v_cndmask_b32_e64 v9, v9, v15, s[4:5]
	global_store_dwordx4 v[10:11], v[2:5], off sc1 nt
	s_bitset1_b32 s98, 30
	s_andn2_b64 vcc, exec, s[0:1]
	s_mov_b64 s[0:1], -1
	v_lshl_add_u64 v[2:3], v[10:11], 0, s[8:9]
	global_store_dwordx4 v[2:3], v[6:9], off sc1 nt
	s_bitset1_b32 s98, 31
	s_cbranch_vccnz .LBB0_171
	s_andn2_b64 vcc, exec, s[12:13]
	s_cbranch_vccnz .LBB0_170
	s_barrier
	s_branch .LBB0_170

.LBB0_563:
	s_lshl_b32 s98, s64, 8
	s_add_i32 s98, s98, s80
	s_lshl_b32 s98, s98, 11
	s_lshl_b32 s99, s91, 8
	s_or_b32 s99, s99, s81
	s_lshl_b32 s99, s99, 1
	s_add_u32 s98, s98, s99
	s_add_u32 s98, s44, s98
	s_addc_u32 s99, s45, 0
	v_lshlrev_b32_e32 v146, 11, v1
	v_lshl_add_u32 v146, v148, 4, v146
	global_load_dwordx4 v[154:157], v146, s[98:99]
	global_load_dwordx4 v[158:161], v146, s[98:99] offset:256
	s_add_u32 s98, s98, 0x8000
	s_addc_u32 s99, s99, 0
	global_load_dwordx4 v[162:165], v146, s[98:99]
	global_load_dwordx4 v[166:169], v146, s[98:99] offset:256
	s_add_u32 s98, s98, 0x8000
	s_addc_u32 s99, s99, 0
	global_load_dwordx4 v[170:173], v146, s[98:99]
	global_load_dwordx4 v[174:177], v146, s[98:99] offset:256
	s_add_u32 s98, s98, 0x8000
	s_addc_u32 s99, s99, 0
	global_load_dwordx4 v[178:181], v146, s[98:99]
	global_load_dwordx4 v[182:185], v146, s[98:99] offset:256
	s_add_u32 s98, s98, 0x28000
	s_addc_u32 s99, s99, 0
	global_load_dwordx4 v[186:189], v146, s[98:99]
	global_load_dwordx4 v[190:193], v146, s[98:99] offset:256
	s_add_u32 s98, s98, 0x8000
	s_addc_u32 s99, s99, 0
	global_load_dwordx4 v[194:197], v146, s[98:99]
	global_load_dwordx4 v[198:201], v146, s[98:99] offset:256
	s_add_u32 s98, s98, 0x8000
	s_addc_u32 s99, s99, 0
	global_load_dwordx4 v[202:205], v146, s[98:99]
	global_load_dwordx4 v[206:209], v146, s[98:99] offset:256
	s_add_u32 s98, s98, 0x8000
	s_addc_u32 s99, s99, 0
	global_load_dwordx4 v[210:213], v146, s[98:99]
	global_load_dwordx4 v[214:217], v146, s[98:99] offset:256
	s_waitcnt vmcnt(15)
	v_lshlrev_b32_e32 v218, 16, v154
	v_and_b32_e32 v154, 0xffff0000, v154
	v_lshlrev_b32_e32 v219, 16, v155
	v_and_b32_e32 v155, 0xffff0000, v155
	v_lshlrev_b32_e32 v220, 16, v156
	v_and_b32_e32 v156, 0xffff0000, v156
	v_lshlrev_b32_e32 v221, 16, v157
	v_and_b32_e32 v157, 0xffff0000, v157
	v_mul_f32_e32 v126, v126, v218
	v_mul_f32_e32 v127, v127, v154
	v_mul_f32_e32 v128, v128, v219
	v_mul_f32_e32 v129, v129, v155
	v_mul_f32_e32 v122, v122, v220
	v_mul_f32_e32 v123, v123, v156
	v_mul_f32_e32 v124, v124, v221
	v_mul_f32_e32 v125, v125, v157
	v_cvt_pk_bf16_f32 v154, v126, v127
	v_cvt_pk_bf16_f32 v155, v128, v129
	v_cvt_pk_bf16_f32 v156, v122, v123
	v_cvt_pk_bf16_f32 v157, v124, v125
	s_sub_u32 s98, s98, 0x58000
	s_subb_u32 s99, s99, 0
	global_store_dwordx4 v146, v[154:157], s[98:99] sc1 nt
	s_waitcnt vmcnt(15)
	v_lshlrev_b32_e32 v218, 16, v158
	v_and_b32_e32 v158, 0xffff0000, v158
	v_lshlrev_b32_e32 v219, 16, v159
	v_and_b32_e32 v159, 0xffff0000, v159
	v_lshlrev_b32_e32 v220, 16, v160
	v_and_b32_e32 v160, 0xffff0000, v160
	v_lshlrev_b32_e32 v221, 16, v161
	v_and_b32_e32 v161, 0xffff0000, v161
	v_mul_f32_e32 v118, v118, v218
	v_mul_f32_e32 v119, v119, v158
	v_mul_f32_e32 v120, v120, v219
	v_mul_f32_e32 v121, v121, v159
	v_mul_f32_e32 v110, v110, v220
	v_mul_f32_e32 v111, v111, v160
	v_mul_f32_e32 v112, v112, v221
	v_mul_f32_e32 v113, v113, v161
	v_cvt_pk_bf16_f32 v158, v118, v119
	v_cvt_pk_bf16_f32 v159, v120, v121
	v_cvt_pk_bf16_f32 v160, v110, v111
	v_cvt_pk_bf16_f32 v161, v112, v113
	global_store_dwordx4 v146, v[158:161], s[98:99] offset:256 sc1 nt
	s_waitcnt vmcnt(15)
	v_lshlrev_b32_e32 v218, 16, v162
	v_and_b32_e32 v162, 0xffff0000, v162
	v_lshlrev_b32_e32 v219, 16, v163
	v_and_b32_e32 v163, 0xffff0000, v163
	v_lshlrev_b32_e32 v220, 16, v164
	v_and_b32_e32 v164, 0xffff0000, v164
	v_lshlrev_b32_e32 v221, 16, v165
	v_and_b32_e32 v165, 0xffff0000, v165
	v_mul_f32_e32 v114, v114, v218
	v_mul_f32_e32 v115, v115, v162
	v_mul_f32_e32 v116, v116, v219
	v_mul_f32_e32 v117, v117, v163
	v_mul_f32_e32 v106, v106, v220
	v_mul_f32_e32 v107, v107, v164
	v_mul_f32_e32 v108, v108, v221
	v_mul_f32_e32 v109, v109, v165
	v_cvt_pk_bf16_f32 v162, v114, v115
	v_cvt_pk_bf16_f32 v163, v116, v117
	v_cvt_pk_bf16_f32 v164, v106, v107
	v_cvt_pk_bf16_f32 v165, v108, v109
	s_add_u32 s98, s98, 0x8000
	s_addc_u32 s99, s99, 0
	global_store_dwordx4 v146, v[162:165], s[98:99] sc1 nt
	s_waitcnt vmcnt(15)
	v_lshlrev_b32_e32 v218, 16, v166
	v_and_b32_e32 v166, 0xffff0000, v166
	v_lshlrev_b32_e32 v219, 16, v167
	v_and_b32_e32 v167, 0xffff0000, v167
	v_lshlrev_b32_e32 v220, 16, v168
	v_and_b32_e32 v168, 0xffff0000, v168
	v_lshlrev_b32_e32 v221, 16, v169
	v_and_b32_e32 v169, 0xffff0000, v169
	v_mul_f32_e32 v102, v102, v218
	v_mul_f32_e32 v103, v103, v166
	v_mul_f32_e32 v104, v104, v219
	v_mul_f32_e32 v105, v105, v167
	v_mul_f32_e32 v94, v94, v220
	v_mul_f32_e32 v95, v95, v168
	v_mul_f32_e32 v96, v96, v221
	v_mul_f32_e32 v97, v97, v169
	v_cvt_pk_bf16_f32 v166, v102, v103
	v_cvt_pk_bf16_f32 v167, v104, v105
	v_cvt_pk_bf16_f32 v168, v94, v95
	v_cvt_pk_bf16_f32 v169, v96, v97
	global_store_dwordx4 v146, v[166:169], s[98:99] offset:256 sc1 nt
	s_waitcnt vmcnt(15)
	v_lshlrev_b32_e32 v218, 16, v170
	v_and_b32_e32 v170, 0xffff0000, v170
	v_lshlrev_b32_e32 v219, 16, v171
	v_and_b32_e32 v171, 0xffff0000, v171
	v_lshlrev_b32_e32 v220, 16, v172
	v_and_b32_e32 v172, 0xffff0000, v172
	v_lshlrev_b32_e32 v221, 16, v173
	v_and_b32_e32 v173, 0xffff0000, v173
	v_mul_f32_e32 v98, v98, v218
	v_mul_f32_e32 v99, v99, v170
	v_mul_f32_e32 v100, v100, v219
	v_mul_f32_e32 v101, v101, v171
	v_mul_f32_e32 v90, v90, v220
	v_mul_f32_e32 v91, v91, v172
	v_mul_f32_e32 v92, v92, v221
	v_mul_f32_e32 v93, v93, v173
	v_cvt_pk_bf16_f32 v170, v98, v99
	v_cvt_pk_bf16_f32 v171, v100, v101
	v_cvt_pk_bf16_f32 v172, v90, v91
	v_cvt_pk_bf16_f32 v173, v92, v93
	s_add_u32 s98, s98, 0x8000
	s_addc_u32 s99, s99, 0
	global_store_dwordx4 v146, v[170:173], s[98:99] sc1 nt
	s_waitcnt vmcnt(15)
	v_lshlrev_b32_e32 v218, 16, v174
	v_and_b32_e32 v174, 0xffff0000, v174
	v_lshlrev_b32_e32 v219, 16, v175
	v_and_b32_e32 v175, 0xffff0000, v175
	v_lshlrev_b32_e32 v220, 16, v176
	v_and_b32_e32 v176, 0xffff0000, v176
	v_lshlrev_b32_e32 v221, 16, v177
	v_and_b32_e32 v177, 0xffff0000, v177
	v_mul_f32_e32 v86, v86, v218
	v_mul_f32_e32 v87, v87, v174
	v_mul_f32_e32 v88, v88, v219
	v_mul_f32_e32 v89, v89, v175
	v_mul_f32_e32 v78, v78, v220
	v_mul_f32_e32 v79, v79, v176
	v_mul_f32_e32 v80, v80, v221
	v_mul_f32_e32 v81, v81, v177
	v_cvt_pk_bf16_f32 v174, v86, v87
	v_cvt_pk_bf16_f32 v175, v88, v89
	v_cvt_pk_bf16_f32 v176, v78, v79
	v_cvt_pk_bf16_f32 v177, v80, v81
	global_store_dwordx4 v146, v[174:177], s[98:99] offset:256 sc1 nt
	s_waitcnt vmcnt(15)
	v_lshlrev_b32_e32 v218, 16, v178
	v_and_b32_e32 v178, 0xffff0000, v178
	v_lshlrev_b32_e32 v219, 16, v179
	v_and_b32_e32 v179, 0xffff0000, v179
	v_lshlrev_b32_e32 v220, 16, v180
	v_and_b32_e32 v180, 0xffff0000, v180
	v_lshlrev_b32_e32 v221, 16, v181
	v_and_b32_e32 v181, 0xffff0000, v181
	v_mul_f32_e32 v82, v82, v218
	v_mul_f32_e32 v83, v83, v178
	v_mul_f32_e32 v84, v84, v219
	v_mul_f32_e32 v85, v85, v179
	v_mul_f32_e32 v74, v74, v220
	v_mul_f32_e32 v75, v75, v180
	v_mul_f32_e32 v76, v76, v221
	v_mul_f32_e32 v77, v77, v181
	v_cvt_pk_bf16_f32 v178, v82, v83
	v_cvt_pk_bf16_f32 v179, v84, v85
	v_cvt_pk_bf16_f32 v180, v74, v75
	v_cvt_pk_bf16_f32 v181, v76, v77
	s_add_u32 s98, s98, 0x8000
	s_addc_u32 s99, s99, 0
	global_store_dwordx4 v146, v[178:181], s[98:99] sc1 nt
	s_waitcnt vmcnt(15)
	v_lshlrev_b32_e32 v218, 16, v182
	v_and_b32_e32 v182, 0xffff0000, v182
	v_lshlrev_b32_e32 v219, 16, v183
	v_and_b32_e32 v183, 0xffff0000, v183
	v_lshlrev_b32_e32 v220, 16, v184
	v_and_b32_e32 v184, 0xffff0000, v184
	v_lshlrev_b32_e32 v221, 16, v185
	v_and_b32_e32 v185, 0xffff0000, v185
	v_mul_f32_e32 v70, v70, v218
	v_mul_f32_e32 v71, v71, v182
	v_mul_f32_e32 v72, v72, v219
	v_mul_f32_e32 v73, v73, v183
	v_mul_f32_e32 v66, v66, v220
	v_mul_f32_e32 v67, v67, v184
	v_mul_f32_e32 v68, v68, v221
	v_mul_f32_e32 v69, v69, v185
	v_cvt_pk_bf16_f32 v182, v70, v71
	v_cvt_pk_bf16_f32 v183, v72, v73
	v_cvt_pk_bf16_f32 v184, v66, v67
	v_cvt_pk_bf16_f32 v185, v68, v69
	global_store_dwordx4 v146, v[182:185], s[98:99] offset:256 sc1 nt
	s_waitcnt vmcnt(15)
	v_lshlrev_b32_e32 v218, 16, v186
	v_and_b32_e32 v186, 0xffff0000, v186
	v_lshlrev_b32_e32 v219, 16, v187
	v_and_b32_e32 v187, 0xffff0000, v187
	v_lshlrev_b32_e32 v220, 16, v188
	v_and_b32_e32 v188, 0xffff0000, v188
	v_lshlrev_b32_e32 v221, 16, v189
	v_and_b32_e32 v189, 0xffff0000, v189
	v_mul_f32_e32 v62, v62, v218
	v_mul_f32_e32 v63, v63, v186
	v_mul_f32_e32 v64, v64, v219
	v_mul_f32_e32 v65, v65, v187
	v_mul_f32_e32 v58, v58, v220
	v_mul_f32_e32 v59, v59, v188
	v_mul_f32_e32 v60, v60, v221
	v_mul_f32_e32 v61, v61, v189
	v_cvt_pk_bf16_f32 v186, v62, v63
	v_cvt_pk_bf16_f32 v187, v64, v65
	v_cvt_pk_bf16_f32 v188, v58, v59
	v_cvt_pk_bf16_f32 v189, v60, v61
	s_add_u32 s98, s98, 0x28000
	s_addc_u32 s99, s99, 0
	global_store_dwordx4 v146, v[186:189], s[98:99] sc1 nt
	s_waitcnt vmcnt(15)
	v_lshlrev_b32_e32 v218, 16, v190
	v_and_b32_e32 v190, 0xffff0000, v190
	v_lshlrev_b32_e32 v219, 16, v191
	v_and_b32_e32 v191, 0xffff0000, v191
	v_lshlrev_b32_e32 v220, 16, v192
	v_and_b32_e32 v192, 0xffff0000, v192
	v_lshlrev_b32_e32 v221, 16, v193
	v_and_b32_e32 v193, 0xffff0000, v193
	v_mul_f32_e32 v54, v54, v218
	v_mul_f32_e32 v55, v55, v190
	v_mul_f32_e32 v56, v56, v219
	v_mul_f32_e32 v57, v57, v191
	v_mul_f32_e32 v46, v46, v220
	v_mul_f32_e32 v47, v47, v192
	v_mul_f32_e32 v48, v48, v221
	v_mul_f32_e32 v49, v49, v193
	v_cvt_pk_bf16_f32 v190, v54, v55
	v_cvt_pk_bf16_f32 v191, v56, v57
	v_cvt_pk_bf16_f32 v192, v46, v47
	v_cvt_pk_bf16_f32 v193, v48, v49
	global_store_dwordx4 v146, v[190:193], s[98:99] offset:256 sc1 nt
	s_waitcnt vmcnt(15)
	v_lshlrev_b32_e32 v218, 16, v194
	v_and_b32_e32 v194, 0xffff0000, v194
	v_lshlrev_b32_e32 v219, 16, v195
	v_and_b32_e32 v195, 0xffff0000, v195
	v_lshlrev_b32_e32 v220, 16, v196
	v_and_b32_e32 v196, 0xffff0000, v196
	v_lshlrev_b32_e32 v221, 16, v197
	v_and_b32_e32 v197, 0xffff0000, v197
	v_mul_f32_e32 v50, v50, v218
	v_mul_f32_e32 v51, v51, v194
	v_mul_f32_e32 v52, v52, v219
	v_mul_f32_e32 v53, v53, v195
	v_mul_f32_e32 v42, v42, v220
	v_mul_f32_e32 v43, v43, v196
	v_mul_f32_e32 v44, v44, v221
	v_mul_f32_e32 v45, v45, v197
	v_cvt_pk_bf16_f32 v194, v50, v51
	v_cvt_pk_bf16_f32 v195, v52, v53
	v_cvt_pk_bf16_f32 v196, v42, v43
	v_cvt_pk_bf16_f32 v197, v44, v45
	s_add_u32 s98, s98, 0x8000
	s_addc_u32 s99, s99, 0
	global_store_dwordx4 v146, v[194:197], s[98:99] sc1 nt
	s_waitcnt vmcnt(15)
	v_lshlrev_b32_e32 v218, 16, v198
	v_and_b32_e32 v198, 0xffff0000, v198
	v_lshlrev_b32_e32 v219, 16, v199
	v_and_b32_e32 v199, 0xffff0000, v199
	v_lshlrev_b32_e32 v220, 16, v200
	v_and_b32_e32 v200, 0xffff0000, v200
	v_lshlrev_b32_e32 v221, 16, v201
	v_and_b32_e32 v201, 0xffff0000, v201
	v_mul_f32_e32 v38, v38, v218
	v_mul_f32_e32 v39, v39, v198
	v_mul_f32_e32 v40, v40, v219
	v_mul_f32_e32 v41, v41, v199
	v_mul_f32_e32 v30, v30, v220
	v_mul_f32_e32 v31, v31, v200
	v_mul_f32_e32 v32, v32, v221
	v_mul_f32_e32 v33, v33, v201
	v_cvt_pk_bf16_f32 v198, v38, v39
	v_cvt_pk_bf16_f32 v199, v40, v41
	v_cvt_pk_bf16_f32 v200, v30, v31
	v_cvt_pk_bf16_f32 v201, v32, v33
	global_store_dwordx4 v146, v[198:201], s[98:99] offset:256 sc1 nt
	s_waitcnt vmcnt(15)
	v_lshlrev_b32_e32 v218, 16, v202
	v_and_b32_e32 v202, 0xffff0000, v202
	v_lshlrev_b32_e32 v219, 16, v203
	v_and_b32_e32 v203, 0xffff0000, v203
	v_lshlrev_b32_e32 v220, 16, v204
	v_and_b32_e32 v204, 0xffff0000, v204
	v_lshlrev_b32_e32 v221, 16, v205
	v_and_b32_e32 v205, 0xffff0000, v205
	v_mul_f32_e32 v34, v34, v218
	v_mul_f32_e32 v35, v35, v202
	v_mul_f32_e32 v36, v36, v219
	v_mul_f32_e32 v37, v37, v203
	v_mul_f32_e32 v26, v26, v220
	v_mul_f32_e32 v27, v27, v204
	v_mul_f32_e32 v28, v28, v221
	v_mul_f32_e32 v29, v29, v205
	v_cvt_pk_bf16_f32 v202, v34, v35
	v_cvt_pk_bf16_f32 v203, v36, v37
	v_cvt_pk_bf16_f32 v204, v26, v27
	v_cvt_pk_bf16_f32 v205, v28, v29
	s_add_u32 s98, s98, 0x8000
	s_addc_u32 s99, s99, 0
	global_store_dwordx4 v146, v[202:205], s[98:99] sc1 nt
	s_waitcnt vmcnt(15)
	v_lshlrev_b32_e32 v218, 16, v206
	v_and_b32_e32 v206, 0xffff0000, v206
	v_lshlrev_b32_e32 v219, 16, v207
	v_and_b32_e32 v207, 0xffff0000, v207
	v_lshlrev_b32_e32 v220, 16, v208
	v_and_b32_e32 v208, 0xffff0000, v208
	v_lshlrev_b32_e32 v221, 16, v209
	v_and_b32_e32 v209, 0xffff0000, v209
	v_mul_f32_e32 v22, v22, v218
	v_mul_f32_e32 v23, v23, v206
	v_mul_f32_e32 v24, v24, v219
	v_mul_f32_e32 v25, v25, v207
	v_mul_f32_e32 v14, v14, v220
	v_mul_f32_e32 v15, v15, v208
	v_mul_f32_e32 v16, v16, v221
	v_mul_f32_e32 v17, v17, v209
	v_cvt_pk_bf16_f32 v206, v22, v23
	v_cvt_pk_bf16_f32 v207, v24, v25
	v_cvt_pk_bf16_f32 v208, v14, v15
	v_cvt_pk_bf16_f32 v209, v16, v17
	global_store_dwordx4 v146, v[206:209], s[98:99] offset:256 sc1 nt
	s_waitcnt vmcnt(15)
	v_lshlrev_b32_e32 v218, 16, v210
	v_and_b32_e32 v210, 0xffff0000, v210
	v_lshlrev_b32_e32 v219, 16, v211
	v_and_b32_e32 v211, 0xffff0000, v211
	v_lshlrev_b32_e32 v220, 16, v212
	v_and_b32_e32 v212, 0xffff0000, v212
	v_lshlrev_b32_e32 v221, 16, v213
	v_and_b32_e32 v213, 0xffff0000, v213
	v_mul_f32_e32 v18, v18, v218
	v_mul_f32_e32 v19, v19, v210
	v_mul_f32_e32 v20, v20, v219
	v_mul_f32_e32 v21, v21, v211
	v_mul_f32_e32 v10, v10, v220
	v_mul_f32_e32 v11, v11, v212
	v_mul_f32_e32 v12, v12, v221
	v_mul_f32_e32 v13, v13, v213
	v_cvt_pk_bf16_f32 v210, v18, v19
	v_cvt_pk_bf16_f32 v211, v20, v21
	v_cvt_pk_bf16_f32 v212, v10, v11
	v_cvt_pk_bf16_f32 v213, v12, v13
	s_add_u32 s98, s98, 0x8000
	s_addc_u32 s99, s99, 0
	global_store_dwordx4 v146, v[210:213], s[98:99] sc1 nt
	s_waitcnt vmcnt(15)
	v_lshlrev_b32_e32 v218, 16, v214
	v_and_b32_e32 v214, 0xffff0000, v214
	v_lshlrev_b32_e32 v219, 16, v215
	v_and_b32_e32 v215, 0xffff0000, v215
	v_lshlrev_b32_e32 v220, 16, v216
	v_and_b32_e32 v216, 0xffff0000, v216
	v_lshlrev_b32_e32 v221, 16, v217
	v_and_b32_e32 v217, 0xffff0000, v217
	v_mul_f32_e32 v6, v6, v218
	v_mul_f32_e32 v7, v7, v214
	v_mul_f32_e32 v8, v8, v219
	v_mul_f32_e32 v9, v9, v215
	v_mul_f32_e32 v2, v2, v220
	v_mul_f32_e32 v3, v3, v216
	v_mul_f32_e32 v4, v4, v221
	v_mul_f32_e32 v5, v5, v217
	v_cvt_pk_bf16_f32 v214, v6, v7
	v_cvt_pk_bf16_f32 v215, v8, v9
	v_cvt_pk_bf16_f32 v216, v2, v3
	v_cvt_pk_bf16_f32 v217, v4, v5
	global_store_dwordx4 v146, v[214:217], s[98:99] offset:256 sc1 nt
	s_andn2_b64 vcc, exec, s[0:1]
	s_mov_b64 s[0:1], -1
	s_mov_b32 s100, 1
	s_cbranch_vccnz .LBB0_552
	s_andn2_b64 vcc, exec, s[10:11]
	s_cbranch_vccnz .LBB0_551
	s_barrier
	s_branch .LBB0_551

.LBB0_587:
	s_lshl_b32 s98, s70, 8
	s_add_i32 s98, s98, s82
	s_lshl_b32 s98, s98, 11
	s_lshl_b32 s99, s89, 8
	s_or_b32 s99, s99, s83
	s_lshl_b32 s99, s99, 1
	s_add_u32 s98, s98, s99
	s_add_u32 s98, s44, s98
	s_addc_u32 s99, s45, 0
	v_lshlrev_b32_e32 v146, 11, v1
	v_lshl_add_u32 v146, v148, 4, v146
	v_add_u32_e32 v147, 0x8000000, v146
	global_load_dwordx4 v[154:157], v146, s[98:99]
	global_load_dwordx4 v[158:161], v147, s[98:99]
	global_load_dwordx4 v[162:165], v146, s[98:99] offset:256
	global_load_dwordx4 v[166:169], v147, s[98:99] offset:256
	s_add_u32 s98, s98, 0x8000
	s_addc_u32 s99, s99, 0
	global_load_dwordx4 v[170:173], v146, s[98:99]
	global_load_dwordx4 v[174:177], v147, s[98:99]
	global_load_dwordx4 v[178:181], v146, s[98:99] offset:256
	global_load_dwordx4 v[182:185], v147, s[98:99] offset:256
	s_add_u32 s98, s98, 0x8000
	s_addc_u32 s99, s99, 0
	global_load_dwordx4 v[186:189], v146, s[98:99]
	global_load_dwordx4 v[190:193], v147, s[98:99]
	global_load_dwordx4 v[194:197], v146, s[98:99] offset:256
	global_load_dwordx4 v[198:201], v147, s[98:99] offset:256
	s_add_u32 s98, s98, 0x8000
	s_addc_u32 s99, s99, 0
	global_load_dwordx4 v[202:205], v146, s[98:99]
	global_load_dwordx4 v[206:209], v147, s[98:99]
	global_load_dwordx4 v[210:213], v146, s[98:99] offset:256
	global_load_dwordx4 v[214:217], v147, s[98:99] offset:256
	s_waitcnt vmcnt(14)
	v_lshlrev_b32_e32 v218, 16, v154
	v_and_b32_e32 v154, 0xffff0000, v154
	v_lshlrev_b32_e32 v219, 16, v155
	v_and_b32_e32 v155, 0xffff0000, v155
	v_lshlrev_b32_e32 v220, 16, v156
	v_and_b32_e32 v156, 0xffff0000, v156
	v_lshlrev_b32_e32 v221, 16, v157
	v_and_b32_e32 v157, 0xffff0000, v157
	v_lshlrev_b32_e32 v222, 16, v158
	v_and_b32_e32 v158, 0xffff0000, v158
	v_lshlrev_b32_e32 v223, 16, v159
	v_and_b32_e32 v159, 0xffff0000, v159
	v_lshlrev_b32_e32 v224, 16, v160
	v_and_b32_e32 v160, 0xffff0000, v160
	v_lshlrev_b32_e32 v225, 16, v161
	v_and_b32_e32 v161, 0xffff0000, v161
	v_fmac_f32_e32 v218, v126, v222
	v_fmac_f32_e32 v154, v127, v158
	v_fmac_f32_e32 v219, v128, v223
	v_fmac_f32_e32 v155, v129, v159
	v_fmac_f32_e32 v220, v122, v224
	v_fmac_f32_e32 v156, v123, v160
	v_fmac_f32_e32 v221, v124, v225
	v_fmac_f32_e32 v157, v125, v161
	v_cvt_pk_bf16_f32 v158, v218, v154
	v_cvt_pk_bf16_f32 v159, v219, v155
	v_cvt_pk_bf16_f32 v160, v220, v156
	v_cvt_pk_bf16_f32 v161, v221, v157
	s_sub_u32 s98, s98, 0x18000
	s_subb_u32 s99, s99, 0
	global_store_dwordx4 v146, v[158:161], s[98:99] sc1 nt
	s_waitcnt vmcnt(13)
	v_lshlrev_b32_e32 v218, 16, v162
	v_and_b32_e32 v162, 0xffff0000, v162
	v_lshlrev_b32_e32 v219, 16, v163
	v_and_b32_e32 v163, 0xffff0000, v163
	v_lshlrev_b32_e32 v220, 16, v164
	v_and_b32_e32 v164, 0xffff0000, v164
	v_lshlrev_b32_e32 v221, 16, v165
	v_and_b32_e32 v165, 0xffff0000, v165
	v_lshlrev_b32_e32 v222, 16, v166
	v_and_b32_e32 v166, 0xffff0000, v166
	v_lshlrev_b32_e32 v223, 16, v167
	v_and_b32_e32 v167, 0xffff0000, v167
	v_lshlrev_b32_e32 v224, 16, v168
	v_and_b32_e32 v168, 0xffff0000, v168
	v_lshlrev_b32_e32 v225, 16, v169
	v_and_b32_e32 v169, 0xffff0000, v169
	v_fmac_f32_e32 v218, v118, v222
	v_fmac_f32_e32 v162, v119, v166
	v_fmac_f32_e32 v219, v120, v223
	v_fmac_f32_e32 v163, v121, v167
	v_fmac_f32_e32 v220, v114, v224
	v_fmac_f32_e32 v164, v115, v168
	v_fmac_f32_e32 v221, v116, v225
	v_fmac_f32_e32 v165, v117, v169
	v_cvt_pk_bf16_f32 v166, v218, v162
	v_cvt_pk_bf16_f32 v167, v219, v163
	v_cvt_pk_bf16_f32 v168, v220, v164
	v_cvt_pk_bf16_f32 v169, v221, v165
	global_store_dwordx4 v146, v[166:169], s[98:99] offset:256 sc1 nt
	s_waitcnt vmcnt(12)
	v_lshlrev_b32_e32 v218, 16, v170
	v_and_b32_e32 v170, 0xffff0000, v170
	v_lshlrev_b32_e32 v219, 16, v171
	v_and_b32_e32 v171, 0xffff0000, v171
	v_lshlrev_b32_e32 v220, 16, v172
	v_and_b32_e32 v172, 0xffff0000, v172
	v_lshlrev_b32_e32 v221, 16, v173
	v_and_b32_e32 v173, 0xffff0000, v173
	v_lshlrev_b32_e32 v222, 16, v174
	v_and_b32_e32 v174, 0xffff0000, v174
	v_lshlrev_b32_e32 v223, 16, v175
	v_and_b32_e32 v175, 0xffff0000, v175
	v_lshlrev_b32_e32 v224, 16, v176
	v_and_b32_e32 v176, 0xffff0000, v176
	v_lshlrev_b32_e32 v225, 16, v177
	v_and_b32_e32 v177, 0xffff0000, v177
	v_fmac_f32_e32 v218, v110, v222
	v_fmac_f32_e32 v170, v111, v174
	v_fmac_f32_e32 v219, v112, v223
	v_fmac_f32_e32 v171, v113, v175
	v_fmac_f32_e32 v220, v106, v224
	v_fmac_f32_e32 v172, v107, v176
	v_fmac_f32_e32 v221, v108, v225
	v_fmac_f32_e32 v173, v109, v177
	v_cvt_pk_bf16_f32 v174, v218, v170
	v_cvt_pk_bf16_f32 v175, v219, v171
	v_cvt_pk_bf16_f32 v176, v220, v172
	v_cvt_pk_bf16_f32 v177, v221, v173
	s_add_u32 s98, s98, 0x8000
	s_addc_u32 s99, s99, 0
	global_store_dwordx4 v146, v[174:177], s[98:99] sc1 nt
	s_waitcnt vmcnt(11)
	v_lshlrev_b32_e32 v218, 16, v178
	v_and_b32_e32 v178, 0xffff0000, v178
	v_lshlrev_b32_e32 v219, 16, v179
	v_and_b32_e32 v179, 0xffff0000, v179
	v_lshlrev_b32_e32 v220, 16, v180
	v_and_b32_e32 v180, 0xffff0000, v180
	v_lshlrev_b32_e32 v221, 16, v181
	v_and_b32_e32 v181, 0xffff0000, v181
	v_lshlrev_b32_e32 v222, 16, v182
	v_and_b32_e32 v182, 0xffff0000, v182
	v_lshlrev_b32_e32 v223, 16, v183
	v_and_b32_e32 v183, 0xffff0000, v183
	v_lshlrev_b32_e32 v224, 16, v184
	v_and_b32_e32 v184, 0xffff0000, v184
	v_lshlrev_b32_e32 v225, 16, v185
	v_and_b32_e32 v185, 0xffff0000, v185
	v_fmac_f32_e32 v218, v102, v222
	v_fmac_f32_e32 v178, v103, v182
	v_fmac_f32_e32 v219, v104, v223
	v_fmac_f32_e32 v179, v105, v183
	v_fmac_f32_e32 v220, v98, v224
	v_fmac_f32_e32 v180, v99, v184
	v_fmac_f32_e32 v221, v100, v225
	v_fmac_f32_e32 v181, v101, v185
	v_cvt_pk_bf16_f32 v182, v218, v178
	v_cvt_pk_bf16_f32 v183, v219, v179
	v_cvt_pk_bf16_f32 v184, v220, v180
	v_cvt_pk_bf16_f32 v185, v221, v181
	global_store_dwordx4 v146, v[182:185], s[98:99] offset:256 sc1 nt
	s_waitcnt vmcnt(10)
	v_lshlrev_b32_e32 v218, 16, v186
	v_and_b32_e32 v186, 0xffff0000, v186
	v_lshlrev_b32_e32 v219, 16, v187
	v_and_b32_e32 v187, 0xffff0000, v187
	v_lshlrev_b32_e32 v220, 16, v188
	v_and_b32_e32 v188, 0xffff0000, v188
	v_lshlrev_b32_e32 v221, 16, v189
	v_and_b32_e32 v189, 0xffff0000, v189
	v_lshlrev_b32_e32 v222, 16, v190
	v_and_b32_e32 v190, 0xffff0000, v190
	v_lshlrev_b32_e32 v223, 16, v191
	v_and_b32_e32 v191, 0xffff0000, v191
	v_lshlrev_b32_e32 v224, 16, v192
	v_and_b32_e32 v192, 0xffff0000, v192
	v_lshlrev_b32_e32 v225, 16, v193
	v_and_b32_e32 v193, 0xffff0000, v193
	v_fmac_f32_e32 v218, v94, v222
	v_fmac_f32_e32 v186, v95, v190
	v_fmac_f32_e32 v219, v96, v223
	v_fmac_f32_e32 v187, v97, v191
	v_fmac_f32_e32 v220, v90, v224
	v_fmac_f32_e32 v188, v91, v192
	v_fmac_f32_e32 v221, v92, v225
	v_fmac_f32_e32 v189, v93, v193
	v_cvt_pk_bf16_f32 v190, v218, v186
	v_cvt_pk_bf16_f32 v191, v219, v187
	v_cvt_pk_bf16_f32 v192, v220, v188
	v_cvt_pk_bf16_f32 v193, v221, v189
	s_add_u32 s98, s98, 0x8000
	s_addc_u32 s99, s99, 0
	global_store_dwordx4 v146, v[190:193], s[98:99] sc1 nt
	s_waitcnt vmcnt(9)
	v_lshlrev_b32_e32 v218, 16, v194
	v_and_b32_e32 v194, 0xffff0000, v194
	v_lshlrev_b32_e32 v219, 16, v195
	v_and_b32_e32 v195, 0xffff0000, v195
	v_lshlrev_b32_e32 v220, 16, v196
	v_and_b32_e32 v196, 0xffff0000, v196
	v_lshlrev_b32_e32 v221, 16, v197
	v_and_b32_e32 v197, 0xffff0000, v197
	v_lshlrev_b32_e32 v222, 16, v198
	v_and_b32_e32 v198, 0xffff0000, v198
	v_lshlrev_b32_e32 v223, 16, v199
	v_and_b32_e32 v199, 0xffff0000, v199
	v_lshlrev_b32_e32 v224, 16, v200
	v_and_b32_e32 v200, 0xffff0000, v200
	v_lshlrev_b32_e32 v225, 16, v201
	v_and_b32_e32 v201, 0xffff0000, v201
	v_fmac_f32_e32 v218, v86, v222
	v_fmac_f32_e32 v194, v87, v198
	v_fmac_f32_e32 v219, v88, v223
	v_fmac_f32_e32 v195, v89, v199
	v_fmac_f32_e32 v220, v82, v224
	v_fmac_f32_e32 v196, v83, v200
	v_fmac_f32_e32 v221, v84, v225
	v_fmac_f32_e32 v197, v85, v201
	v_cvt_pk_bf16_f32 v198, v218, v194
	v_cvt_pk_bf16_f32 v199, v219, v195
	v_cvt_pk_bf16_f32 v200, v220, v196
	v_cvt_pk_bf16_f32 v201, v221, v197
	global_store_dwordx4 v146, v[198:201], s[98:99] offset:256 sc1 nt
	s_waitcnt vmcnt(8)
	v_lshlrev_b32_e32 v218, 16, v202
	v_and_b32_e32 v202, 0xffff0000, v202
	v_lshlrev_b32_e32 v219, 16, v203
	v_and_b32_e32 v203, 0xffff0000, v203
	v_lshlrev_b32_e32 v220, 16, v204
	v_and_b32_e32 v204, 0xffff0000, v204
	v_lshlrev_b32_e32 v221, 16, v205
	v_and_b32_e32 v205, 0xffff0000, v205
	v_lshlrev_b32_e32 v222, 16, v206
	v_and_b32_e32 v206, 0xffff0000, v206
	v_lshlrev_b32_e32 v223, 16, v207
	v_and_b32_e32 v207, 0xffff0000, v207
	v_lshlrev_b32_e32 v224, 16, v208
	v_and_b32_e32 v208, 0xffff0000, v208
	v_lshlrev_b32_e32 v225, 16, v209
	v_and_b32_e32 v209, 0xffff0000, v209
	v_fmac_f32_e32 v218, v78, v222
	v_fmac_f32_e32 v202, v79, v206
	v_fmac_f32_e32 v219, v80, v223
	v_fmac_f32_e32 v203, v81, v207
	v_fmac_f32_e32 v220, v74, v224
	v_fmac_f32_e32 v204, v75, v208
	v_fmac_f32_e32 v221, v76, v225
	v_fmac_f32_e32 v205, v77, v209
	v_cvt_pk_bf16_f32 v206, v218, v202
	v_cvt_pk_bf16_f32 v207, v219, v203
	v_cvt_pk_bf16_f32 v208, v220, v204
	v_cvt_pk_bf16_f32 v209, v221, v205
	s_add_u32 s98, s98, 0x8000
	s_addc_u32 s99, s99, 0
	global_store_dwordx4 v146, v[206:209], s[98:99] sc1 nt
	s_waitcnt vmcnt(7)
	v_lshlrev_b32_e32 v218, 16, v210
	v_and_b32_e32 v210, 0xffff0000, v210
	v_lshlrev_b32_e32 v219, 16, v211
	v_and_b32_e32 v211, 0xffff0000, v211
	v_lshlrev_b32_e32 v220, 16, v212
	v_and_b32_e32 v212, 0xffff0000, v212
	v_lshlrev_b32_e32 v221, 16, v213
	v_and_b32_e32 v213, 0xffff0000, v213
	v_lshlrev_b32_e32 v222, 16, v214
	v_and_b32_e32 v214, 0xffff0000, v214
	v_lshlrev_b32_e32 v223, 16, v215
	v_and_b32_e32 v215, 0xffff0000, v215
	v_lshlrev_b32_e32 v224, 16, v216
	v_and_b32_e32 v216, 0xffff0000, v216
	v_lshlrev_b32_e32 v225, 16, v217
	v_and_b32_e32 v217, 0xffff0000, v217
	v_fmac_f32_e32 v218, v70, v222
	v_fmac_f32_e32 v210, v71, v214
	v_fmac_f32_e32 v219, v72, v223
	v_fmac_f32_e32 v211, v73, v215
	v_fmac_f32_e32 v220, v66, v224
	v_fmac_f32_e32 v212, v67, v216
	v_fmac_f32_e32 v221, v68, v225
	v_fmac_f32_e32 v213, v69, v217
	v_cvt_pk_bf16_f32 v214, v218, v210
	v_cvt_pk_bf16_f32 v215, v219, v211
	v_cvt_pk_bf16_f32 v216, v220, v212
	v_cvt_pk_bf16_f32 v217, v221, v213
	global_store_dwordx4 v146, v[214:217], s[98:99] offset:256 sc1 nt
	s_add_u32 s98, s98, 0x28000
	s_addc_u32 s99, s99, 0
	global_load_dwordx4 v[154:157], v146, s[98:99]
	global_load_dwordx4 v[158:161], v147, s[98:99]
	global_load_dwordx4 v[162:165], v146, s[98:99] offset:256
	global_load_dwordx4 v[166:169], v147, s[98:99] offset:256
	s_add_u32 s98, s98, 0x8000
	s_addc_u32 s99, s99, 0
	global_load_dwordx4 v[170:173], v146, s[98:99]
	global_load_dwordx4 v[174:177], v147, s[98:99]
	global_load_dwordx4 v[178:181], v146, s[98:99] offset:256
	global_load_dwordx4 v[182:185], v147, s[98:99] offset:256
	s_add_u32 s98, s98, 0x8000
	s_addc_u32 s99, s99, 0
	global_load_dwordx4 v[186:189], v146, s[98:99]
	global_load_dwordx4 v[190:193], v147, s[98:99]
	global_load_dwordx4 v[194:197], v146, s[98:99] offset:256
	global_load_dwordx4 v[198:201], v147, s[98:99] offset:256
	s_add_u32 s98, s98, 0x8000
	s_addc_u32 s99, s99, 0
	global_load_dwordx4 v[202:205], v146, s[98:99]
	global_load_dwordx4 v[206:209], v147, s[98:99]
	global_load_dwordx4 v[210:213], v146, s[98:99] offset:256
	global_load_dwordx4 v[214:217], v147, s[98:99] offset:256
	s_waitcnt vmcnt(14)
	v_lshlrev_b32_e32 v218, 16, v154
	v_and_b32_e32 v154, 0xffff0000, v154
	v_lshlrev_b32_e32 v219, 16, v155
	v_and_b32_e32 v155, 0xffff0000, v155
	v_lshlrev_b32_e32 v220, 16, v156
	v_and_b32_e32 v156, 0xffff0000, v156
	v_lshlrev_b32_e32 v221, 16, v157
	v_and_b32_e32 v157, 0xffff0000, v157
	v_lshlrev_b32_e32 v222, 16, v158
	v_and_b32_e32 v158, 0xffff0000, v158
	v_lshlrev_b32_e32 v223, 16, v159
	v_and_b32_e32 v159, 0xffff0000, v159
	v_lshlrev_b32_e32 v224, 16, v160
	v_and_b32_e32 v160, 0xffff0000, v160
	v_lshlrev_b32_e32 v225, 16, v161
	v_and_b32_e32 v161, 0xffff0000, v161
	v_fmac_f32_e32 v218, v62, v222
	v_fmac_f32_e32 v154, v63, v158
	v_fmac_f32_e32 v219, v64, v223
	v_fmac_f32_e32 v155, v65, v159
	v_fmac_f32_e32 v220, v58, v224
	v_fmac_f32_e32 v156, v59, v160
	v_fmac_f32_e32 v221, v60, v225
	v_fmac_f32_e32 v157, v61, v161
	v_cvt_pk_bf16_f32 v158, v218, v154
	v_cvt_pk_bf16_f32 v159, v219, v155
	v_cvt_pk_bf16_f32 v160, v220, v156
	v_cvt_pk_bf16_f32 v161, v221, v157
	s_sub_u32 s98, s98, 0x18000
	s_subb_u32 s99, s99, 0
	global_store_dwordx4 v146, v[158:161], s[98:99] sc1 nt
	s_waitcnt vmcnt(13)
	v_lshlrev_b32_e32 v218, 16, v162
	v_and_b32_e32 v162, 0xffff0000, v162
	v_lshlrev_b32_e32 v219, 16, v163
	v_and_b32_e32 v163, 0xffff0000, v163
	v_lshlrev_b32_e32 v220, 16, v164
	v_and_b32_e32 v164, 0xffff0000, v164
	v_lshlrev_b32_e32 v221, 16, v165
	v_and_b32_e32 v165, 0xffff0000, v165
	v_lshlrev_b32_e32 v222, 16, v166
	v_and_b32_e32 v166, 0xffff0000, v166
	v_lshlrev_b32_e32 v223, 16, v167
	v_and_b32_e32 v167, 0xffff0000, v167
	v_lshlrev_b32_e32 v224, 16, v168
	v_and_b32_e32 v168, 0xffff0000, v168
	v_lshlrev_b32_e32 v225, 16, v169
	v_and_b32_e32 v169, 0xffff0000, v169
	v_fmac_f32_e32 v218, v54, v222
	v_fmac_f32_e32 v162, v55, v166
	v_fmac_f32_e32 v219, v56, v223
	v_fmac_f32_e32 v163, v57, v167
	v_fmac_f32_e32 v220, v50, v224
	v_fmac_f32_e32 v164, v51, v168
	v_fmac_f32_e32 v221, v52, v225
	v_fmac_f32_e32 v165, v53, v169
	v_cvt_pk_bf16_f32 v166, v218, v162
	v_cvt_pk_bf16_f32 v167, v219, v163
	v_cvt_pk_bf16_f32 v168, v220, v164
	v_cvt_pk_bf16_f32 v169, v221, v165
	global_store_dwordx4 v146, v[166:169], s[98:99] offset:256 sc1 nt
	s_waitcnt vmcnt(12)
	v_lshlrev_b32_e32 v218, 16, v170
	v_and_b32_e32 v170, 0xffff0000, v170
	v_lshlrev_b32_e32 v219, 16, v171
	v_and_b32_e32 v171, 0xffff0000, v171
	v_lshlrev_b32_e32 v220, 16, v172
	v_and_b32_e32 v172, 0xffff0000, v172
	v_lshlrev_b32_e32 v221, 16, v173
	v_and_b32_e32 v173, 0xffff0000, v173
	v_lshlrev_b32_e32 v222, 16, v174
	v_and_b32_e32 v174, 0xffff0000, v174
	v_lshlrev_b32_e32 v223, 16, v175
	v_and_b32_e32 v175, 0xffff0000, v175
	v_lshlrev_b32_e32 v224, 16, v176
	v_and_b32_e32 v176, 0xffff0000, v176
	v_lshlrev_b32_e32 v225, 16, v177
	v_and_b32_e32 v177, 0xffff0000, v177
	v_fmac_f32_e32 v218, v46, v222
	v_fmac_f32_e32 v170, v47, v174
	v_fmac_f32_e32 v219, v48, v223
	v_fmac_f32_e32 v171, v49, v175
	v_fmac_f32_e32 v220, v42, v224
	v_fmac_f32_e32 v172, v43, v176
	v_fmac_f32_e32 v221, v44, v225
	v_fmac_f32_e32 v173, v45, v177
	v_cvt_pk_bf16_f32 v174, v218, v170
	v_cvt_pk_bf16_f32 v175, v219, v171
	v_cvt_pk_bf16_f32 v176, v220, v172
	v_cvt_pk_bf16_f32 v177, v221, v173
	s_add_u32 s98, s98, 0x8000
	s_addc_u32 s99, s99, 0
	global_store_dwordx4 v146, v[174:177], s[98:99] sc1 nt
	s_waitcnt vmcnt(11)
	v_lshlrev_b32_e32 v218, 16, v178
	v_and_b32_e32 v178, 0xffff0000, v178
	v_lshlrev_b32_e32 v219, 16, v179
	v_and_b32_e32 v179, 0xffff0000, v179
	v_lshlrev_b32_e32 v220, 16, v180
	v_and_b32_e32 v180, 0xffff0000, v180
	v_lshlrev_b32_e32 v221, 16, v181
	v_and_b32_e32 v181, 0xffff0000, v181
	v_lshlrev_b32_e32 v222, 16, v182
	v_and_b32_e32 v182, 0xffff0000, v182
	v_lshlrev_b32_e32 v223, 16, v183
	v_and_b32_e32 v183, 0xffff0000, v183
	v_lshlrev_b32_e32 v224, 16, v184
	v_and_b32_e32 v184, 0xffff0000, v184
	v_lshlrev_b32_e32 v225, 16, v185
	v_and_b32_e32 v185, 0xffff0000, v185
	v_fmac_f32_e32 v218, v38, v222
	v_fmac_f32_e32 v178, v39, v182
	v_fmac_f32_e32 v219, v40, v223
	v_fmac_f32_e32 v179, v41, v183
	v_fmac_f32_e32 v220, v34, v224
	v_fmac_f32_e32 v180, v35, v184
	v_fmac_f32_e32 v221, v36, v225
	v_fmac_f32_e32 v181, v37, v185
	v_cvt_pk_bf16_f32 v182, v218, v178
	v_cvt_pk_bf16_f32 v183, v219, v179
	v_cvt_pk_bf16_f32 v184, v220, v180
	v_cvt_pk_bf16_f32 v185, v221, v181
	global_store_dwordx4 v146, v[182:185], s[98:99] offset:256 sc1 nt
	s_waitcnt vmcnt(10)
	v_lshlrev_b32_e32 v218, 16, v186
	v_and_b32_e32 v186, 0xffff0000, v186
	v_lshlrev_b32_e32 v219, 16, v187
	v_and_b32_e32 v187, 0xffff0000, v187
	v_lshlrev_b32_e32 v220, 16, v188
	v_and_b32_e32 v188, 0xffff0000, v188
	v_lshlrev_b32_e32 v221, 16, v189
	v_and_b32_e32 v189, 0xffff0000, v189
	v_lshlrev_b32_e32 v222, 16, v190
	v_and_b32_e32 v190, 0xffff0000, v190
	v_lshlrev_b32_e32 v223, 16, v191
	v_and_b32_e32 v191, 0xffff0000, v191
	v_lshlrev_b32_e32 v224, 16, v192
	v_and_b32_e32 v192, 0xffff0000, v192
	v_lshlrev_b32_e32 v225, 16, v193
	v_and_b32_e32 v193, 0xffff0000, v193
	v_fmac_f32_e32 v218, v30, v222
	v_fmac_f32_e32 v186, v31, v190
	v_fmac_f32_e32 v219, v32, v223
	v_fmac_f32_e32 v187, v33, v191
	v_fmac_f32_e32 v220, v26, v224
	v_fmac_f32_e32 v188, v27, v192
	v_fmac_f32_e32 v221, v28, v225
	v_fmac_f32_e32 v189, v29, v193
	v_cvt_pk_bf16_f32 v190, v218, v186
	v_cvt_pk_bf16_f32 v191, v219, v187
	v_cvt_pk_bf16_f32 v192, v220, v188
	v_cvt_pk_bf16_f32 v193, v221, v189
	s_add_u32 s98, s98, 0x8000
	s_addc_u32 s99, s99, 0
	global_store_dwordx4 v146, v[190:193], s[98:99] sc1 nt
	s_waitcnt vmcnt(9)
	v_lshlrev_b32_e32 v218, 16, v194
	v_and_b32_e32 v194, 0xffff0000, v194
	v_lshlrev_b32_e32 v219, 16, v195
	v_and_b32_e32 v195, 0xffff0000, v195
	v_lshlrev_b32_e32 v220, 16, v196
	v_and_b32_e32 v196, 0xffff0000, v196
	v_lshlrev_b32_e32 v221, 16, v197
	v_and_b32_e32 v197, 0xffff0000, v197
	v_lshlrev_b32_e32 v222, 16, v198
	v_and_b32_e32 v198, 0xffff0000, v198
	v_lshlrev_b32_e32 v223, 16, v199
	v_and_b32_e32 v199, 0xffff0000, v199
	v_lshlrev_b32_e32 v224, 16, v200
	v_and_b32_e32 v200, 0xffff0000, v200
	v_lshlrev_b32_e32 v225, 16, v201
	v_and_b32_e32 v201, 0xffff0000, v201
	v_fmac_f32_e32 v218, v22, v222
	v_fmac_f32_e32 v194, v23, v198
	v_fmac_f32_e32 v219, v24, v223
	v_fmac_f32_e32 v195, v25, v199
	v_fmac_f32_e32 v220, v18, v224
	v_fmac_f32_e32 v196, v19, v200
	v_fmac_f32_e32 v221, v20, v225
	v_fmac_f32_e32 v197, v21, v201
	v_cvt_pk_bf16_f32 v198, v218, v194
	v_cvt_pk_bf16_f32 v199, v219, v195
	v_cvt_pk_bf16_f32 v200, v220, v196
	v_cvt_pk_bf16_f32 v201, v221, v197
	global_store_dwordx4 v146, v[198:201], s[98:99] offset:256 sc1 nt
	s_waitcnt vmcnt(8)
	v_lshlrev_b32_e32 v218, 16, v202
	v_and_b32_e32 v202, 0xffff0000, v202
	v_lshlrev_b32_e32 v219, 16, v203
	v_and_b32_e32 v203, 0xffff0000, v203
	v_lshlrev_b32_e32 v220, 16, v204
	v_and_b32_e32 v204, 0xffff0000, v204
	v_lshlrev_b32_e32 v221, 16, v205
	v_and_b32_e32 v205, 0xffff0000, v205
	v_lshlrev_b32_e32 v222, 16, v206
	v_and_b32_e32 v206, 0xffff0000, v206
	v_lshlrev_b32_e32 v223, 16, v207
	v_and_b32_e32 v207, 0xffff0000, v207
	v_lshlrev_b32_e32 v224, 16, v208
	v_and_b32_e32 v208, 0xffff0000, v208
	v_lshlrev_b32_e32 v225, 16, v209
	v_and_b32_e32 v209, 0xffff0000, v209
	v_fmac_f32_e32 v218, v14, v222
	v_fmac_f32_e32 v202, v15, v206
	v_fmac_f32_e32 v219, v16, v223
	v_fmac_f32_e32 v203, v17, v207
	v_fmac_f32_e32 v220, v10, v224
	v_fmac_f32_e32 v204, v11, v208
	v_fmac_f32_e32 v221, v12, v225
	v_fmac_f32_e32 v205, v13, v209
	v_cvt_pk_bf16_f32 v206, v218, v202
	v_cvt_pk_bf16_f32 v207, v219, v203
	v_cvt_pk_bf16_f32 v208, v220, v204
	v_cvt_pk_bf16_f32 v209, v221, v205
	s_add_u32 s98, s98, 0x8000
	s_addc_u32 s99, s99, 0
	global_store_dwordx4 v146, v[206:209], s[98:99] sc1 nt
	s_waitcnt vmcnt(7)
	v_lshlrev_b32_e32 v218, 16, v210
	v_and_b32_e32 v210, 0xffff0000, v210
	v_lshlrev_b32_e32 v219, 16, v211
	v_and_b32_e32 v211, 0xffff0000, v211
	v_lshlrev_b32_e32 v220, 16, v212
	v_and_b32_e32 v212, 0xffff0000, v212
	v_lshlrev_b32_e32 v221, 16, v213
	v_and_b32_e32 v213, 0xffff0000, v213
	v_lshlrev_b32_e32 v222, 16, v214
	v_and_b32_e32 v214, 0xffff0000, v214
	v_lshlrev_b32_e32 v223, 16, v215
	v_and_b32_e32 v215, 0xffff0000, v215
	v_lshlrev_b32_e32 v224, 16, v216
	v_and_b32_e32 v216, 0xffff0000, v216
	v_lshlrev_b32_e32 v225, 16, v217
	v_and_b32_e32 v217, 0xffff0000, v217
	v_fmac_f32_e32 v218, v6, v222
	v_fmac_f32_e32 v210, v7, v214
	v_fmac_f32_e32 v219, v8, v223
	v_fmac_f32_e32 v211, v9, v215
	v_fmac_f32_e32 v220, v2, v224
	v_fmac_f32_e32 v212, v3, v216
	v_fmac_f32_e32 v221, v4, v225
	v_fmac_f32_e32 v213, v5, v217
	v_cvt_pk_bf16_f32 v214, v218, v210
	v_cvt_pk_bf16_f32 v215, v219, v211
	v_cvt_pk_bf16_f32 v216, v220, v212
	v_cvt_pk_bf16_f32 v217, v221, v213
	global_store_dwordx4 v146, v[214:217], s[98:99] offset:256 sc1 nt
	s_andn2_b64 vcc, exec, s[0:1]
	s_mov_b64 s[0:1], -1
	s_mov_b32 s100, 1
	s_cbranch_vccnz .LBB0_576
	s_andn2_b64 vcc, exec, s[8:9]
	s_cbranch_vccnz .LBB0_575
	s_barrier
	s_branch .LBB0_575

.LBB0_707:
	s_or_b64 exec, exec, s[8:9]
	s_add_u32 s7, s68, s66
	s_waitcnt lgkmcnt(0)
	s_barrier
	v_lshl_add_u32 v2, v237, 2, s93
	s_addc_u32 s8, s69, s67
	s_or_b32 s0, s55, s88
	ds_read2_b32 v[88:89], v2 offset1:16
	ds_read2_b32 v[86:87], v2 offset0:32 offset1:48
	ds_read2_b32 v[84:85], v2 offset0:128 offset1:144
	ds_read2_b32 v[66:67], v2 offset0:160 offset1:176
	v_add_u32_e32 v2, s0, v239
	s_add_u32 s0, s7, 0x4000
	s_waitcnt vmcnt(2)
	v_ashrrev_i32_e32 v3, 31, v2
	s_addc_u32 s1, s8, 0
	s_waitcnt vmcnt(1)
	v_lshlrev_b64 v[4:5], 2, v[2:3]
	s_waitcnt lgkmcnt(0)
	v_lshl_add_u64 v[8:9], s[0:1], 0, v[4:5]
	global_load_dwordx4 v[74:77], v[8:9], off
	v_add_u32_e32 v8, 16, v2
	v_ashrrev_i32_e32 v9, 31, v8
	v_lshlrev_b64 v[8:9], 2, v[8:9]
	v_lshl_add_u64 v[10:11], s[0:1], 0, v[8:9]
	global_load_dwordx4 v[92:95], v[10:11], off
	v_add_u32_e32 v10, 32, v2
	v_ashrrev_i32_e32 v11, 31, v10
	v_add_u32_e32 v2, 48, v2
	v_lshlrev_b64 v[78:79], 2, v[10:11]
	v_ashrrev_i32_e32 v3, 31, v2
	s_waitcnt vmcnt(2)
	v_lshl_add_u64 v[6:7], s[16:17], 0, v[4:5]
	v_lshl_add_u64 v[10:11], s[0:1], 0, v[78:79]
	v_lshlrev_b64 v[2:3], 2, v[2:3]
	global_load_dwordx4 v[70:73], v[6:7], off
	global_load_dwordx4 v[130:133], v[10:11], off
	v_lshl_add_u64 v[10:11], s[0:1], 0, v[2:3]
	global_load_dwordx4 v[134:137], v[10:11], off
	global_load_dwordx4 v[138:141], v[6:7], off offset:64
	global_load_dwordx4 v[142:145], v[6:7], off offset:128
	global_load_dwordx4 v[152:155], v[6:7], off offset:192
	s_add_u32 s0, s7, 0x3000
	s_addc_u32 s1, s8, 0
	v_lshl_add_u64 v[4:5], s[0:1], 0, v[4:5]
	global_load_dwordx4 v[14:17], v[4:5], off
	v_lshl_add_u64 v[4:5], s[0:1], 0, v[8:9]
	global_load_dwordx4 v[10:13], v[4:5], off
	v_lshl_add_u64 v[4:5], s[0:1], 0, v[78:79]
	global_load_dwordx4 v[6:9], v[4:5], off
	v_lshl_add_u64 v[2:3], s[0:1], 0, v[2:3]
	global_load_dwordx4 v[2:5], v[2:3], off
	s_mulk_i32 s6, 0x900
	v_lshrrev_b32_e32 v68, 3, v68
	v_lshlrev_b32_e32 v69, 4, v238
	s_add_i32 s0, s6, 0
	v_mul_lo_u32 v78, v237, s97
	v_lshlrev_b32_e32 v79, 3, v236
	v_or_b32_e32 v100, s31, v68
	v_and_b32_e32 v101, 0x70, v69
	v_mul_u32_u24_e32 v68, 0x90, v68
	s_add_i32 s0, s0, 0x22000
	v_add3_u32 v91, s0, v78, v79
	v_add3_u32 v90, s0, v68, v101
	v_cvt_pk_bf16_f32 v68, v222, v223
	v_cvt_pk_bf16_f32 v69, v214, v215
	ds_write_b64 v91, v[68:69]
	v_cvt_pk_bf16_f32 v68, v220, v221
	v_cvt_pk_bf16_f32 v69, v212, v213
	ds_write_b64 v91, v[68:69] offset:32
	v_cvt_pk_bf16_f32 v68, v218, v219
	v_cvt_pk_bf16_f32 v69, v210, v211
	ds_write_b64 v91, v[68:69] offset:64
	v_cvt_pk_bf16_f32 v96, v216, v217
	v_cvt_pk_bf16_f32 v97, v208, v209
	ds_write_b64 v91, v[96:97] offset:96
	s_lshl_b32 s1, s62, 9
	s_or_b32 s0, s1, s89
	s_andn2_b64 vcc, exec, s[4:5]
	s_waitcnt vmcnt(11)
	v_pk_add_f32 v[68:69], v[76:77], 1.0 op_sel_hi:[1,0]
	v_pk_add_f32 v[74:75], v[74:75], 1.0 op_sel_hi:[1,0]
	s_waitcnt vmcnt(9)
	v_pk_mul_f32 v[80:81], v[72:73], v[68:69]
	v_pk_mul_f32 v[82:83], v[70:71], v[74:75]
	v_pk_add_f32 v[68:69], v[94:95], 1.0 op_sel_hi:[1,0]
	v_pk_add_f32 v[70:71], v[92:93], 1.0 op_sel_hi:[1,0]
	s_waitcnt vmcnt(7)
	v_pk_add_f32 v[94:95], v[134:135], 1.0 op_sel_hi:[1,0]
	s_waitcnt vmcnt(6)
	v_pk_mul_f32 v[78:79], v[138:139], v[70:71]
	s_waitcnt vmcnt(4)
	v_pk_mul_f32 v[70:71], v[152:153], v[94:95]
	ds_read_b128 v[94:97], v90
	v_pk_add_f32 v[72:73], v[132:133], 1.0 op_sel_hi:[1,0]
	v_pk_add_f32 v[74:75], v[130:131], 1.0 op_sel_hi:[1,0]
	ds_read_b128 v[130:133], v90 offset:1152
	v_pk_add_f32 v[92:93], v[136:137], 1.0 op_sel_hi:[1,0]
	v_pk_mul_f32 v[76:77], v[140:141], v[68:69]
	v_pk_mul_f32 v[68:69], v[154:155], v[92:93]
	v_or_b32_e32 v92, s0, v101
	v_lshl_add_u32 v92, v100, 11, v92
	s_waitcnt lgkmcnt(1)
	global_store_dwordx4 v92, v[94:97], s[40:41] sc1 nt
	s_bitset1_b32 s98, 0
	v_add_u32_e32 v93, 0x4000, v92
	s_waitcnt lgkmcnt(0)
	global_store_dwordx4 v93, v[130:133], s[40:41] sc1 nt
	s_bitset1_b32 s98, 1
	v_pk_mul_f32 v[94:95], v[222:223], v[88:89] op_sel_hi:[1,0]
	v_pk_mul_f32 v[96:97], v[214:215], v[88:89] op_sel_hi:[1,0]
	s_waitcnt vmcnt(5)
	v_pk_fma_f32 v[94:95], v[94:95], v[82:83], v[14:15]
	v_pk_fma_f32 v[96:97], v[96:97], v[80:81], v[16:17]
	v_cvt_pk_bf16_f32 v94, v94, v95
	v_pk_mul_f32 v[74:75], v[142:143], v[74:75]
	v_cvt_pk_bf16_f32 v95, v96, v97
	ds_write_b64 v91, v[94:95]
	v_pk_mul_f32 v[94:95], v[220:221], v[88:89] op_sel_hi:[1,0]
	v_pk_mul_f32 v[96:97], v[212:213], v[88:89] op_sel_hi:[1,0]
	s_waitcnt vmcnt(4)
	v_pk_fma_f32 v[94:95], v[94:95], v[78:79], v[10:11]
	v_pk_fma_f32 v[96:97], v[96:97], v[76:77], v[12:13]
	v_cvt_pk_bf16_f32 v94, v94, v95
	v_pk_mul_f32 v[72:73], v[144:145], v[72:73]
	v_cvt_pk_bf16_f32 v95, v96, v97
	ds_write_b64 v91, v[94:95] offset:32
	v_pk_mul_f32 v[94:95], v[218:219], v[88:89] op_sel_hi:[1,0]
	v_pk_mul_f32 v[96:97], v[210:211], v[88:89] op_sel_hi:[1,0]
	s_waitcnt vmcnt(3)
	v_pk_fma_f32 v[94:95], v[94:95], v[74:75], v[6:7]
	v_pk_fma_f32 v[96:97], v[96:97], v[72:73], v[8:9]
	v_cvt_pk_bf16_f32 v94, v94, v95
	v_add_u32_e32 v100, 0xc000, v92
	v_cvt_pk_bf16_f32 v95, v96, v97
	ds_write_b64 v91, v[94:95] offset:64
	v_pk_mul_f32 v[94:95], v[216:217], v[88:89] op_sel_hi:[1,0]
	v_pk_mul_f32 v[96:97], v[208:209], v[88:89] op_sel_hi:[1,0]
	s_waitcnt vmcnt(2)
	v_pk_fma_f32 v[94:95], v[94:95], v[70:71], v[2:3]
	v_pk_fma_f32 v[96:97], v[96:97], v[68:69], v[4:5]
	v_cvt_pk_bf16_f32 v94, v94, v95
	v_mov_b32_e32 v88, v89
	v_cvt_pk_bf16_f32 v95, v96, v97
	ds_write_b64 v91, v[94:95] offset:96
	ds_read_b128 v[94:97], v90
	ds_read_b128 v[130:133], v90 offset:1152
	s_waitcnt lgkmcnt(1)
	global_store_dwordx4 v92, v[94:97], s[18:19] sc1 nt
	s_bitset1_b32 s98, 2
	s_waitcnt lgkmcnt(0)
	global_store_dwordx4 v93, v[130:133], s[18:19] sc1 nt
	s_bitset1_b32 s98, 3
	v_cvt_pk_bf16_f32 v94, v190, v191
	v_cvt_pk_bf16_f32 v95, v192, v193
	ds_write_b64 v91, v[94:95]
	v_cvt_pk_bf16_f32 v94, v186, v187
	v_cvt_pk_bf16_f32 v95, v188, v189
	ds_write_b64 v91, v[94:95] offset:32
	v_cvt_pk_bf16_f32 v94, v182, v183
	v_cvt_pk_bf16_f32 v95, v184, v185
	ds_write_b64 v91, v[94:95] offset:64
	v_cvt_pk_bf16_f32 v94, v178, v179
	v_cvt_pk_bf16_f32 v95, v180, v181
	ds_write_b64 v91, v[94:95] offset:96
	ds_read_b128 v[94:97], v90
	ds_read_b128 v[130:133], v90 offset:1152
	v_add_u32_e32 v93, 0x8000, v92
	s_mov_b64 s[0:1], -1
	s_waitcnt lgkmcnt(1)
	global_store_dwordx4 v93, v[94:97], s[40:41] sc1 nt
	s_bitset1_b32 s98, 4
	s_waitcnt lgkmcnt(0)
	global_store_dwordx4 v100, v[130:133], s[40:41] sc1 nt
	s_bitset1_b32 s98, 5
	v_pk_mul_f32 v[94:95], v[190:191], v[88:89] op_sel_hi:[1,0]
	v_pk_mul_f32 v[96:97], v[192:193], v[88:89] op_sel_hi:[1,0]
	v_pk_fma_f32 v[94:95], v[94:95], v[82:83], v[14:15]
	v_pk_fma_f32 v[96:97], v[96:97], v[80:81], v[16:17]
	v_cvt_pk_bf16_f32 v94, v94, v95
	s_nop 0
	v_cvt_pk_bf16_f32 v95, v96, v97
	ds_write_b64 v91, v[94:95]
	v_pk_mul_f32 v[94:95], v[186:187], v[88:89] op_sel_hi:[1,0]
	v_pk_mul_f32 v[96:97], v[188:189], v[88:89] op_sel_hi:[1,0]
	v_pk_fma_f32 v[94:95], v[94:95], v[78:79], v[10:11]
	v_pk_fma_f32 v[96:97], v[96:97], v[76:77], v[12:13]
	v_cvt_pk_bf16_f32 v94, v94, v95
	s_nop 0
	v_cvt_pk_bf16_f32 v95, v96, v97
	ds_write_b64 v91, v[94:95] offset:32
	v_pk_mul_f32 v[94:95], v[182:183], v[88:89] op_sel_hi:[1,0]
	v_pk_mul_f32 v[96:97], v[184:185], v[88:89] op_sel_hi:[1,0]
	v_pk_fma_f32 v[94:95], v[94:95], v[74:75], v[6:7]
	v_pk_fma_f32 v[96:97], v[96:97], v[72:73], v[8:9]
	v_cvt_pk_bf16_f32 v94, v94, v95
	s_nop 0
	v_cvt_pk_bf16_f32 v95, v96, v97
	ds_write_b64 v91, v[94:95] offset:64
	v_pk_mul_f32 v[94:95], v[178:179], v[88:89] op_sel_hi:[1,0]
	v_pk_mul_f32 v[88:89], v[180:181], v[88:89] op_sel_hi:[1,0]
	v_pk_fma_f32 v[94:95], v[94:95], v[70:71], v[2:3]
	v_pk_fma_f32 v[88:89], v[88:89], v[68:69], v[4:5]
	v_cvt_pk_bf16_f32 v94, v94, v95
	s_nop 0
	v_cvt_pk_bf16_f32 v95, v88, v89
	ds_write_b64 v91, v[94:95] offset:96
	ds_read_b128 v[94:97], v90
	ds_read_b128 v[130:133], v90 offset:1152
	s_waitcnt lgkmcnt(1)
	global_store_dwordx4 v93, v[94:97], s[18:19] sc1 nt
	s_bitset1_b32 s98, 6
	s_waitcnt lgkmcnt(0)
	global_store_dwordx4 v100, v[130:133], s[18:19] sc1 nt
	s_bitset1_b32 s98, 7
	v_cvt_pk_bf16_f32 v88, v174, v175
	v_cvt_pk_bf16_f32 v89, v176, v177
	ds_write_b64 v91, v[88:89]
	v_cvt_pk_bf16_f32 v88, v170, v171
	v_cvt_pk_bf16_f32 v89, v172, v173
	ds_write_b64 v91, v[88:89] offset:32
	v_cvt_pk_bf16_f32 v88, v166, v167
	v_cvt_pk_bf16_f32 v89, v168, v169
	ds_write_b64 v91, v[88:89] offset:64
	v_cvt_pk_bf16_f32 v88, v162, v163
	v_cvt_pk_bf16_f32 v89, v164, v165
	ds_write_b64 v91, v[88:89] offset:96
	ds_read_b128 v[94:97], v90
	ds_read_b128 v[130:133], v90 offset:1152
	v_add_u32_e32 v93, 0x10000, v92
	v_add_u32_e32 v100, 0x14000, v92
	v_pk_mul_f32 v[88:89], v[174:175], v[86:87] op_sel_hi:[1,0]
	s_waitcnt lgkmcnt(1)
	global_store_dwordx4 v93, v[94:97], s[40:41] sc1 nt
	s_bitset1_b32 s98, 8
	s_waitcnt lgkmcnt(0)
	global_store_dwordx4 v100, v[130:133], s[40:41] sc1 nt
	s_bitset1_b32 s98, 9
	v_pk_fma_f32 v[88:89], v[88:89], v[82:83], v[14:15]
	v_pk_mul_f32 v[94:95], v[176:177], v[86:87] op_sel_hi:[1,0]
	v_cvt_pk_bf16_f32 v88, v88, v89
	s_nop 0
	v_pk_fma_f32 v[94:95], v[94:95], v[80:81], v[16:17]
	s_nop 0
	v_cvt_pk_bf16_f32 v89, v94, v95
	ds_write_b64 v91, v[88:89]
	v_pk_mul_f32 v[88:89], v[170:171], v[86:87] op_sel_hi:[1,0]
	v_pk_mul_f32 v[94:95], v[172:173], v[86:87] op_sel_hi:[1,0]
	v_pk_fma_f32 v[88:89], v[88:89], v[78:79], v[10:11]
	v_pk_fma_f32 v[94:95], v[94:95], v[76:77], v[12:13]
	v_cvt_pk_bf16_f32 v88, v88, v89
	s_nop 0
	v_cvt_pk_bf16_f32 v89, v94, v95
	ds_write_b64 v91, v[88:89] offset:32
	v_pk_mul_f32 v[88:89], v[166:167], v[86:87] op_sel_hi:[1,0]
	v_pk_mul_f32 v[94:95], v[168:169], v[86:87] op_sel_hi:[1,0]
	v_pk_fma_f32 v[88:89], v[88:89], v[74:75], v[6:7]
	v_pk_fma_f32 v[94:95], v[94:95], v[72:73], v[8:9]
	v_cvt_pk_bf16_f32 v88, v88, v89
	s_nop 0
	v_cvt_pk_bf16_f32 v89, v94, v95
	ds_write_b64 v91, v[88:89] offset:64
	v_pk_mul_f32 v[88:89], v[162:163], v[86:87] op_sel_hi:[1,0]
	v_pk_mul_f32 v[94:95], v[164:165], v[86:87] op_sel_hi:[1,0]
	v_pk_fma_f32 v[88:89], v[88:89], v[70:71], v[2:3]
	v_pk_fma_f32 v[94:95], v[94:95], v[68:69], v[4:5]
	v_cvt_pk_bf16_f32 v88, v88, v89
	v_mov_b32_e32 v86, v87
	v_cvt_pk_bf16_f32 v89, v94, v95
	ds_write_b64 v91, v[88:89] offset:96
	ds_read_b128 v[94:97], v90
	ds_read_b128 v[130:133], v90 offset:1152
	s_waitcnt lgkmcnt(1)
	global_store_dwordx4 v93, v[94:97], s[18:19] sc1 nt
	s_bitset1_b32 s98, 10
	s_waitcnt lgkmcnt(0)
	global_store_dwordx4 v100, v[130:133], s[18:19] sc1 nt
	s_bitset1_b32 s98, 11
	v_cvt_pk_bf16_f32 v88, v128, v129
	v_cvt_pk_bf16_f32 v89, v120, v121
	ds_write_b64 v91, v[88:89]
	v_cvt_pk_bf16_f32 v88, v126, v127
	v_cvt_pk_bf16_f32 v89, v118, v119
	ds_write_b64 v91, v[88:89] offset:32
	v_cvt_pk_bf16_f32 v88, v124, v125
	v_cvt_pk_bf16_f32 v89, v116, v117
	ds_write_b64 v91, v[88:89] offset:64
	v_cvt_pk_bf16_f32 v88, v122, v123
	v_cvt_pk_bf16_f32 v89, v114, v115
	ds_write_b64 v91, v[88:89] offset:96
	ds_read_b128 v[94:97], v90
	ds_read_b128 v[130:133], v90 offset:1152
	v_add_u32_e32 v93, 0x18000, v92
	v_add_u32_e32 v100, 0x1c000, v92
	v_pk_mul_f32 v[88:89], v[128:129], v[86:87] op_sel_hi:[1,0]
	s_waitcnt lgkmcnt(1)
	global_store_dwordx4 v93, v[94:97], s[40:41] sc1 nt
	s_bitset1_b32 s98, 12
	s_waitcnt lgkmcnt(0)
	global_store_dwordx4 v100, v[130:133], s[40:41] sc1 nt
	s_bitset1_b32 s98, 13
	v_pk_fma_f32 v[88:89], v[88:89], v[82:83], v[14:15]
	v_pk_mul_f32 v[94:95], v[120:121], v[86:87] op_sel_hi:[1,0]
	v_cvt_pk_bf16_f32 v88, v88, v89
	s_nop 0
	v_pk_fma_f32 v[94:95], v[94:95], v[80:81], v[16:17]
	s_nop 0
	v_cvt_pk_bf16_f32 v89, v94, v95
	ds_write_b64 v91, v[88:89]
	v_pk_mul_f32 v[88:89], v[126:127], v[86:87] op_sel_hi:[1,0]
	v_pk_mul_f32 v[94:95], v[118:119], v[86:87] op_sel_hi:[1,0]
	v_pk_fma_f32 v[88:89], v[88:89], v[78:79], v[10:11]
	v_pk_fma_f32 v[94:95], v[94:95], v[76:77], v[12:13]
	v_cvt_pk_bf16_f32 v88, v88, v89
	s_nop 0
	v_cvt_pk_bf16_f32 v89, v94, v95
	ds_write_b64 v91, v[88:89] offset:32
	v_pk_mul_f32 v[88:89], v[124:125], v[86:87] op_sel_hi:[1,0]
	v_pk_mul_f32 v[94:95], v[116:117], v[86:87] op_sel_hi:[1,0]
	v_pk_fma_f32 v[88:89], v[88:89], v[74:75], v[6:7]
	v_pk_fma_f32 v[94:95], v[94:95], v[72:73], v[8:9]
	v_cvt_pk_bf16_f32 v88, v88, v89
	s_nop 0
	v_cvt_pk_bf16_f32 v89, v94, v95
	ds_write_b64 v91, v[88:89] offset:64
	v_pk_mul_f32 v[88:89], v[122:123], v[86:87] op_sel_hi:[1,0]
	v_pk_mul_f32 v[86:87], v[114:115], v[86:87] op_sel_hi:[1,0]
	v_pk_fma_f32 v[88:89], v[88:89], v[70:71], v[2:3]
	v_pk_fma_f32 v[86:87], v[86:87], v[68:69], v[4:5]
	v_cvt_pk_bf16_f32 v88, v88, v89
	s_nop 0
	v_cvt_pk_bf16_f32 v89, v86, v87
	ds_write_b64 v91, v[88:89] offset:96
	ds_read_b128 v[86:89], v90
	ds_read_b128 v[94:97], v90 offset:1152
	s_waitcnt lgkmcnt(1)
	global_store_dwordx4 v93, v[86:89], s[18:19] sc1 nt
	s_bitset1_b32 s98, 14
	s_waitcnt lgkmcnt(0)
	global_store_dwordx4 v100, v[94:97], s[18:19] sc1 nt
	s_bitset1_b32 s98, 15
	v_cvt_pk_bf16_f32 v86, v150, v151
	v_cvt_pk_bf16_f32 v87, v148, v149
	ds_write_b64 v91, v[86:87]
	v_cvt_pk_bf16_f32 v86, v62, v63
	v_cvt_pk_bf16_f32 v87, v64, v65
	ds_write_b64 v91, v[86:87] offset:32
	v_cvt_pk_bf16_f32 v86, v54, v55
	v_cvt_pk_bf16_f32 v87, v56, v57
	ds_write_b64 v91, v[86:87] offset:64
	v_cvt_pk_bf16_f32 v86, v146, v147
	v_cvt_pk_bf16_f32 v87, v52, v53
	ds_write_b64 v91, v[86:87] offset:96
	ds_read_b128 v[86:89], v90
	ds_read_b128 v[94:97], v90 offset:1152
	v_add_u32_e32 v93, 0x40000, v92
	v_add_u32_e32 v100, 0x44000, v92
	v_pk_mul_f32 v[62:63], v[62:63], v[84:85] op_sel_hi:[1,0]
	s_waitcnt lgkmcnt(1)
	global_store_dwordx4 v93, v[86:89], s[40:41] sc1 nt
	s_bitset1_b32 s98, 16
	v_pk_mul_f32 v[54:55], v[54:55], v[84:85] op_sel_hi:[1,0]
	s_waitcnt lgkmcnt(0)
	global_store_dwordx4 v100, v[94:97], s[40:41] sc1 nt
	s_bitset1_b32 s98, 17
	v_pk_mul_f32 v[86:87], v[150:151], v[84:85] op_sel_hi:[1,0]
	v_pk_mul_f32 v[88:89], v[148:149], v[84:85] op_sel_hi:[1,0]
	v_pk_fma_f32 v[86:87], v[86:87], v[82:83], v[14:15]
	v_pk_mul_f32 v[64:65], v[64:65], v[84:85] op_sel_hi:[1,0]
	v_pk_fma_f32 v[62:63], v[62:63], v[78:79], v[10:11]
	v_pk_mul_f32 v[56:57], v[56:57], v[84:85] op_sel_hi:[1,0]
	v_pk_fma_f32 v[54:55], v[54:55], v[74:75], v[6:7]
	v_pk_fma_f32 v[88:89], v[88:89], v[80:81], v[16:17]
	v_cvt_pk_bf16_f32 v86, v86, v87
	v_pk_fma_f32 v[64:65], v[64:65], v[76:77], v[12:13]
	v_cvt_pk_bf16_f32 v87, v88, v89
	ds_write_b64 v91, v[86:87]
	v_cvt_pk_bf16_f32 v62, v62, v63
	v_cvt_pk_bf16_f32 v63, v64, v65
	ds_write_b64 v91, v[62:63] offset:32
	v_pk_fma_f32 v[56:57], v[56:57], v[72:73], v[8:9]
	v_cvt_pk_bf16_f32 v54, v54, v55
	v_pk_mul_f32 v[52:53], v[52:53], v[84:85] op_sel_hi:[1,0]
	v_cvt_pk_bf16_f32 v55, v56, v57
	ds_write_b64 v91, v[54:55] offset:64
	v_pk_mul_f32 v[54:55], v[146:147], v[84:85] op_sel_hi:[1,0]
	v_pk_fma_f32 v[52:53], v[52:53], v[68:69], v[4:5]
	v_pk_fma_f32 v[54:55], v[54:55], v[70:71], v[2:3]
	v_add_u32_e32 v84, 0x48000, v92
	v_cvt_pk_bf16_f32 v54, v54, v55
	v_cvt_pk_bf16_f32 v55, v52, v53
	ds_write_b64 v91, v[54:55] offset:96
	ds_read_b128 v[52:55], v90
	ds_read_b128 v[62:65], v90 offset:1152
	s_waitcnt lgkmcnt(1)
	global_store_dwordx4 v93, v[52:55], s[18:19] sc1 nt
	s_bitset1_b32 s98, 18
	s_waitcnt lgkmcnt(0)
	global_store_dwordx4 v100, v[62:65], s[18:19] sc1 nt
	s_bitset1_b32 s98, 19
	v_cvt_pk_bf16_f32 v52, v110, v111
	v_cvt_pk_bf16_f32 v53, v112, v113
	ds_write_b64 v91, v[52:53]
	v_cvt_pk_bf16_f32 v52, v106, v107
	v_cvt_pk_bf16_f32 v53, v60, v61
	ds_write_b64 v91, v[52:53] offset:32
	v_cvt_pk_bf16_f32 v52, v102, v103
	v_cvt_pk_bf16_f32 v53, v58, v59
	ds_write_b64 v91, v[52:53] offset:64
	v_cvt_pk_bf16_f32 v52, v98, v99
	v_cvt_pk_bf16_f32 v53, v50, v51
	ds_write_b64 v91, v[52:53] offset:96
	ds_read_b128 v[52:55], v90
	ds_read_b128 v[62:65], v90 offset:1152
	v_add_u32_e32 v86, 0x4c000, v92
	s_waitcnt lgkmcnt(1)
	global_store_dwordx4 v84, v[52:55], s[40:41] sc1 nt
	s_bitset1_b32 s98, 20
	s_nop 1
	v_mov_b32_e32 v52, v85
	v_pk_mul_f32 v[54:55], v[110:111], v[52:53] op_sel_hi:[1,0]
	s_waitcnt lgkmcnt(0)
	global_store_dwordx4 v86, v[62:65], s[40:41] sc1 nt
	s_bitset1_b32 s98, 21
	v_pk_mul_f32 v[56:57], v[112:113], v[52:53] op_sel_hi:[1,0]
	v_pk_fma_f32 v[54:55], v[54:55], v[82:83], v[14:15]
	v_pk_fma_f32 v[56:57], v[56:57], v[80:81], v[16:17]
	v_cvt_pk_bf16_f32 v54, v54, v55
	v_pk_mul_f32 v[50:51], v[50:51], v[52:53] op_sel_hi:[1,0]
	v_cvt_pk_bf16_f32 v55, v56, v57
	ds_write_b64 v91, v[54:55]
	v_pk_mul_f32 v[54:55], v[106:107], v[52:53] op_sel_hi:[1,0]
	v_pk_mul_f32 v[56:57], v[60:61], v[52:53] op_sel_hi:[1,0]
	v_pk_fma_f32 v[54:55], v[54:55], v[78:79], v[10:11]
	v_pk_fma_f32 v[56:57], v[56:57], v[76:77], v[12:13]
	v_cvt_pk_bf16_f32 v54, v54, v55
	v_pk_fma_f32 v[50:51], v[50:51], v[68:69], v[4:5]
	v_cvt_pk_bf16_f32 v55, v56, v57
	ds_write_b64 v91, v[54:55] offset:32
	v_pk_mul_f32 v[54:55], v[102:103], v[52:53] op_sel_hi:[1,0]
	v_pk_mul_f32 v[56:57], v[58:59], v[52:53] op_sel_hi:[1,0]
	v_pk_fma_f32 v[54:55], v[54:55], v[74:75], v[6:7]
	v_pk_fma_f32 v[56:57], v[56:57], v[72:73], v[8:9]
	v_cvt_pk_bf16_f32 v54, v54, v55
	v_add_u32_e32 v58, 0x50000, v92
	v_cvt_pk_bf16_f32 v55, v56, v57
	ds_write_b64 v91, v[54:55] offset:64
	v_pk_mul_f32 v[54:55], v[98:99], v[52:53] op_sel_hi:[1,0]
	s_nop 0
	v_pk_fma_f32 v[52:53], v[54:55], v[70:71], v[2:3]
	s_nop 0
	v_cvt_pk_bf16_f32 v52, v52, v53
	v_cvt_pk_bf16_f32 v53, v50, v51
	ds_write_b64 v91, v[52:53] offset:96
	ds_read_b128 v[50:53], v90
	ds_read_b128 v[54:57], v90 offset:1152
	s_waitcnt lgkmcnt(1)
	global_store_dwordx4 v84, v[50:53], s[18:19] sc1 nt
	s_bitset1_b32 s98, 22
	s_waitcnt lgkmcnt(0)
	global_store_dwordx4 v86, v[54:57], s[18:19] sc1 nt
	s_bitset1_b32 s98, 23
	v_cvt_pk_bf16_f32 v50, v44, v45
	v_cvt_pk_bf16_f32 v51, v36, v37
	ds_write_b64 v91, v[50:51]
	v_cvt_pk_bf16_f32 v50, v42, v43
	v_cvt_pk_bf16_f32 v51, v34, v35
	ds_write_b64 v91, v[50:51] offset:32
	v_cvt_pk_bf16_f32 v50, v46, v47
	v_cvt_pk_bf16_f32 v51, v38, v39
	ds_write_b64 v91, v[50:51] offset:64
	v_cvt_pk_bf16_f32 v50, v48, v49
	v_cvt_pk_bf16_f32 v51, v40, v41
	ds_write_b64 v91, v[50:51] offset:96
	ds_read_b128 v[50:53], v90
	ds_read_b128 v[54:57], v90 offset:1152
	v_pk_mul_f32 v[44:45], v[44:45], v[66:67] op_sel_hi:[1,0]
	v_pk_mul_f32 v[36:37], v[36:37], v[66:67] op_sel_hi:[1,0]
	v_pk_fma_f32 v[44:45], v[44:45], v[82:83], v[14:15]
	s_waitcnt lgkmcnt(1)
	global_store_dwordx4 v58, v[50:53], s[40:41] sc1 nt
	s_bitset1_b32 s98, 24
	v_pk_fma_f32 v[36:37], v[36:37], v[80:81], v[16:17]
	v_pk_mul_f32 v[34:35], v[34:35], v[66:67] op_sel_hi:[1,0]
	v_add_u32_e32 v50, 0x54000, v92
	s_waitcnt lgkmcnt(0)
	global_store_dwordx4 v50, v[54:57], s[40:41] sc1 nt
	s_bitset1_b32 s98, 25
	v_cvt_pk_bf16_f32 v44, v44, v45
	v_cvt_pk_bf16_f32 v45, v36, v37
	v_pk_mul_f32 v[36:37], v[42:43], v[66:67] op_sel_hi:[1,0]
	v_pk_fma_f32 v[34:35], v[34:35], v[76:77], v[12:13]
	v_pk_fma_f32 v[36:37], v[36:37], v[78:79], v[10:11]
	ds_write_b64 v91, v[44:45]
	v_cvt_pk_bf16_f32 v36, v36, v37
	v_cvt_pk_bf16_f32 v37, v34, v35
	v_pk_mul_f32 v[34:35], v[46:47], v[66:67] op_sel_hi:[1,0]
	ds_write_b64 v91, v[36:37] offset:32
	v_pk_mul_f32 v[36:37], v[38:39], v[66:67] op_sel_hi:[1,0]
	v_pk_fma_f32 v[34:35], v[34:35], v[74:75], v[6:7]
	v_pk_fma_f32 v[36:37], v[36:37], v[72:73], v[8:9]
	v_cvt_pk_bf16_f32 v34, v34, v35
	v_add_u32_e32 v42, 0x58000, v92
	v_cvt_pk_bf16_f32 v35, v36, v37
	ds_write_b64 v91, v[34:35] offset:64
	v_pk_mul_f32 v[34:35], v[48:49], v[66:67] op_sel_hi:[1,0]
	v_pk_mul_f32 v[36:37], v[40:41], v[66:67] op_sel_hi:[1,0]
	v_pk_fma_f32 v[34:35], v[34:35], v[70:71], v[2:3]
	v_pk_fma_f32 v[36:37], v[36:37], v[68:69], v[4:5]
	v_cvt_pk_bf16_f32 v34, v34, v35
	s_nop 0
	v_cvt_pk_bf16_f32 v35, v36, v37
	ds_write_b64 v91, v[34:35] offset:96
	ds_read_b128 v[34:37], v90
	ds_read_b128 v[38:41], v90 offset:1152
	s_waitcnt lgkmcnt(1)
	global_store_dwordx4 v58, v[34:37], s[18:19] sc1 nt
	s_bitset1_b32 s98, 26
	s_waitcnt lgkmcnt(0)
	global_store_dwordx4 v50, v[38:41], s[18:19] sc1 nt
	s_bitset1_b32 s98, 27
	v_cvt_pk_bf16_f32 v34, v32, v33
	v_cvt_pk_bf16_f32 v35, v24, v25
	ds_write_b64 v91, v[34:35]
	v_cvt_pk_bf16_f32 v34, v30, v31
	v_cvt_pk_bf16_f32 v35, v22, v23
	ds_write_b64 v91, v[34:35] offset:32
	v_cvt_pk_bf16_f32 v34, v28, v29
	v_cvt_pk_bf16_f32 v35, v20, v21
	ds_write_b64 v91, v[34:35] offset:64
	v_cvt_pk_bf16_f32 v34, v26, v27
	v_cvt_pk_bf16_f32 v35, v18, v19
	ds_write_b64 v91, v[34:35] offset:96
	ds_read_b128 v[34:37], v90
	ds_read_b128 v[38:41], v90 offset:1152
	s_waitcnt lgkmcnt(1)
	global_store_dwordx4 v42, v[34:37], s[40:41] sc1 nt
	s_bitset1_b32 s98, 28
	s_nop 1
	v_add_u32_e32 v35, 0x5c000, v92
	v_mov_b32_e32 v34, v67
	v_pk_mul_f32 v[32:33], v[32:33], v[34:35] op_sel_hi:[1,0]
	s_waitcnt lgkmcnt(0)
	global_store_dwordx4 v35, v[38:41], s[40:41] sc1 nt
	s_bitset1_b32 s98, 29
	v_pk_mul_f32 v[24:25], v[24:25], v[34:35] op_sel_hi:[1,0]
	v_pk_fma_f32 v[14:15], v[32:33], v[82:83], v[14:15]
	v_pk_fma_f32 v[16:17], v[24:25], v[80:81], v[16:17]
	v_cvt_pk_bf16_f32 v14, v14, v15
	s_nop 0
	v_cvt_pk_bf16_f32 v15, v16, v17
	ds_write_b64 v91, v[14:15]
	v_pk_mul_f32 v[14:15], v[30:31], v[34:35] op_sel_hi:[1,0]
	v_pk_mul_f32 v[16:17], v[22:23], v[34:35] op_sel_hi:[1,0]
	v_pk_fma_f32 v[10:11], v[14:15], v[78:79], v[10:11]
	v_pk_fma_f32 v[12:13], v[16:17], v[76:77], v[12:13]
	v_cvt_pk_bf16_f32 v10, v10, v11
	s_nop 0
	v_cvt_pk_bf16_f32 v11, v12, v13
	ds_write_b64 v91, v[10:11] offset:32
	v_pk_mul_f32 v[10:11], v[28:29], v[34:35] op_sel_hi:[1,0]
	v_pk_mul_f32 v[12:13], v[20:21], v[34:35] op_sel_hi:[1,0]
	v_pk_fma_f32 v[6:7], v[10:11], v[74:75], v[6:7]
	v_pk_fma_f32 v[8:9], v[12:13], v[72:73], v[8:9]
	v_cvt_pk_bf16_f32 v6, v6, v7
	s_nop 0
	v_cvt_pk_bf16_f32 v7, v8, v9
	ds_write_b64 v91, v[6:7] offset:64
	v_pk_mul_f32 v[6:7], v[26:27], v[34:35] op_sel_hi:[1,0]
	v_pk_mul_f32 v[8:9], v[18:19], v[34:35] op_sel_hi:[1,0]
	v_pk_fma_f32 v[2:3], v[6:7], v[70:71], v[2:3]
	v_pk_fma_f32 v[4:5], v[8:9], v[68:69], v[4:5]
	v_cvt_pk_bf16_f32 v2, v2, v3
	s_nop 0
	v_cvt_pk_bf16_f32 v3, v4, v5
	ds_write_b64 v91, v[2:3] offset:96
	ds_read_b128 v[2:5], v90
	ds_read_b128 v[6:9], v90 offset:1152
	s_waitcnt lgkmcnt(1)
	global_store_dwordx4 v42, v[2:5], s[18:19] sc1 nt
	s_bitset1_b32 s98, 30
	s_waitcnt lgkmcnt(0)
	global_store_dwordx4 v35, v[6:9], s[18:19] sc1 nt
	s_bitset1_b32 s98, 31
	s_cbranch_vccnz .LBB0_654
	s_andn2_b64 vcc, exec, s[46:47]
	s_cbranch_vccnz .LBB0_653
	s_barrier
	s_branch .LBB0_653

.LBB0_783:
	s_lshl_b32 s98, s4, 8
	s_add_i32 s98, s98, s59
	s_lshl_b32 s98, s98, 13
	s_lshl_b32 s99, s5, 9
	s_add_u32 s98, s98, s99
	s_add_u32 s98, s98, s8
	s_add_u32 s98, s14, s98
	s_addc_u32 s99, s15, 0
	v_and_b32_e32 v148, 7, v1
	v_lshlrev_b32_e32 v148, 13, v148
	v_lshl_add_u32 v148, v150, 4, v148
	v_and_b32_e32 v149, 8, v1
	v_lshl_add_u32 v148, v149, 3, v148
	v_max_f32_e32 v122, 0, v122
	v_max_f32_e32 v123, 0, v123
	v_max_f32_e32 v124, 0, v124
	v_max_f32_e32 v125, 0, v125
	v_max_f32_e32 v126, 0, v126
	v_max_f32_e32 v127, 0, v127
	v_max_f32_e32 v128, 0, v128
	v_max_f32_e32 v129, 0, v129
	v_max_f32_e32 v114, 0, v114
	v_max_f32_e32 v115, 0, v115
	v_max_f32_e32 v116, 0, v116
	v_max_f32_e32 v117, 0, v117
	v_max_f32_e32 v118, 0, v118
	v_max_f32_e32 v119, 0, v119
	v_max_f32_e32 v120, 0, v120
	v_max_f32_e32 v121, 0, v121
	v_mul_f32_e32 v122, v122, v122
	v_mul_f32_e32 v123, v123, v123
	v_mul_f32_e32 v124, v124, v124
	v_mul_f32_e32 v125, v125, v125
	v_mul_f32_e32 v126, v126, v126
	v_mul_f32_e32 v127, v127, v127
	v_mul_f32_e32 v128, v128, v128
	v_mul_f32_e32 v129, v129, v129
	v_mul_f32_e32 v114, v114, v114
	v_mul_f32_e32 v115, v115, v115
	v_mul_f32_e32 v116, v116, v116
	v_mul_f32_e32 v117, v117, v117
	v_mul_f32_e32 v118, v118, v118
	v_mul_f32_e32 v119, v119, v119
	v_mul_f32_e32 v120, v120, v120
	v_mul_f32_e32 v121, v121, v121
	v_cvt_pk_bf16_f32 v126, v126, v127
	v_cvt_pk_bf16_f32 v127, v128, v129
	v_cvt_pk_bf16_f32 v128, v122, v123
	v_cvt_pk_bf16_f32 v129, v124, v125
	v_cvt_pk_bf16_f32 v118, v118, v119
	v_cvt_pk_bf16_f32 v119, v120, v121
	v_cvt_pk_bf16_f32 v120, v114, v115
	v_cvt_pk_bf16_f32 v121, v116, v117
	v_mov_b32_e32 v122, v126
	v_mov_b32_e32 v123, v127
	v_mov_b32_e32 v124, v128
	v_mov_b32_e32 v125, v129
	v_mov_b32_dpp v126, v118 row_ror:8 row_mask:0xf bank_mask:0xc
	v_mov_b32_dpp v127, v119 row_ror:8 row_mask:0xf bank_mask:0xc
	v_mov_b32_dpp v128, v120 row_ror:8 row_mask:0xf bank_mask:0xc
	v_mov_b32_dpp v129, v121 row_ror:8 row_mask:0xf bank_mask:0xc
	v_mov_b32_dpp v118, v122 row_ror:8 row_mask:0xf bank_mask:0x3
	v_mov_b32_dpp v119, v123 row_ror:8 row_mask:0xf bank_mask:0x3
	v_mov_b32_dpp v120, v124 row_ror:8 row_mask:0xf bank_mask:0x3
	v_mov_b32_dpp v121, v125 row_ror:8 row_mask:0xf bank_mask:0x3
	global_store_dwordx4 v148, v[126:129], s[98:99] sc1 nt
	s_add_u32 s98, s98, 0x10000
	s_addc_u32 s99, s99, 0
	global_store_dwordx4 v148, v[118:121], s[98:99] sc1 nt
	v_max_f32_e32 v106, 0, v106
	v_max_f32_e32 v107, 0, v107
	v_max_f32_e32 v108, 0, v108
	v_max_f32_e32 v109, 0, v109
	v_max_f32_e32 v110, 0, v110
	v_max_f32_e32 v111, 0, v111
	v_max_f32_e32 v112, 0, v112
	v_max_f32_e32 v113, 0, v113
	v_max_f32_e32 v98, 0, v98
	v_max_f32_e32 v99, 0, v99
	v_max_f32_e32 v100, 0, v100
	v_max_f32_e32 v101, 0, v101
	v_max_f32_e32 v102, 0, v102
	v_max_f32_e32 v103, 0, v103
	v_max_f32_e32 v104, 0, v104
	v_max_f32_e32 v105, 0, v105
	v_mul_f32_e32 v106, v106, v106
	v_mul_f32_e32 v107, v107, v107
	v_mul_f32_e32 v108, v108, v108
	v_mul_f32_e32 v109, v109, v109
	v_mul_f32_e32 v110, v110, v110
	v_mul_f32_e32 v111, v111, v111
	v_mul_f32_e32 v112, v112, v112
	v_mul_f32_e32 v113, v113, v113
	v_mul_f32_e32 v98, v98, v98
	v_mul_f32_e32 v99, v99, v99
	v_mul_f32_e32 v100, v100, v100
	v_mul_f32_e32 v101, v101, v101
	v_mul_f32_e32 v102, v102, v102
	v_mul_f32_e32 v103, v103, v103
	v_mul_f32_e32 v104, v104, v104
	v_mul_f32_e32 v105, v105, v105
	v_cvt_pk_bf16_f32 v110, v110, v111
	v_cvt_pk_bf16_f32 v111, v112, v113
	v_cvt_pk_bf16_f32 v112, v106, v107
	v_cvt_pk_bf16_f32 v113, v108, v109
	v_cvt_pk_bf16_f32 v102, v102, v103
	v_cvt_pk_bf16_f32 v103, v104, v105
	v_cvt_pk_bf16_f32 v104, v98, v99
	v_cvt_pk_bf16_f32 v105, v100, v101
	v_mov_b32_e32 v106, v110
	v_mov_b32_e32 v107, v111
	v_mov_b32_e32 v108, v112
	v_mov_b32_e32 v109, v113
	v_mov_b32_dpp v110, v102 row_ror:8 row_mask:0xf bank_mask:0xc
	v_mov_b32_dpp v111, v103 row_ror:8 row_mask:0xf bank_mask:0xc
	v_mov_b32_dpp v112, v104 row_ror:8 row_mask:0xf bank_mask:0xc
	v_mov_b32_dpp v113, v105 row_ror:8 row_mask:0xf bank_mask:0xc
	v_mov_b32_dpp v102, v106 row_ror:8 row_mask:0xf bank_mask:0x3
	v_mov_b32_dpp v103, v107 row_ror:8 row_mask:0xf bank_mask:0x3
	v_mov_b32_dpp v104, v108 row_ror:8 row_mask:0xf bank_mask:0x3
	v_mov_b32_dpp v105, v109 row_ror:8 row_mask:0xf bank_mask:0x3
	s_add_u32 s98, s98, 0x10000
	s_addc_u32 s99, s99, 0
	global_store_dwordx4 v148, v[110:113], s[98:99] sc1 nt
	s_add_u32 s98, s98, 0x10000
	s_addc_u32 s99, s99, 0
	global_store_dwordx4 v148, v[102:105], s[98:99] sc1 nt
	v_max_f32_e32 v90, 0, v90
	v_max_f32_e32 v91, 0, v91
	v_max_f32_e32 v92, 0, v92
	v_max_f32_e32 v93, 0, v93
	v_max_f32_e32 v94, 0, v94
	v_max_f32_e32 v95, 0, v95
	v_max_f32_e32 v96, 0, v96
	v_max_f32_e32 v97, 0, v97
	v_max_f32_e32 v82, 0, v82
	v_max_f32_e32 v83, 0, v83
	v_max_f32_e32 v84, 0, v84
	v_max_f32_e32 v85, 0, v85
	v_max_f32_e32 v86, 0, v86
	v_max_f32_e32 v87, 0, v87
	v_max_f32_e32 v88, 0, v88
	v_max_f32_e32 v89, 0, v89
	v_mul_f32_e32 v90, v90, v90
	v_mul_f32_e32 v91, v91, v91
	v_mul_f32_e32 v92, v92, v92
	v_mul_f32_e32 v93, v93, v93
	v_mul_f32_e32 v94, v94, v94
	v_mul_f32_e32 v95, v95, v95
	v_mul_f32_e32 v96, v96, v96
	v_mul_f32_e32 v97, v97, v97
	v_mul_f32_e32 v82, v82, v82
	v_mul_f32_e32 v83, v83, v83
	v_mul_f32_e32 v84, v84, v84
	v_mul_f32_e32 v85, v85, v85
	v_mul_f32_e32 v86, v86, v86
	v_mul_f32_e32 v87, v87, v87
	v_mul_f32_e32 v88, v88, v88
	v_mul_f32_e32 v89, v89, v89
	v_cvt_pk_bf16_f32 v94, v94, v95
	v_cvt_pk_bf16_f32 v95, v96, v97
	v_cvt_pk_bf16_f32 v96, v90, v91
	v_cvt_pk_bf16_f32 v97, v92, v93
	v_cvt_pk_bf16_f32 v86, v86, v87
	v_cvt_pk_bf16_f32 v87, v88, v89
	v_cvt_pk_bf16_f32 v88, v82, v83
	v_cvt_pk_bf16_f32 v89, v84, v85
	v_mov_b32_e32 v90, v94
	v_mov_b32_e32 v91, v95
	v_mov_b32_e32 v92, v96
	v_mov_b32_e32 v93, v97
	v_mov_b32_dpp v94, v86 row_ror:8 row_mask:0xf bank_mask:0xc
	v_mov_b32_dpp v95, v87 row_ror:8 row_mask:0xf bank_mask:0xc
	v_mov_b32_dpp v96, v88 row_ror:8 row_mask:0xf bank_mask:0xc
	v_mov_b32_dpp v97, v89 row_ror:8 row_mask:0xf bank_mask:0xc
	v_mov_b32_dpp v86, v90 row_ror:8 row_mask:0xf bank_mask:0x3
	v_mov_b32_dpp v87, v91 row_ror:8 row_mask:0xf bank_mask:0x3
	v_mov_b32_dpp v88, v92 row_ror:8 row_mask:0xf bank_mask:0x3
	v_mov_b32_dpp v89, v93 row_ror:8 row_mask:0xf bank_mask:0x3
	s_add_u32 s98, s98, 0x10000
	s_addc_u32 s99, s99, 0
	global_store_dwordx4 v148, v[94:97], s[98:99] sc1 nt
	s_add_u32 s98, s98, 0x10000
	s_addc_u32 s99, s99, 0
	global_store_dwordx4 v148, v[86:89], s[98:99] sc1 nt
	v_max_f32_e32 v74, 0, v74
	v_max_f32_e32 v75, 0, v75
	v_max_f32_e32 v76, 0, v76
	v_max_f32_e32 v77, 0, v77
	v_max_f32_e32 v78, 0, v78
	v_max_f32_e32 v79, 0, v79
	v_max_f32_e32 v80, 0, v80
	v_max_f32_e32 v81, 0, v81
	v_max_f32_e32 v66, 0, v66
	v_max_f32_e32 v67, 0, v67
	v_max_f32_e32 v68, 0, v68
	v_max_f32_e32 v69, 0, v69
	v_max_f32_e32 v70, 0, v70
	v_max_f32_e32 v71, 0, v71
	v_max_f32_e32 v72, 0, v72
	v_max_f32_e32 v73, 0, v73
	v_mul_f32_e32 v74, v74, v74
	v_mul_f32_e32 v75, v75, v75
	v_mul_f32_e32 v76, v76, v76
	v_mul_f32_e32 v77, v77, v77
	v_mul_f32_e32 v78, v78, v78
	v_mul_f32_e32 v79, v79, v79
	v_mul_f32_e32 v80, v80, v80
	v_mul_f32_e32 v81, v81, v81
	v_mul_f32_e32 v66, v66, v66
	v_mul_f32_e32 v67, v67, v67
	v_mul_f32_e32 v68, v68, v68
	v_mul_f32_e32 v69, v69, v69
	v_mul_f32_e32 v70, v70, v70
	v_mul_f32_e32 v71, v71, v71
	v_mul_f32_e32 v72, v72, v72
	v_mul_f32_e32 v73, v73, v73
	v_cvt_pk_bf16_f32 v78, v78, v79
	v_cvt_pk_bf16_f32 v79, v80, v81
	v_cvt_pk_bf16_f32 v80, v74, v75
	v_cvt_pk_bf16_f32 v81, v76, v77
	v_cvt_pk_bf16_f32 v70, v70, v71
	v_cvt_pk_bf16_f32 v71, v72, v73
	v_cvt_pk_bf16_f32 v72, v66, v67
	v_cvt_pk_bf16_f32 v73, v68, v69
	v_mov_b32_e32 v74, v78
	v_mov_b32_e32 v75, v79
	v_mov_b32_e32 v76, v80
	v_mov_b32_e32 v77, v81
	v_mov_b32_dpp v78, v70 row_ror:8 row_mask:0xf bank_mask:0xc
	v_mov_b32_dpp v79, v71 row_ror:8 row_mask:0xf bank_mask:0xc
	v_mov_b32_dpp v80, v72 row_ror:8 row_mask:0xf bank_mask:0xc
	v_mov_b32_dpp v81, v73 row_ror:8 row_mask:0xf bank_mask:0xc
	v_mov_b32_dpp v70, v74 row_ror:8 row_mask:0xf bank_mask:0x3
	v_mov_b32_dpp v71, v75 row_ror:8 row_mask:0xf bank_mask:0x3
	v_mov_b32_dpp v72, v76 row_ror:8 row_mask:0xf bank_mask:0x3
	v_mov_b32_dpp v73, v77 row_ror:8 row_mask:0xf bank_mask:0x3
	s_add_u32 s98, s98, 0x10000
	s_addc_u32 s99, s99, 0
	global_store_dwordx4 v148, v[78:81], s[98:99] sc1 nt
	s_add_u32 s98, s98, 0x10000
	s_addc_u32 s99, s99, 0
	global_store_dwordx4 v148, v[70:73], s[98:99] sc1 nt
	v_max_f32_e32 v58, 0, v58
	v_max_f32_e32 v59, 0, v59
	v_max_f32_e32 v60, 0, v60
	v_max_f32_e32 v61, 0, v61
	v_max_f32_e32 v62, 0, v62
	v_max_f32_e32 v63, 0, v63
	v_max_f32_e32 v64, 0, v64
	v_max_f32_e32 v65, 0, v65
	v_max_f32_e32 v50, 0, v50
	v_max_f32_e32 v51, 0, v51
	v_max_f32_e32 v52, 0, v52
	v_max_f32_e32 v53, 0, v53
	v_max_f32_e32 v54, 0, v54
	v_max_f32_e32 v55, 0, v55
	v_max_f32_e32 v56, 0, v56
	v_max_f32_e32 v57, 0, v57
	v_mul_f32_e32 v58, v58, v58
	v_mul_f32_e32 v59, v59, v59
	v_mul_f32_e32 v60, v60, v60
	v_mul_f32_e32 v61, v61, v61
	v_mul_f32_e32 v62, v62, v62
	v_mul_f32_e32 v63, v63, v63
	v_mul_f32_e32 v64, v64, v64
	v_mul_f32_e32 v65, v65, v65
	v_mul_f32_e32 v50, v50, v50
	v_mul_f32_e32 v51, v51, v51
	v_mul_f32_e32 v52, v52, v52
	v_mul_f32_e32 v53, v53, v53
	v_mul_f32_e32 v54, v54, v54
	v_mul_f32_e32 v55, v55, v55
	v_mul_f32_e32 v56, v56, v56
	v_mul_f32_e32 v57, v57, v57
	v_cvt_pk_bf16_f32 v62, v62, v63
	v_cvt_pk_bf16_f32 v63, v64, v65
	v_cvt_pk_bf16_f32 v64, v58, v59
	v_cvt_pk_bf16_f32 v65, v60, v61
	v_cvt_pk_bf16_f32 v54, v54, v55
	v_cvt_pk_bf16_f32 v55, v56, v57
	v_cvt_pk_bf16_f32 v56, v50, v51
	v_cvt_pk_bf16_f32 v57, v52, v53
	v_mov_b32_e32 v58, v62
	v_mov_b32_e32 v59, v63
	v_mov_b32_e32 v60, v64
	v_mov_b32_e32 v61, v65
	v_mov_b32_dpp v62, v54 row_ror:8 row_mask:0xf bank_mask:0xc
	v_mov_b32_dpp v63, v55 row_ror:8 row_mask:0xf bank_mask:0xc
	v_mov_b32_dpp v64, v56 row_ror:8 row_mask:0xf bank_mask:0xc
	v_mov_b32_dpp v65, v57 row_ror:8 row_mask:0xf bank_mask:0xc
	v_mov_b32_dpp v54, v58 row_ror:8 row_mask:0xf bank_mask:0x3
	v_mov_b32_dpp v55, v59 row_ror:8 row_mask:0xf bank_mask:0x3
	v_mov_b32_dpp v56, v60 row_ror:8 row_mask:0xf bank_mask:0x3
	v_mov_b32_dpp v57, v61 row_ror:8 row_mask:0xf bank_mask:0x3
	s_add_u32 s98, s98, 0x90000
	s_addc_u32 s99, s99, 0
	global_store_dwordx4 v148, v[62:65], s[98:99] sc1 nt
	s_add_u32 s98, s98, 0x10000
	s_addc_u32 s99, s99, 0
	global_store_dwordx4 v148, v[54:57], s[98:99] sc1 nt
	v_max_f32_e32 v42, 0, v42
	v_max_f32_e32 v43, 0, v43
	v_max_f32_e32 v44, 0, v44
	v_max_f32_e32 v45, 0, v45
	v_max_f32_e32 v46, 0, v46
	v_max_f32_e32 v47, 0, v47
	v_max_f32_e32 v48, 0, v48
	v_max_f32_e32 v49, 0, v49
	v_max_f32_e32 v34, 0, v34
	v_max_f32_e32 v35, 0, v35
	v_max_f32_e32 v36, 0, v36
	v_max_f32_e32 v37, 0, v37
	v_max_f32_e32 v38, 0, v38
	v_max_f32_e32 v39, 0, v39
	v_max_f32_e32 v40, 0, v40
	v_max_f32_e32 v41, 0, v41
	v_mul_f32_e32 v42, v42, v42
	v_mul_f32_e32 v43, v43, v43
	v_mul_f32_e32 v44, v44, v44
	v_mul_f32_e32 v45, v45, v45
	v_mul_f32_e32 v46, v46, v46
	v_mul_f32_e32 v47, v47, v47
	v_mul_f32_e32 v48, v48, v48
	v_mul_f32_e32 v49, v49, v49
	v_mul_f32_e32 v34, v34, v34
	v_mul_f32_e32 v35, v35, v35
	v_mul_f32_e32 v36, v36, v36
	v_mul_f32_e32 v37, v37, v37
	v_mul_f32_e32 v38, v38, v38
	v_mul_f32_e32 v39, v39, v39
	v_mul_f32_e32 v40, v40, v40
	v_mul_f32_e32 v41, v41, v41
	v_cvt_pk_bf16_f32 v46, v46, v47
	v_cvt_pk_bf16_f32 v47, v48, v49
	v_cvt_pk_bf16_f32 v48, v42, v43
	v_cvt_pk_bf16_f32 v49, v44, v45
	v_cvt_pk_bf16_f32 v38, v38, v39
	v_cvt_pk_bf16_f32 v39, v40, v41
	v_cvt_pk_bf16_f32 v40, v34, v35
	v_cvt_pk_bf16_f32 v41, v36, v37
	v_mov_b32_e32 v42, v46
	v_mov_b32_e32 v43, v47
	v_mov_b32_e32 v44, v48
	v_mov_b32_e32 v45, v49
	v_mov_b32_dpp v46, v38 row_ror:8 row_mask:0xf bank_mask:0xc
	v_mov_b32_dpp v47, v39 row_ror:8 row_mask:0xf bank_mask:0xc
	v_mov_b32_dpp v48, v40 row_ror:8 row_mask:0xf bank_mask:0xc
	v_mov_b32_dpp v49, v41 row_ror:8 row_mask:0xf bank_mask:0xc
	v_mov_b32_dpp v38, v42 row_ror:8 row_mask:0xf bank_mask:0x3
	v_mov_b32_dpp v39, v43 row_ror:8 row_mask:0xf bank_mask:0x3
	v_mov_b32_dpp v40, v44 row_ror:8 row_mask:0xf bank_mask:0x3
	v_mov_b32_dpp v41, v45 row_ror:8 row_mask:0xf bank_mask:0x3
	s_add_u32 s98, s98, 0x10000
	s_addc_u32 s99, s99, 0
	global_store_dwordx4 v148, v[46:49], s[98:99] sc1 nt
	s_add_u32 s98, s98, 0x10000
	s_addc_u32 s99, s99, 0
	global_store_dwordx4 v148, v[38:41], s[98:99] sc1 nt
	v_max_f32_e32 v26, 0, v26
	v_max_f32_e32 v27, 0, v27
	v_max_f32_e32 v28, 0, v28
	v_max_f32_e32 v29, 0, v29
	v_max_f32_e32 v30, 0, v30
	v_max_f32_e32 v31, 0, v31
	v_max_f32_e32 v32, 0, v32
	v_max_f32_e32 v33, 0, v33
	v_max_f32_e32 v18, 0, v18
	v_max_f32_e32 v19, 0, v19
	v_max_f32_e32 v20, 0, v20
	v_max_f32_e32 v21, 0, v21
	v_max_f32_e32 v22, 0, v22
	v_max_f32_e32 v23, 0, v23
	v_max_f32_e32 v24, 0, v24
	v_max_f32_e32 v25, 0, v25
	v_mul_f32_e32 v26, v26, v26
	v_mul_f32_e32 v27, v27, v27
	v_mul_f32_e32 v28, v28, v28
	v_mul_f32_e32 v29, v29, v29
	v_mul_f32_e32 v30, v30, v30
	v_mul_f32_e32 v31, v31, v31
	v_mul_f32_e32 v32, v32, v32
	v_mul_f32_e32 v33, v33, v33
	v_mul_f32_e32 v18, v18, v18
	v_mul_f32_e32 v19, v19, v19
	v_mul_f32_e32 v20, v20, v20
	v_mul_f32_e32 v21, v21, v21
	v_mul_f32_e32 v22, v22, v22
	v_mul_f32_e32 v23, v23, v23
	v_mul_f32_e32 v24, v24, v24
	v_mul_f32_e32 v25, v25, v25
	v_cvt_pk_bf16_f32 v30, v30, v31
	v_cvt_pk_bf16_f32 v31, v32, v33
	v_cvt_pk_bf16_f32 v32, v26, v27
	v_cvt_pk_bf16_f32 v33, v28, v29
	v_cvt_pk_bf16_f32 v22, v22, v23
	v_cvt_pk_bf16_f32 v23, v24, v25
	v_cvt_pk_bf16_f32 v24, v18, v19
	v_cvt_pk_bf16_f32 v25, v20, v21
	v_mov_b32_e32 v26, v30
	v_mov_b32_e32 v27, v31
	v_mov_b32_e32 v28, v32
	v_mov_b32_e32 v29, v33
	v_mov_b32_dpp v30, v22 row_ror:8 row_mask:0xf bank_mask:0xc
	v_mov_b32_dpp v31, v23 row_ror:8 row_mask:0xf bank_mask:0xc
	v_mov_b32_dpp v32, v24 row_ror:8 row_mask:0xf bank_mask:0xc
	v_mov_b32_dpp v33, v25 row_ror:8 row_mask:0xf bank_mask:0xc
	v_mov_b32_dpp v22, v26 row_ror:8 row_mask:0xf bank_mask:0x3
	v_mov_b32_dpp v23, v27 row_ror:8 row_mask:0xf bank_mask:0x3
	v_mov_b32_dpp v24, v28 row_ror:8 row_mask:0xf bank_mask:0x3
	v_mov_b32_dpp v25, v29 row_ror:8 row_mask:0xf bank_mask:0x3
	s_add_u32 s98, s98, 0x10000
	s_addc_u32 s99, s99, 0
	global_store_dwordx4 v148, v[30:33], s[98:99] sc1 nt
	s_add_u32 s98, s98, 0x10000
	s_addc_u32 s99, s99, 0
	global_store_dwordx4 v148, v[22:25], s[98:99] sc1 nt
	v_max_f32_e32 v10, 0, v10
	v_max_f32_e32 v11, 0, v11
	v_max_f32_e32 v12, 0, v12
	v_max_f32_e32 v13, 0, v13
	v_max_f32_e32 v14, 0, v14
	v_max_f32_e32 v15, 0, v15
	v_max_f32_e32 v16, 0, v16
	v_max_f32_e32 v17, 0, v17
	v_max_f32_e32 v2, 0, v2
	v_max_f32_e32 v3, 0, v3
	v_max_f32_e32 v4, 0, v4
	v_max_f32_e32 v5, 0, v5
	v_max_f32_e32 v6, 0, v6
	v_max_f32_e32 v7, 0, v7
	v_max_f32_e32 v8, 0, v8
	v_max_f32_e32 v9, 0, v9
	v_mul_f32_e32 v10, v10, v10
	v_mul_f32_e32 v11, v11, v11
	v_mul_f32_e32 v12, v12, v12
	v_mul_f32_e32 v13, v13, v13
	v_mul_f32_e32 v14, v14, v14
	v_mul_f32_e32 v15, v15, v15
	v_mul_f32_e32 v16, v16, v16
	v_mul_f32_e32 v17, v17, v17
	v_mul_f32_e32 v2, v2, v2
	v_mul_f32_e32 v3, v3, v3
	v_mul_f32_e32 v4, v4, v4
	v_mul_f32_e32 v5, v5, v5
	v_mul_f32_e32 v6, v6, v6
	v_mul_f32_e32 v7, v7, v7
	v_mul_f32_e32 v8, v8, v8
	v_mul_f32_e32 v9, v9, v9
	v_cvt_pk_bf16_f32 v14, v14, v15
	v_cvt_pk_bf16_f32 v15, v16, v17
	v_cvt_pk_bf16_f32 v16, v10, v11
	v_cvt_pk_bf16_f32 v17, v12, v13
	v_cvt_pk_bf16_f32 v6, v6, v7
	v_cvt_pk_bf16_f32 v7, v8, v9
	v_cvt_pk_bf16_f32 v8, v2, v3
	v_cvt_pk_bf16_f32 v9, v4, v5
	v_mov_b32_e32 v10, v14
	v_mov_b32_e32 v11, v15
	v_mov_b32_e32 v12, v16
	v_mov_b32_e32 v13, v17
	v_mov_b32_dpp v14, v6 row_ror:8 row_mask:0xf bank_mask:0xc
	v_mov_b32_dpp v15, v7 row_ror:8 row_mask:0xf bank_mask:0xc
	v_mov_b32_dpp v16, v8 row_ror:8 row_mask:0xf bank_mask:0xc
	v_mov_b32_dpp v17, v9 row_ror:8 row_mask:0xf bank_mask:0xc
	v_mov_b32_dpp v6, v10 row_ror:8 row_mask:0xf bank_mask:0x3
	v_mov_b32_dpp v7, v11 row_ror:8 row_mask:0xf bank_mask:0x3
	v_mov_b32_dpp v8, v12 row_ror:8 row_mask:0xf bank_mask:0x3
	v_mov_b32_dpp v9, v13 row_ror:8 row_mask:0xf bank_mask:0x3
	s_add_u32 s98, s98, 0x10000
	s_addc_u32 s99, s99, 0
	global_store_dwordx4 v148, v[14:17], s[98:99] sc1 nt
	s_add_u32 s98, s98, 0x10000
	s_addc_u32 s99, s99, 0
	global_store_dwordx4 v148, v[6:9], s[98:99] sc1 nt
	s_andn2_b64 vcc, exec, s[0:1]
	s_mov_b64 s[0:1], -1
	s_mov_b32 s98, 1
	s_cbranch_vccnz .LBB0_772
	s_andn2_b64 vcc, exec, s[10:11]
	s_cbranch_vccnz .LBB0_771
	s_barrier
	s_branch .LBB0_771

.LBB0_900:
	s_or_b64 exec, exec, s[6:7]
	s_or_b32 s4, s51, s74
	s_ashr_i32 s5, s4, 31
	s_lshl_b64 s[6:7], s[4:5], 2
	s_add_u32 s6, s22, s6
	s_waitcnt lgkmcnt(0)
	s_barrier
	v_lshl_add_u32 v2, v199, 2, s82
	v_ashrrev_i32_e32 v161, 31, v160
	s_addc_u32 s7, s23, s7
	ds_read2_b32 v[172:173], v2 offset1:16
	ds_read2_b32 v[126:127], v2 offset0:32 offset1:48
	ds_read2_b32 v[120:121], v2 offset0:128 offset1:144
	ds_read2_b32 v[118:119], v2 offset0:160 offset1:176
	s_waitcnt lgkmcnt(0)
	s_waitcnt vmcnt(2)
	v_lshl_add_u64 v[2:3], v[160:161], 2, s[6:7]
	global_load_dwordx4 v[14:17], v[2:3], off
	global_load_dwordx4 v[10:13], v[2:3], off offset:64
	global_load_dwordx4 v[6:9], v[2:3], off offset:512
	s_nop 0
	global_load_dwordx4 v[2:5], v[2:3], off offset:576
	v_cmp_gt_i32_e32 vcc, 8, v199
	s_waitcnt lgkmcnt(3)
	v_pk_mul_f32 v[136:137], v[142:143], v[172:173] op_sel_hi:[1,0]
	v_pk_mul_f32 v[138:139], v[138:139], v[172:173] op_sel_hi:[1,0]
	v_pk_mul_f32 v[140:141], v[140:141], v[172:173] op_sel_hi:[1,0]
	v_and_or_b32 v128, v199, 7, s49
	v_cndmask_b32_e64 v129, 64, 0, vcc
	v_mov_b32_e32 v178, 0
	v_mov_b32_e32 v179, 0
	v_mov_b32_e32 v181, 0
	v_mov_b32_e32 v183, 0
	v_mov_b32_e32 v185, 0
	v_pk_mul_f32 v[142:143], v[144:145], v[172:173] op_sel_hi:[1,0]
	v_pk_mul_f32 v[122:123], v[122:123], v[172:173] op_sel_hi:[1,0]
	v_pk_mul_f32 v[124:125], v[124:125], v[172:173] op_sel_hi:[1,0]
	v_mov_b32_e32 v180, 0
	v_mov_b32_e32 v182, 0
	v_mov_b32_e32 v184, 0
	v_mov_b32_e32 v186, 0
	v_mov_b32_e32 v188, 0
	v_mov_b32_e32 v199, 0
	v_mov_b32_e32 v201, 0
	v_lshlrev_b32_e32 v128, 12, v128
	v_lshl_add_u32 v129, v198, 4, v129
	s_lshl_b32 s4, s4, 2
	v_pk_mul_f32 v[114:115], v[114:115], v[172:173] op_sel_hi:[1,0]
	v_pk_mul_f32 v[116:117], v[116:117], v[172:173] op_sel_hi:[1,0]
	v_add3_u32 v128, v129, v128, s4
	v_add_u32_e32 v198, 0x8000, v128
	v_mov_b32_e32 v187, 0
	v_mov_b32_e32 v189, 0
	v_mov_b32_e32 v200, 0
	v_mov_b32_e32 v202, 0
	v_add_u32_e32 v129, 0x200, v128
	s_waitcnt lgkmcnt(2)
	v_pk_mul_f32 v[90:91], v[90:91], v[126:127] op_sel_hi:[1,0]
	v_pk_mul_f32 v[92:93], v[92:93], v[126:127] op_sel_hi:[1,0]
	v_pk_mul_f32 v[94:95], v[94:95], v[126:127] op_sel_hi:[1,0]
	v_pk_mul_f32 v[96:97], v[96:97], v[126:127] op_sel_hi:[1,0]
	v_pk_mul_f32 v[82:83], v[82:83], v[126:127] op_sel_hi:[1,0]
	v_pk_mul_f32 v[84:85], v[84:85], v[126:127] op_sel_hi:[1,0]
	v_pk_mul_f32 v[86:87], v[86:87], v[126:127] op_sel_hi:[1,0]
	v_pk_mul_f32 v[88:89], v[88:89], v[126:127] op_sel_hi:[1,0]
	s_waitcnt lgkmcnt(1)
	v_pk_mul_f32 v[62:63], v[62:63], v[120:121] op_sel_hi:[1,0]
	v_pk_mul_f32 v[64:65], v[64:65], v[120:121] op_sel_hi:[1,0]
	v_pk_mul_f32 v[50:51], v[50:51], v[120:121] op_sel_hi:[1,0]
	v_pk_mul_f32 v[52:53], v[52:53], v[120:121] op_sel_hi:[1,0]
	v_pk_mul_f32 v[54:55], v[54:55], v[120:121] op_sel_hi:[1,0]
	v_pk_mul_f32 v[56:57], v[56:57], v[120:121] op_sel_hi:[1,0]
	s_waitcnt lgkmcnt(0)
	v_pk_mul_f32 v[32:33], v[32:33], v[118:119] op_sel_hi:[1,0]
	v_pk_mul_f32 v[28:29], v[28:29], v[118:119] op_sel_hi:[1,0]
	v_pk_mul_f32 v[22:23], v[22:23], v[118:119] op_sel_hi:[1,0]
	v_pk_mul_f32 v[24:25], v[24:25], v[118:119] op_sel_hi:[1,0]
	s_waitcnt vmcnt(3)
	v_pk_mul_f32 v[136:137], v[136:137], v[14:15]
	s_waitcnt vmcnt(2)
	v_pk_mul_f32 v[140:141], v[140:141], v[12:13]
	v_pk_mul_f32 v[138:139], v[138:139], v[10:11]
	v_pk_mul_f32 v[142:143], v[142:143], v[16:17]
	s_waitcnt vmcnt(1)
	v_pk_mul_f32 v[144:145], v[124:125], v[8:9]
	v_pk_mul_f32 v[160:161], v[122:123], v[6:7]
	v_mov_b32_dpp v178, v136 row_ror:8 row_mask:0xf bank_mask:0xf
	v_mov_b32_dpp v179, v138 row_ror:8 row_mask:0xf bank_mask:0xf
	v_mov_b32_dpp v181, v139 row_ror:8 row_mask:0xf bank_mask:0xf
	v_mov_b32_dpp v183, v140 row_ror:8 row_mask:0xf bank_mask:0xf
	v_mov_b32_dpp v185, v141 row_ror:8 row_mask:0xf bank_mask:0xf
	s_waitcnt vmcnt(0)
	v_pk_mul_f32 v[174:175], v[116:117], v[4:5]
	v_pk_mul_f32 v[176:177], v[114:115], v[2:3]
	v_mov_b32_dpp v180, v137 row_ror:8 row_mask:0xf bank_mask:0xf
	v_mov_b32_dpp v182, v142 row_ror:8 row_mask:0xf bank_mask:0xf
	v_mov_b32_dpp v184, v143 row_ror:8 row_mask:0xf bank_mask:0xf
	v_mov_b32_dpp v186, v160 row_ror:8 row_mask:0xf bank_mask:0xf
	v_mov_b32_dpp v188, v161 row_ror:8 row_mask:0xf bank_mask:0xf
	v_mov_b32_dpp v199, v144 row_ror:8 row_mask:0xf bank_mask:0xf
	v_mov_b32_dpp v201, v145 row_ror:8 row_mask:0xf bank_mask:0xf
	v_cndmask_b32_e32 v115, v181, v137, vcc
	v_cndmask_b32_e32 v114, v179, v136, vcc
	v_cndmask_b32_e32 v117, v185, v143, vcc
	v_cndmask_b32_e32 v116, v183, v142, vcc
	v_cndmask_b32_e32 v122, v138, v178, vcc
	v_cndmask_b32_e32 v123, v139, v180, vcc
	v_cndmask_b32_e32 v125, v141, v184, vcc
	v_cndmask_b32_e32 v124, v140, v182, vcc
	global_store_dwordx4 v128, v[114:117], s[24:25] sc1 nt
	s_bitset1_b32 s98, 0
	global_store_dwordx4 v198, v[122:125], s[24:25] sc1 nt
	s_bitset1_b32 s98, 1
	v_mov_b32_dpp v187, v176 row_ror:8 row_mask:0xf bank_mask:0xf
	v_cndmask_b32_e32 v115, v177, v188, vcc
	v_cndmask_b32_e32 v114, v176, v186, vcc
	v_cndmask_b32_e32 v117, v175, v201, vcc
	v_cndmask_b32_e32 v116, v174, v199, vcc
	v_add_u32_e32 v122, 0x8200, v128
	global_store_dwordx4 v122, v[114:117], s[24:25] sc1 nt
	s_bitset1_b32 s98, 2
	v_mov_b32_dpp v189, v177 row_ror:8 row_mask:0xf bank_mask:0xf
	v_mov_b32_dpp v200, v174 row_ror:8 row_mask:0xf bank_mask:0xf
	v_mov_b32_e32 v114, v173
	v_mov_b32_dpp v202, v175 row_ror:8 row_mask:0xf bank_mask:0xf
	v_pk_mul_f32 v[106:107], v[106:107], v[114:115] op_sel_hi:[1,0]
	v_pk_mul_f32 v[108:109], v[108:109], v[114:115] op_sel_hi:[1,0]
	v_cndmask_b32_e32 v137, v189, v161, vcc
	v_cndmask_b32_e32 v136, v187, v160, vcc
	v_cndmask_b32_e32 v139, v202, v145, vcc
	v_cndmask_b32_e32 v138, v200, v144, vcc
	v_pk_mul_f32 v[110:111], v[110:111], v[114:115] op_sel_hi:[1,0]
	v_pk_mul_f32 v[112:113], v[112:113], v[114:115] op_sel_hi:[1,0]
	v_pk_mul_f32 v[116:117], v[108:109], v[12:13]
	v_pk_mul_f32 v[122:123], v[106:107], v[10:11]
	v_mov_b32_e32 v106, 0
	v_mov_b32_e32 v107, 0
	v_mov_b32_e32 v108, 0
	v_mov_b32_e32 v109, 0
	global_store_dwordx4 v129, v[136:139], s[24:25] sc1 nt
	s_bitset1_b32 s98, 3
	v_pk_mul_f32 v[112:113], v[112:113], v[16:17]
	v_pk_mul_f32 v[110:111], v[110:111], v[14:15]
	v_mov_b32_e32 v124, 0
	v_mov_b32_dpp v106, v122 row_ror:8 row_mask:0xf bank_mask:0xf
	v_mov_b32_e32 v125, 0
	v_mov_b32_dpp v107, v123 row_ror:8 row_mask:0xf bank_mask:0xf
	v_mov_b32_e32 v129, 0
	v_mov_b32_dpp v108, v116 row_ror:8 row_mask:0xf bank_mask:0xf
	v_mov_b32_e32 v136, 0
	v_mov_b32_dpp v109, v117 row_ror:8 row_mask:0xf bank_mask:0xf
	v_add_u32_e32 v115, 0x10000, v128
	v_mov_b32_dpp v124, v110 row_ror:8 row_mask:0xf bank_mask:0xf
	v_mov_b32_dpp v125, v111 row_ror:8 row_mask:0xf bank_mask:0xf
	v_mov_b32_dpp v129, v112 row_ror:8 row_mask:0xf bank_mask:0xf
	v_mov_b32_dpp v136, v113 row_ror:8 row_mask:0xf bank_mask:0xf
	v_cndmask_b32_e32 v107, v107, v111, vcc
	v_cndmask_b32_e32 v106, v106, v110, vcc
	v_cndmask_b32_e32 v109, v109, v113, vcc
	v_cndmask_b32_e32 v108, v108, v112, vcc
	v_cndmask_b32_e32 v111, v123, v125, vcc
	v_cndmask_b32_e32 v110, v122, v124, vcc
	v_cndmask_b32_e32 v113, v117, v136, vcc
	v_cndmask_b32_e32 v112, v116, v129, vcc
	global_store_dwordx4 v115, v[106:109], s[24:25] sc1 nt
	s_bitset1_b32 s98, 4
	v_pk_mul_f32 v[98:99], v[98:99], v[114:115] op_sel_hi:[1,0]
	v_pk_mul_f32 v[100:101], v[100:101], v[114:115] op_sel_hi:[1,0]
	v_add_u32_e32 v106, 0x18000, v128
	global_store_dwordx4 v106, v[110:113], s[24:25] sc1 nt
	s_bitset1_b32 s98, 5
	v_pk_mul_f32 v[102:103], v[102:103], v[114:115] op_sel_hi:[1,0]
	v_pk_mul_f32 v[104:105], v[104:105], v[114:115] op_sel_hi:[1,0]
	v_pk_mul_f32 v[106:107], v[100:101], v[4:5]
	v_pk_mul_f32 v[108:109], v[98:99], v[2:3]
	v_mov_b32_e32 v98, 0
	v_mov_b32_e32 v99, 0
	v_mov_b32_e32 v100, 0
	v_mov_b32_e32 v101, 0
	v_pk_mul_f32 v[104:105], v[104:105], v[8:9]
	v_pk_mul_f32 v[102:103], v[102:103], v[6:7]
	v_mov_b32_e32 v111, 0
	v_mov_b32_dpp v98, v108 row_ror:8 row_mask:0xf bank_mask:0xf
	v_mov_b32_e32 v112, 0
	v_mov_b32_dpp v99, v109 row_ror:8 row_mask:0xf bank_mask:0xf
	v_mov_b32_e32 v113, 0
	v_mov_b32_dpp v100, v106 row_ror:8 row_mask:0xf bank_mask:0xf
	v_mov_b32_e32 v114, 0
	v_mov_b32_dpp v101, v107 row_ror:8 row_mask:0xf bank_mask:0xf
	v_add_u32_e32 v110, 0x10200, v128
	v_mov_b32_dpp v111, v102 row_ror:8 row_mask:0xf bank_mask:0xf
	v_mov_b32_dpp v112, v103 row_ror:8 row_mask:0xf bank_mask:0xf
	v_mov_b32_dpp v113, v104 row_ror:8 row_mask:0xf bank_mask:0xf
	v_mov_b32_dpp v114, v105 row_ror:8 row_mask:0xf bank_mask:0xf
	v_cndmask_b32_e32 v99, v99, v103, vcc
	v_cndmask_b32_e32 v98, v98, v102, vcc
	v_cndmask_b32_e32 v101, v101, v105, vcc
	v_cndmask_b32_e32 v100, v100, v104, vcc
	v_cndmask_b32_e32 v103, v109, v112, vcc
	v_cndmask_b32_e32 v102, v108, v111, vcc
	v_cndmask_b32_e32 v105, v107, v114, vcc
	v_cndmask_b32_e32 v104, v106, v113, vcc
	global_store_dwordx4 v110, v[98:101], s[24:25] sc1 nt
	s_bitset1_b32 s98, 6
	v_pk_mul_f32 v[96:97], v[96:97], v[16:17]
	v_pk_mul_f32 v[94:95], v[94:95], v[14:15]
	v_add_u32_e32 v98, 0x18200, v128
	global_store_dwordx4 v98, v[102:105], s[24:25] sc1 nt
	s_bitset1_b32 s98, 7
	v_pk_mul_f32 v[98:99], v[92:93], v[12:13]
	v_pk_mul_f32 v[100:101], v[90:91], v[10:11]
	v_mov_b32_e32 v90, 0
	v_mov_b32_e32 v91, 0
	v_mov_b32_e32 v92, 0
	v_mov_b32_e32 v93, 0
	v_mov_b32_e32 v103, 0
	v_mov_b32_dpp v90, v100 row_ror:8 row_mask:0xf bank_mask:0xf
	v_mov_b32_e32 v104, 0
	v_mov_b32_dpp v91, v101 row_ror:8 row_mask:0xf bank_mask:0xf
	v_mov_b32_e32 v105, 0
	v_mov_b32_dpp v92, v98 row_ror:8 row_mask:0xf bank_mask:0xf
	v_mov_b32_e32 v106, 0
	v_mov_b32_dpp v93, v99 row_ror:8 row_mask:0xf bank_mask:0xf
	v_add_u32_e32 v102, 0x20000, v128
	v_mov_b32_dpp v103, v94 row_ror:8 row_mask:0xf bank_mask:0xf
	v_mov_b32_dpp v104, v95 row_ror:8 row_mask:0xf bank_mask:0xf
	v_mov_b32_dpp v105, v96 row_ror:8 row_mask:0xf bank_mask:0xf
	v_mov_b32_dpp v106, v97 row_ror:8 row_mask:0xf bank_mask:0xf
	v_cndmask_b32_e32 v91, v91, v95, vcc
	v_cndmask_b32_e32 v90, v90, v94, vcc
	v_cndmask_b32_e32 v93, v93, v97, vcc
	v_cndmask_b32_e32 v92, v92, v96, vcc
	v_cndmask_b32_e32 v95, v101, v104, vcc
	v_cndmask_b32_e32 v94, v100, v103, vcc
	v_cndmask_b32_e32 v97, v99, v106, vcc
	v_cndmask_b32_e32 v96, v98, v105, vcc
	global_store_dwordx4 v102, v[90:93], s[24:25] sc1 nt
	s_bitset1_b32 s98, 8
	v_pk_mul_f32 v[88:89], v[88:89], v[8:9]
	v_pk_mul_f32 v[86:87], v[86:87], v[6:7]
	v_add_u32_e32 v90, 0x28000, v128
	global_store_dwordx4 v90, v[94:97], s[24:25] sc1 nt
	s_bitset1_b32 s98, 9
	v_pk_mul_f32 v[90:91], v[84:85], v[4:5]
	v_pk_mul_f32 v[92:93], v[82:83], v[2:3]
	v_mov_b32_e32 v82, 0
	v_mov_b32_e32 v83, 0
	v_mov_b32_e32 v84, 0
	v_mov_b32_e32 v85, 0
	v_mov_b32_e32 v95, 0
	v_mov_b32_dpp v82, v92 row_ror:8 row_mask:0xf bank_mask:0xf
	v_mov_b32_e32 v96, 0
	v_mov_b32_dpp v83, v93 row_ror:8 row_mask:0xf bank_mask:0xf
	v_mov_b32_e32 v97, 0
	v_mov_b32_dpp v84, v90 row_ror:8 row_mask:0xf bank_mask:0xf
	v_mov_b32_e32 v98, 0
	v_mov_b32_dpp v85, v91 row_ror:8 row_mask:0xf bank_mask:0xf
	v_add_u32_e32 v94, 0x20200, v128
	v_mov_b32_dpp v95, v86 row_ror:8 row_mask:0xf bank_mask:0xf
	v_mov_b32_dpp v96, v87 row_ror:8 row_mask:0xf bank_mask:0xf
	v_mov_b32_dpp v97, v88 row_ror:8 row_mask:0xf bank_mask:0xf
	v_mov_b32_dpp v98, v89 row_ror:8 row_mask:0xf bank_mask:0xf
	v_cndmask_b32_e32 v83, v83, v87, vcc
	v_cndmask_b32_e32 v82, v82, v86, vcc
	v_cndmask_b32_e32 v85, v85, v89, vcc
	v_cndmask_b32_e32 v84, v84, v88, vcc
	v_cndmask_b32_e32 v87, v93, v96, vcc
	v_cndmask_b32_e32 v86, v92, v95, vcc
	v_cndmask_b32_e32 v89, v91, v98, vcc
	v_cndmask_b32_e32 v88, v90, v97, vcc
	global_store_dwordx4 v94, v[82:85], s[24:25] sc1 nt
	s_bitset1_b32 s98, 10
	v_mov_b32_e32 v90, 0
	v_mov_b32_e32 v91, 0
	v_add_u32_e32 v82, 0x28200, v128
	global_store_dwordx4 v82, v[86:89], s[24:25] sc1 nt
	s_bitset1_b32 s98, 11
	v_mov_b32_e32 v82, v127
	v_pk_mul_f32 v[74:75], v[74:75], v[82:83] op_sel_hi:[1,0]
	v_pk_mul_f32 v[76:77], v[76:77], v[82:83] op_sel_hi:[1,0]
	v_pk_mul_f32 v[78:79], v[78:79], v[82:83] op_sel_hi:[1,0]
	v_pk_mul_f32 v[80:81], v[80:81], v[82:83] op_sel_hi:[1,0]
	v_pk_mul_f32 v[84:85], v[76:77], v[12:13]
	v_pk_mul_f32 v[86:87], v[74:75], v[10:11]
	v_mov_b32_e32 v74, 0
	v_mov_b32_e32 v75, 0
	v_mov_b32_e32 v76, 0
	v_mov_b32_e32 v77, 0
	v_pk_mul_f32 v[80:81], v[80:81], v[16:17]
	v_pk_mul_f32 v[78:79], v[78:79], v[14:15]
	v_mov_b32_e32 v88, 0
	v_mov_b32_dpp v74, v86 row_ror:8 row_mask:0xf bank_mask:0xf
	v_mov_b32_e32 v89, 0
	v_mov_b32_dpp v75, v87 row_ror:8 row_mask:0xf bank_mask:0xf
	v_mov_b32_dpp v76, v84 row_ror:8 row_mask:0xf bank_mask:0xf
	v_mov_b32_dpp v77, v85 row_ror:8 row_mask:0xf bank_mask:0xf
	v_add_u32_e32 v83, 0x30000, v128
	v_mov_b32_dpp v88, v78 row_ror:8 row_mask:0xf bank_mask:0xf
	v_mov_b32_dpp v89, v79 row_ror:8 row_mask:0xf bank_mask:0xf
	v_mov_b32_dpp v90, v80 row_ror:8 row_mask:0xf bank_mask:0xf
	v_mov_b32_dpp v91, v81 row_ror:8 row_mask:0xf bank_mask:0xf
	v_cndmask_b32_e32 v75, v75, v79, vcc
	v_cndmask_b32_e32 v74, v74, v78, vcc
	v_cndmask_b32_e32 v77, v77, v81, vcc
	v_cndmask_b32_e32 v76, v76, v80, vcc
	v_cndmask_b32_e32 v79, v87, v89, vcc
	v_cndmask_b32_e32 v78, v86, v88, vcc
	v_cndmask_b32_e32 v81, v85, v91, vcc
	v_cndmask_b32_e32 v80, v84, v90, vcc
	global_store_dwordx4 v83, v[74:77], s[24:25] sc1 nt
	s_bitset1_b32 s98, 12
	v_pk_mul_f32 v[66:67], v[66:67], v[82:83] op_sel_hi:[1,0]
	v_pk_mul_f32 v[68:69], v[68:69], v[82:83] op_sel_hi:[1,0]
	v_add_u32_e32 v74, 0x38000, v128
	global_store_dwordx4 v74, v[78:81], s[24:25] sc1 nt
	s_bitset1_b32 s98, 13
	v_pk_mul_f32 v[70:71], v[70:71], v[82:83] op_sel_hi:[1,0]
	v_pk_mul_f32 v[72:73], v[72:73], v[82:83] op_sel_hi:[1,0]
	v_pk_mul_f32 v[74:75], v[68:69], v[4:5]
	v_pk_mul_f32 v[76:77], v[66:67], v[2:3]
	v_mov_b32_e32 v66, 0
	v_mov_b32_e32 v67, 0
	v_mov_b32_e32 v68, 0
	v_mov_b32_e32 v69, 0
	v_pk_mul_f32 v[72:73], v[72:73], v[8:9]
	v_pk_mul_f32 v[70:71], v[70:71], v[6:7]
	v_mov_b32_e32 v79, 0
	v_mov_b32_dpp v66, v76 row_ror:8 row_mask:0xf bank_mask:0xf
	v_mov_b32_e32 v80, 0
	v_mov_b32_dpp v67, v77 row_ror:8 row_mask:0xf bank_mask:0xf
	v_mov_b32_e32 v81, 0
	v_mov_b32_dpp v68, v74 row_ror:8 row_mask:0xf bank_mask:0xf
	v_mov_b32_e32 v82, 0
	v_mov_b32_dpp v69, v75 row_ror:8 row_mask:0xf bank_mask:0xf
	v_add_u32_e32 v78, 0x30200, v128
	v_mov_b32_dpp v79, v70 row_ror:8 row_mask:0xf bank_mask:0xf
	v_mov_b32_dpp v80, v71 row_ror:8 row_mask:0xf bank_mask:0xf
	v_mov_b32_dpp v81, v72 row_ror:8 row_mask:0xf bank_mask:0xf
	v_mov_b32_dpp v82, v73 row_ror:8 row_mask:0xf bank_mask:0xf
	v_cndmask_b32_e32 v67, v67, v71, vcc
	v_cndmask_b32_e32 v66, v66, v70, vcc
	v_cndmask_b32_e32 v69, v69, v73, vcc
	v_cndmask_b32_e32 v68, v68, v72, vcc
	v_cndmask_b32_e32 v71, v77, v80, vcc
	v_cndmask_b32_e32 v70, v76, v79, vcc
	v_cndmask_b32_e32 v73, v75, v82, vcc
	v_cndmask_b32_e32 v72, v74, v81, vcc
	global_store_dwordx4 v78, v[66:69], s[24:25] sc1 nt
	s_bitset1_b32 s98, 14
	v_mov_b32_e32 v75, 0
	v_mov_b32_e32 v76, 0
	v_add_u32_e32 v66, 0x38200, v128
	global_store_dwordx4 v66, v[70:73], s[24:25] sc1 nt
	s_bitset1_b32 s98, 15
	v_pk_mul_f32 v[66:67], v[170:171], v[120:121] op_sel_hi:[1,0]
	v_pk_mul_f32 v[68:69], v[166:167], v[120:121] op_sel_hi:[1,0]
	v_pk_mul_f32 v[70:71], v[64:65], v[12:13]
	v_pk_mul_f32 v[72:73], v[62:63], v[10:11]
	v_mov_b32_e32 v62, 0
	v_mov_b32_e32 v63, 0
	v_mov_b32_e32 v64, 0
	v_mov_b32_e32 v65, 0
	v_pk_mul_f32 v[68:69], v[68:69], v[16:17]
	v_pk_mul_f32 v[66:67], v[66:67], v[14:15]
	v_mov_b32_dpp v62, v72 row_ror:8 row_mask:0xf bank_mask:0xf
	v_mov_b32_dpp v63, v73 row_ror:8 row_mask:0xf bank_mask:0xf
	v_mov_b32_e32 v77, 0
	v_mov_b32_dpp v64, v70 row_ror:8 row_mask:0xf bank_mask:0xf
	v_mov_b32_e32 v78, 0
	v_mov_b32_dpp v65, v71 row_ror:8 row_mask:0xf bank_mask:0xf
	v_add_u32_e32 v74, 0x80000, v128
	v_mov_b32_dpp v75, v66 row_ror:8 row_mask:0xf bank_mask:0xf
	v_mov_b32_dpp v76, v67 row_ror:8 row_mask:0xf bank_mask:0xf
	v_mov_b32_dpp v77, v68 row_ror:8 row_mask:0xf bank_mask:0xf
	v_mov_b32_dpp v78, v69 row_ror:8 row_mask:0xf bank_mask:0xf
	v_cndmask_b32_e32 v63, v63, v67, vcc
	v_cndmask_b32_e32 v62, v62, v66, vcc
	v_cndmask_b32_e32 v65, v65, v69, vcc
	v_cndmask_b32_e32 v64, v64, v68, vcc
	v_cndmask_b32_e32 v67, v73, v76, vcc
	v_cndmask_b32_e32 v66, v72, v75, vcc
	v_cndmask_b32_e32 v69, v71, v78, vcc
	v_cndmask_b32_e32 v68, v70, v77, vcc
	global_store_dwordx4 v74, v[62:65], s[24:25] sc1 nt
	s_bitset1_b32 s98, 16
	v_pk_mul_f32 v[56:57], v[56:57], v[8:9]
	v_pk_mul_f32 v[54:55], v[54:55], v[6:7]
	v_add_u32_e32 v62, 0x88000, v128
	global_store_dwordx4 v62, v[66:69], s[24:25] sc1 nt
	s_bitset1_b32 s98, 17
	v_pk_mul_f32 v[62:63], v[52:53], v[4:5]
	v_pk_mul_f32 v[64:65], v[50:51], v[2:3]
	v_mov_b32_e32 v50, 0
	v_mov_b32_e32 v51, 0
	v_mov_b32_e32 v52, 0
	v_mov_b32_e32 v53, 0
	v_mov_b32_e32 v67, 0
	v_mov_b32_dpp v50, v64 row_ror:8 row_mask:0xf bank_mask:0xf
	v_mov_b32_e32 v68, 0
	v_mov_b32_dpp v51, v65 row_ror:8 row_mask:0xf bank_mask:0xf
	v_mov_b32_e32 v69, 0
	v_mov_b32_dpp v52, v62 row_ror:8 row_mask:0xf bank_mask:0xf
	v_mov_b32_e32 v70, 0
	v_mov_b32_dpp v53, v63 row_ror:8 row_mask:0xf bank_mask:0xf
	v_add_u32_e32 v66, 0x80200, v128
	v_mov_b32_dpp v67, v54 row_ror:8 row_mask:0xf bank_mask:0xf
	v_mov_b32_dpp v68, v55 row_ror:8 row_mask:0xf bank_mask:0xf
	v_mov_b32_dpp v69, v56 row_ror:8 row_mask:0xf bank_mask:0xf
	v_mov_b32_dpp v70, v57 row_ror:8 row_mask:0xf bank_mask:0xf
	v_cndmask_b32_e32 v51, v51, v55, vcc
	v_cndmask_b32_e32 v50, v50, v54, vcc
	v_cndmask_b32_e32 v53, v53, v57, vcc
	v_cndmask_b32_e32 v52, v52, v56, vcc
	v_cndmask_b32_e32 v55, v65, v68, vcc
	v_cndmask_b32_e32 v54, v64, v67, vcc
	v_cndmask_b32_e32 v57, v63, v70, vcc
	v_cndmask_b32_e32 v56, v62, v69, vcc
	global_store_dwordx4 v66, v[50:53], s[24:25] sc1 nt
	s_bitset1_b32 s98, 18
	v_mov_b32_e32 v63, 0
	v_mov_b32_e32 v65, 0
	v_add_u32_e32 v50, 0x88200, v128
	global_store_dwordx4 v50, v[54:57], s[24:25] sc1 nt
	s_bitset1_b32 s98, 19
	v_mov_b32_e32 v62, 0
	v_mov_b32_e32 v64, 0
	v_mov_b32_e32 v56, v121
	v_pk_mul_f32 v[50:51], v[58:59], v[56:57] op_sel_hi:[1,0]
	v_pk_mul_f32 v[48:49], v[48:49], v[56:57] op_sel_hi:[1,0]
	v_pk_mul_f32 v[54:55], v[60:61], v[56:57] op_sel_hi:[1,0]
	v_pk_mul_f32 v[52:53], v[48:49], v[16:17]
	v_pk_mul_f32 v[48:49], v[50:51], v[14:15]
	v_pk_mul_f32 v[50:51], v[164:165], v[56:57] op_sel_hi:[1,0]
	v_pk_mul_f32 v[54:55], v[54:55], v[12:13]
	v_pk_mul_f32 v[58:59], v[50:51], v[10:11]
	v_mov_b32_e32 v50, 0
	v_mov_b32_e32 v51, 0
	v_mov_b32_e32 v60, 0
	v_mov_b32_dpp v50, v58 row_ror:8 row_mask:0xf bank_mask:0xf
	v_mov_b32_e32 v61, 0
	v_mov_b32_dpp v51, v59 row_ror:8 row_mask:0xf bank_mask:0xf
	v_mov_b32_dpp v63, v54 row_ror:8 row_mask:0xf bank_mask:0xf
	v_mov_b32_dpp v65, v55 row_ror:8 row_mask:0xf bank_mask:0xf
	v_add_u32_e32 v57, 0x90000, v128
	v_mov_b32_dpp v60, v48 row_ror:8 row_mask:0xf bank_mask:0xf
	v_mov_b32_dpp v61, v49 row_ror:8 row_mask:0xf bank_mask:0xf
	v_mov_b32_dpp v62, v52 row_ror:8 row_mask:0xf bank_mask:0xf
	v_mov_b32_dpp v64, v53 row_ror:8 row_mask:0xf bank_mask:0xf
	v_cndmask_b32_e32 v49, v51, v49, vcc
	v_cndmask_b32_e32 v48, v50, v48, vcc
	v_cndmask_b32_e32 v51, v65, v53, vcc
	v_cndmask_b32_e32 v50, v63, v52, vcc
	v_cndmask_b32_e32 v53, v59, v61, vcc
	v_cndmask_b32_e32 v52, v58, v60, vcc
	v_cndmask_b32_e32 v55, v55, v64, vcc
	v_cndmask_b32_e32 v54, v54, v62, vcc
	global_store_dwordx4 v57, v[48:51], s[24:25] sc1 nt
	s_bitset1_b32 s98, 20
	v_pk_mul_f32 v[34:35], v[34:35], v[56:57] op_sel_hi:[1,0]
	v_pk_mul_f32 v[36:37], v[36:37], v[56:57] op_sel_hi:[1,0]
	v_add_u32_e32 v48, 0x98000, v128
	global_store_dwordx4 v48, v[52:55], s[24:25] sc1 nt
	s_bitset1_b32 s98, 21
	v_pk_mul_f32 v[38:39], v[38:39], v[56:57] op_sel_hi:[1,0]
	v_pk_mul_f32 v[40:41], v[40:41], v[56:57] op_sel_hi:[1,0]
	v_pk_mul_f32 v[48:49], v[36:37], v[4:5]
	v_pk_mul_f32 v[50:51], v[34:35], v[2:3]
	v_mov_b32_e32 v34, 0
	v_mov_b32_e32 v35, 0
	v_mov_b32_e32 v36, 0
	v_mov_b32_e32 v37, 0
	v_pk_mul_f32 v[40:41], v[40:41], v[8:9]
	v_pk_mul_f32 v[38:39], v[38:39], v[6:7]
	v_mov_b32_e32 v53, 0
	v_mov_b32_dpp v34, v50 row_ror:8 row_mask:0xf bank_mask:0xf
	v_mov_b32_e32 v54, 0
	v_mov_b32_dpp v35, v51 row_ror:8 row_mask:0xf bank_mask:0xf
	v_mov_b32_e32 v55, 0
	v_mov_b32_dpp v36, v48 row_ror:8 row_mask:0xf bank_mask:0xf
	v_mov_b32_e32 v56, 0
	v_mov_b32_dpp v37, v49 row_ror:8 row_mask:0xf bank_mask:0xf
	v_add_u32_e32 v52, 0x90200, v128
	v_mov_b32_dpp v53, v38 row_ror:8 row_mask:0xf bank_mask:0xf
	v_mov_b32_dpp v54, v39 row_ror:8 row_mask:0xf bank_mask:0xf
	v_mov_b32_dpp v55, v40 row_ror:8 row_mask:0xf bank_mask:0xf
	v_mov_b32_dpp v56, v41 row_ror:8 row_mask:0xf bank_mask:0xf
	v_cndmask_b32_e32 v35, v35, v39, vcc
	v_cndmask_b32_e32 v34, v34, v38, vcc
	v_cndmask_b32_e32 v37, v37, v41, vcc
	v_cndmask_b32_e32 v36, v36, v40, vcc
	v_cndmask_b32_e32 v39, v51, v54, vcc
	v_cndmask_b32_e32 v38, v50, v53, vcc
	v_cndmask_b32_e32 v41, v49, v56, vcc
	v_cndmask_b32_e32 v40, v48, v55, vcc
	global_store_dwordx4 v52, v[34:37], s[24:25] sc1 nt
	s_bitset1_b32 s98, 22
	v_mov_b32_e32 v50, 0
	v_mov_b32_e32 v52, 0
	v_add_u32_e32 v34, 0x98200, v128
	global_store_dwordx4 v34, v[38:41], s[24:25] sc1 nt
	s_bitset1_b32 s98, 23
	v_pk_mul_f32 v[34:35], v[46:47], v[118:119] op_sel_hi:[1,0]
	v_pk_mul_f32 v[36:37], v[16:17], v[32:33]
	v_pk_mul_f32 v[32:33], v[14:15], v[34:35]
	v_pk_mul_f32 v[34:35], v[168:169], v[118:119] op_sel_hi:[1,0]
	v_pk_mul_f32 v[38:39], v[162:163], v[118:119] op_sel_hi:[1,0]
	v_pk_mul_f32 v[40:41], v[34:35], v[10:11]
	v_pk_mul_f32 v[38:39], v[38:39], v[12:13]
	v_mov_b32_e32 v34, 0
	v_mov_b32_e32 v35, 0
	v_mov_b32_e32 v47, 0
	v_mov_b32_dpp v34, v40 row_ror:8 row_mask:0xf bank_mask:0xf
	v_mov_b32_e32 v48, 0
	v_mov_b32_dpp v35, v41 row_ror:8 row_mask:0xf bank_mask:0xf
	v_mov_b32_e32 v49, 0
	v_mov_b32_dpp v50, v38 row_ror:8 row_mask:0xf bank_mask:0xf
	v_mov_b32_e32 v51, 0
	v_mov_b32_dpp v52, v39 row_ror:8 row_mask:0xf bank_mask:0xf
	v_add_u32_e32 v46, 0xa0000, v128
	v_mov_b32_dpp v47, v32 row_ror:8 row_mask:0xf bank_mask:0xf
	v_mov_b32_dpp v48, v33 row_ror:8 row_mask:0xf bank_mask:0xf
	v_mov_b32_dpp v49, v36 row_ror:8 row_mask:0xf bank_mask:0xf
	v_mov_b32_dpp v51, v37 row_ror:8 row_mask:0xf bank_mask:0xf
	v_cndmask_b32_e32 v33, v35, v33, vcc
	v_cndmask_b32_e32 v32, v34, v32, vcc
	v_cndmask_b32_e32 v35, v52, v37, vcc
	v_cndmask_b32_e32 v34, v50, v36, vcc
	v_cndmask_b32_e32 v37, v41, v48, vcc
	v_cndmask_b32_e32 v36, v40, v47, vcc
	v_cndmask_b32_e32 v39, v39, v51, vcc
	v_cndmask_b32_e32 v38, v38, v49, vcc
	global_store_dwordx4 v46, v[32:35], s[24:25] sc1 nt
	s_bitset1_b32 s98, 24
	v_pk_mul_f32 v[28:29], v[28:29], v[4:5]
	v_mov_b32_e32 v40, 0
	v_add_u32_e32 v32, 0xa8000, v128
	global_store_dwordx4 v32, v[36:39], s[24:25] sc1 nt
	s_bitset1_b32 s98, 25
	v_pk_mul_f32 v[32:33], v[44:45], v[118:119] op_sel_hi:[1,0]
	v_mov_b32_e32 v35, 0
	v_pk_mul_f32 v[32:33], v[32:33], v[2:3]
	v_mov_b32_e32 v38, 0
	v_mov_b32_e32 v44, 0
	v_pk_mul_f32 v[24:25], v[24:25], v[8:9]
	v_pk_mul_f32 v[22:23], v[22:23], v[6:7]
	v_mov_b32_e32 v34, 0
	v_mov_b32_dpp v35, v32 row_ror:8 row_mask:0xf bank_mask:0xf
	v_mov_b32_e32 v37, 0
	v_mov_b32_dpp v38, v33 row_ror:8 row_mask:0xf bank_mask:0xf
	v_mov_b32_e32 v39, 0
	v_mov_b32_dpp v40, v28 row_ror:8 row_mask:0xf bank_mask:0xf
	v_mov_b32_e32 v41, 0
	v_mov_b32_dpp v44, v29 row_ror:8 row_mask:0xf bank_mask:0xf
	v_add_u32_e32 v36, 0xa0200, v128
	v_mov_b32_dpp v34, v22 row_ror:8 row_mask:0xf bank_mask:0xf
	v_mov_b32_dpp v37, v23 row_ror:8 row_mask:0xf bank_mask:0xf
	v_mov_b32_dpp v39, v24 row_ror:8 row_mask:0xf bank_mask:0xf
	v_mov_b32_dpp v41, v25 row_ror:8 row_mask:0xf bank_mask:0xf
	v_cndmask_b32_e32 v23, v38, v23, vcc
	v_cndmask_b32_e32 v22, v35, v22, vcc
	v_cndmask_b32_e32 v25, v44, v25, vcc
	v_cndmask_b32_e32 v24, v40, v24, vcc
	v_cndmask_b32_e32 v33, v33, v37, vcc
	v_cndmask_b32_e32 v32, v32, v34, vcc
	v_cndmask_b32_e32 v35, v29, v41, vcc
	v_cndmask_b32_e32 v34, v28, v39, vcc
	global_store_dwordx4 v36, v[22:25], s[24:25] sc1 nt
	s_bitset1_b32 s98, 26
	s_nop 1
	v_add_u32_e32 v22, 0xa8200, v128
	global_store_dwordx4 v22, v[32:35], s[24:25] sc1 nt
	s_bitset1_b32 s98, 27
	v_mov_b32_e32 v22, v119
	v_pk_mul_f32 v[24:25], v[134:135], v[22:23] op_sel_hi:[1,0]
	v_pk_mul_f32 v[28:29], v[42:43], v[22:23] op_sel_hi:[1,0]
	v_pk_mul_f32 v[14:15], v[14:15], v[24:25]
	v_pk_mul_f32 v[16:17], v[16:17], v[28:29]
	v_pk_mul_f32 v[24:25], v[130:131], v[22:23] op_sel_hi:[1,0]
	v_pk_mul_f32 v[28:29], v[132:133], v[22:23] op_sel_hi:[1,0]
	v_pk_mul_f32 v[24:25], v[10:11], v[24:25]
	v_pk_mul_f32 v[28:29], v[12:13], v[28:29]
	v_mov_b32_e32 v10, 0
	v_mov_b32_e32 v11, 0
	v_mov_b32_e32 v12, 0
	v_mov_b32_e32 v13, 0
	v_mov_b32_e32 v32, 0
	v_mov_b32_dpp v10, v24 row_ror:8 row_mask:0xf bank_mask:0xf
	v_mov_b32_e32 v33, 0
	v_mov_b32_dpp v11, v25 row_ror:8 row_mask:0xf bank_mask:0xf
	v_mov_b32_e32 v34, 0
	v_mov_b32_dpp v12, v28 row_ror:8 row_mask:0xf bank_mask:0xf
	v_mov_b32_e32 v35, 0
	v_mov_b32_dpp v13, v29 row_ror:8 row_mask:0xf bank_mask:0xf
	v_add_u32_e32 v23, 0xb0000, v128
	v_mov_b32_dpp v32, v14 row_ror:8 row_mask:0xf bank_mask:0xf
	v_mov_b32_dpp v33, v15 row_ror:8 row_mask:0xf bank_mask:0xf
	v_mov_b32_dpp v34, v16 row_ror:8 row_mask:0xf bank_mask:0xf
	v_mov_b32_dpp v35, v17 row_ror:8 row_mask:0xf bank_mask:0xf
	v_cndmask_b32_e32 v11, v11, v15, vcc
	v_cndmask_b32_e32 v10, v10, v14, vcc
	v_cndmask_b32_e32 v13, v13, v17, vcc
	v_cndmask_b32_e32 v12, v12, v16, vcc
	v_cndmask_b32_e32 v15, v25, v33, vcc
	v_cndmask_b32_e32 v14, v24, v32, vcc
	v_cndmask_b32_e32 v17, v29, v35, vcc
	v_cndmask_b32_e32 v16, v28, v34, vcc
	global_store_dwordx4 v23, v[10:13], s[24:25] sc1 nt
	s_bitset1_b32 s98, 28
	s_nop 1
	v_add_u32_e32 v10, 0xb8000, v128
	global_store_dwordx4 v10, v[14:17], s[24:25] sc1 nt
	s_bitset1_b32 s98, 29
	v_pk_mul_f32 v[10:11], v[20:21], v[22:23] op_sel_hi:[1,0]
	v_pk_mul_f32 v[12:13], v[18:19], v[22:23] op_sel_hi:[1,0]
	v_pk_mul_f32 v[6:7], v[10:11], v[6:7]
	v_pk_mul_f32 v[8:9], v[12:13], v[8:9]
	v_pk_mul_f32 v[10:11], v[30:31], v[22:23] op_sel_hi:[1,0]
	v_pk_mul_f32 v[12:13], v[26:27], v[22:23] op_sel_hi:[1,0]
	v_pk_mul_f32 v[10:11], v[10:11], v[2:3]
	v_pk_mul_f32 v[12:13], v[12:13], v[4:5]
	v_mov_b32_e32 v2, 0
	v_mov_b32_e32 v3, 0
	v_mov_b32_e32 v4, 0
	v_mov_b32_e32 v5, 0
	v_mov_b32_e32 v15, 0
	v_mov_b32_dpp v2, v10 row_ror:8 row_mask:0xf bank_mask:0xf
	v_mov_b32_e32 v16, 0
	v_mov_b32_dpp v3, v11 row_ror:8 row_mask:0xf bank_mask:0xf
	v_mov_b32_e32 v17, 0
	v_mov_b32_dpp v4, v12 row_ror:8 row_mask:0xf bank_mask:0xf
	v_mov_b32_e32 v18, 0
	v_mov_b32_dpp v5, v13 row_ror:8 row_mask:0xf bank_mask:0xf
	v_add_u32_e32 v14, 0xb0200, v128
	v_mov_b32_dpp v15, v6 row_ror:8 row_mask:0xf bank_mask:0xf
	v_mov_b32_dpp v16, v7 row_ror:8 row_mask:0xf bank_mask:0xf
	v_mov_b32_dpp v17, v8 row_ror:8 row_mask:0xf bank_mask:0xf
	v_mov_b32_dpp v18, v9 row_ror:8 row_mask:0xf bank_mask:0xf
	v_cndmask_b32_e32 v3, v3, v7, vcc
	v_cndmask_b32_e32 v2, v2, v6, vcc
	v_cndmask_b32_e32 v5, v5, v9, vcc
	v_cndmask_b32_e32 v4, v4, v8, vcc
	v_cndmask_b32_e32 v7, v11, v16, vcc
	v_cndmask_b32_e32 v6, v10, v15, vcc
	v_cndmask_b32_e32 v9, v13, v18, vcc
	v_cndmask_b32_e32 v8, v12, v17, vcc
	global_store_dwordx4 v14, v[2:5], s[24:25] sc1 nt
	s_bitset1_b32 s98, 30
	s_andn2_b64 vcc, exec, s[0:1]
	s_mov_b64 s[0:1], -1
	v_add_u32_e32 v2, 0xb8200, v128
	global_store_dwordx4 v2, v[6:9], s[24:25] sc1 nt
	s_bitset1_b32 s98, 31
	s_cbranch_vccnz .LBB0_847
	s_andn2_b64 vcc, exec, s[12:13]
	s_cbranch_vccnz .LBB0_846
	s_barrier
	s_branch .LBB0_846
